# GEMM/memattn/MLA tile prologues: LDS-free barrier moved after the first K-tile loads (loads fly during the barrier wait); MLA item tail rmsnorm loads batched 8 at a time
# baseline (speedup 1.0000x reference)
; #define LOADS(S, k0) { LD1(S, 0, k0) LD1(S, 1, k0) LD1(S, 2, k0) LD1(S, 3, k0) }
; #define STORES(S, buf) { ST1(S, 0, buf) ST1(S, 1, buf) ST1(S, 2, buf) ST1(S, 3, buf) }
; template <int AMODE, bool F16 = false, bool MASK = false>
; DI void gemm_tile(const bf16_t* __restrict__ Ab, int lda, int row0, int rlo, int rhi,
;                   const bf16_t* __restrict__ Bt, int ldb, int K, char* smem, f32x16 (&acc)[2][2]) {
;     ...
;     const int gr0 = row0 + (t >> 3);
;     const bool rv0 = gr0 >= rlo && gr0 < rhi, rv1 = gr0 + 32 >= rlo && gr0 + 32 < rhi, rv2 = gr0 + 64 >= rlo && gr0 + 64 < rhi, rv3 = gr0 + 96 >= rlo && gr0 + 96 < rhi;
;     const int nk = K >> 6;
;     const int rhm = rhi - 1;
;     const unsigned aoff0 = (unsigned)min(max(gr0, rlo), rhm) * (unsigned)lda + 8u * (t & 7);
;     const unsigned aoff1 = (unsigned)min(max(gr0 + 32, rlo), rhm) * (unsigned)lda + 8u * (t & 7);
;     const unsigned aoff2 = (unsigned)min(max(gr0 + 64, rlo), rhm) * (unsigned)lda + 8u * (t & 7);
;     const unsigned aoff3 = (unsigned)min(max(gr0 + 96, rlo), rhm) * (unsigned)lda + 8u * (t & 7);
;     const unsigned btoff = (unsigned)((t >> 3) * ldb + 8 * (t & 7));
;     __syncthreads();
;     ...
;     const int klast = (nk - 1) * 64;
;     LOADS(p0, 0);
;     LOADS(p1, 64);
;     STORES(p0, 0);
;     LOADS(p0, min(128, klast));
;     __syncthreads();
; DI void ph_res(KP p, const bf16_t* A, int K, const bf16_t* Wt, const float* xin, char* smem, bool dry) {
;     ...
;         gemm_tile<0>(A, K, rt * 128, 0, TOK, Wt + (size_t)ct * 128 * K, K, K, smem, acc);
.LBB0_32:
	s_add_i32 s12, s11, s33
	s_cmpk_gt_i32 s12, 0xfff
	s_cbranch_scc1 .LBB0_31
	s_ashr_i32 s13, s12, 31
	s_lshr_b32 s13, s13, 26
	s_add_i32 s13, s12, s13
	s_and_b32 s34, s13, 0xffffffc0
	s_sub_i32 s12, s12, s34
	s_lshl_b32 s13, s13, 4
	s_lshl_b32 s34, s11, 7
	s_and_b32 s13, s13, 0xfffffc00
	s_and_b32 s34, s34, 0x380
	v_mov_b32_e32 v50, v182
	s_or_b32 s36, s13, s34
	s_ashr_i32 s12, s12, 3
	v_ashrrev_i32_e32 v48, 3, v50
	v_add_u32_e32 v0, s36, v48
	s_waitcnt lgkmcnt(0)
	v_med3_i32 v1, v0, 0, v192
	v_lshlrev_b32_e32 v2, 3, v50
	v_mul_u32_u24_e32 v1, 0xb00, v1
	v_and_b32_e32 v49, 56, v2
	v_or_b32_e32 v34, v1, v49
	v_max_i32_e32 v1, 0xffffffe0, v0
	v_add_u32_e32 v1, 32, v1
	v_min_u32_e32 v1, 0xffff, v1
	v_mul_u32_u24_e32 v1, 0xb00, v1
	v_or_b32_e32 v8, v1, v49
	v_max_i32_e32 v1, 0xffffffc0, v0
	v_max_i32_e32 v0, 0xffffffa0, v0
	s_mul_i32 s34, s12, 0xb0000
	v_add_u32_e32 v0, 0x60, v0
	s_mul_hi_i32 s13, s12, 0xb0000
	s_add_u32 s34, s2, s34
	v_add_u32_e32 v1, 64, v1
	v_min_u32_e32 v0, 0xffff, v0
	s_addc_u32 s35, s6, s13
	v_min_u32_e32 v1, 0xffff, v1
	v_mul_u32_u24_e32 v0, 0xb00, v0
	s_movk_i32 s13, 0xb00
	v_mul_u32_u24_e32 v1, 0xb00, v1
	v_or_b32_e32 v24, v0, v49
	v_mul_lo_u32 v0, v48, s13
	v_or_b32_e32 v16, v1, v49
	v_or_b32_e32 v0, v0, v49
	v_mov_b32_e32 v1, v35
	s_waitcnt vmcnt(6)
	v_lshl_add_u64 v[132:133], v[0:1], 1, s[34:35]
	s_mov_b32 s13, 0x2c000
	v_add_co_u32_e32 v38, vcc, s13, v132
	v_lshlrev_b64 v[36:37], 1, v[34:35]
	s_nop 0
	v_addc_co_u32_e32 v39, vcc, 0, v133, vcc
	s_mov_b32 s13, 0x58000
	v_lshl_add_u64 v[32:33], s[14:15], 0, v[36:37]
	v_add_co_u32_e32 v42, vcc, s13, v132
	global_load_dwordx4 v[0:3], v[32:33], off
	global_load_dwordx4 v[4:7], v[132:133], off
	v_lshlrev_b32_e32 v34, 1, v8
	global_load_dwordx4 v[12:15], v[38:39], off
	v_lshlrev_b32_e32 v40, 1, v16
	v_addc_co_u32_e32 v43, vcc, 0, v133, vcc
	s_mov_b32 s13, 0x84000
	global_load_dwordx4 v[8:11], v34, s[14:15]
	global_load_dwordx4 v[16:19], v40, s[14:15]
	global_load_dwordx4 v[20:23], v[42:43], off
	v_lshlrev_b32_e32 v44, 1, v24
	v_add_co_u32_e32 v46, vcc, s13, v132
	global_load_dwordx4 v[24:27], v44, s[14:15]
	s_nop 0
	v_addc_co_u32_e32 v47, vcc, 0, v133, vcc
	global_load_dwordx4 v[28:31], v[46:47], off
	v_mul_lo_u32 v48, v48, s81
	v_lshlrev_b32_e32 v49, 1, v49
	v_add3_u32 v146, 0, v48, v49
	v_lshl_add_u64 v[48:49], s[16:17], 0, v[36:37]
	global_load_dwordx4 v[68:71], v[38:39], off offset:128
	global_load_dwordx4 v[72:75], v[46:47], off offset:128
	v_lshl_add_u64 v[36:37], s[18:19], 0, v[36:37]
	global_load_dwordx4 v[80:83], v44, s[16:17]
	global_load_dwordx4 v[76:79], v[36:37], off
	s_mov_b64 s[34:35], 0x2c000
	s_waitcnt vmcnt(17)
	v_lshl_add_u64 v[134:135], v[132:133], 0, s[34:35]
	s_mov_b64 s[34:35], 0x58000
	v_readfirstlane_b32 s37, v50
	s_waitcnt vmcnt(16)
	v_lshl_add_u64 v[136:137], v[132:133], 0, s[34:35]
	s_mov_b64 s[34:35], 0x84000
	s_waitcnt vmcnt(15)
	v_lshl_add_u64 v[138:139], v[132:133], 0, s[34:35]
	s_lshr_b32 s34, s37, 1
	s_and_b32 s34, s34, 0xfffffc0
	v_mov_b32_e32 v41, v35
	v_mov_b32_e32 v45, v35
	s_mov_b32 s13, 0
	s_waitcnt vmcnt(14)
	v_lshl_add_u64 v[140:141], s[14:15], 0, v[34:35]
	s_waitcnt vmcnt(13)
	v_lshl_add_u64 v[142:143], s[14:15], 0, v[40:41]
	s_waitcnt vmcnt(12)
	v_lshl_add_u64 v[144:145], s[14:15], 0, v[44:45]
	v_add_u32_e32 v148, 0xd800, v146
	s_barrier
	s_waitcnt vmcnt(9)
	ds_write_b128 v146, v[12:15] offset:41472
	ds_write_b128 v146, v[0:3]
	ds_write_b128 v146, v[4:7] offset:36864
	s_waitcnt vmcnt(8)
	ds_write_b128 v146, v[8:11] offset:4608
	global_load_dwordx4 v[96:99], v44, s[18:19]
	global_load_dwordx4 v[88:91], v[38:39], off offset:256
	v_and_b32_e32 v0, 31, v50
	s_waitcnt vmcnt(9)
	ds_write_b128 v146, v[16:19] offset:9216
	s_waitcnt vmcnt(8)
	ds_write_b128 v146, v[20:23] offset:46080
	s_waitcnt vmcnt(7)
	ds_write_b128 v146, v[24:27] offset:13824
	s_waitcnt vmcnt(6)
	ds_write_b128 v146, v[28:31] offset:50688
	global_load_dwordx4 v[84:87], v[132:133], off offset:128
	global_load_dwordx4 v[92:95], v[132:133], off offset:256
	global_load_dwordx4 v[100:103], v34, s[16:17]
	global_load_dwordx4 v[104:107], v34, s[18:19]
	global_load_dwordx4 v[112:115], v40, s[16:17]
	global_load_dwordx4 v[120:123], v40, s[18:19]
	global_load_dwordx4 v[116:119], v[42:43], off offset:128
	global_load_dwordx4 v[124:127], v[42:43], off offset:256
	global_load_dwordx4 v[108:111], v[48:49], off
	global_load_dwordx4 v[128:131], v[46:47], off offset:256
	v_or_b32_e32 v1, s34, v0
	v_and_or_b32 v0, s37, 64, v0
	v_lshrrev_b32_e32 v2, 1, v50
	v_mul_u32_u24_e32 v0, 0x48, v0
	v_and_b32_e32 v2, 16, v2
	v_lshlrev_b32_e32 v0, 1, v0
	v_mul_lo_u32 v1, v1, s81
	v_add3_u32 v147, 0, v0, v2
	v_mov_b32_e32 v0, 0
	v_add3_u32 v34, 0, v1, v2
	s_mov_b32 s34, 0
	v_mov_b32_e32 v1, v0
	v_mov_b32_e32 v2, v0
	v_mov_b32_e32 v3, v0
	v_mov_b32_e32 v4, v0
	v_mov_b32_e32 v5, v0
	v_mov_b32_e32 v6, v0
	v_mov_b32_e32 v7, v0
	v_mov_b32_e32 v8, v0
	v_mov_b32_e32 v9, v0
	v_mov_b32_e32 v10, v0
	v_mov_b32_e32 v11, v0
	v_mov_b32_e32 v12, v0
	v_mov_b32_e32 v13, v0
	v_mov_b32_e32 v14, v0
	v_mov_b32_e32 v15, v0
	v_mov_b32_e32 v16, v0
	v_mov_b32_e32 v17, v0
	v_mov_b32_e32 v18, v0
	v_mov_b32_e32 v19, v0
	v_mov_b32_e32 v20, v0
	v_mov_b32_e32 v21, v0
	v_mov_b32_e32 v22, v0
	v_mov_b32_e32 v23, v0
	v_mov_b32_e32 v24, v0
	v_mov_b32_e32 v25, v0
	v_mov_b32_e32 v26, v0
	v_mov_b32_e32 v27, v0
	v_mov_b32_e32 v28, v0
	v_mov_b32_e32 v29, v0
	v_mov_b32_e32 v30, v0
	v_mov_b32_e32 v31, v0
	v_mov_b32_e32 v36, v0
	v_mov_b32_e32 v37, v0
	v_mov_b32_e32 v38, v0
	v_mov_b32_e32 v39, v0
	v_mov_b32_e32 v40, v0
	v_mov_b32_e32 v41, v0
	v_mov_b32_e32 v42, v0
	v_mov_b32_e32 v43, v0
	v_mov_b32_e32 v44, v0
	v_mov_b32_e32 v45, v0
	v_mov_b32_e32 v46, v0
	v_mov_b32_e32 v47, v0
	v_mov_b32_e32 v48, v0
	v_mov_b32_e32 v49, v0
	v_mov_b32_e32 v50, v0
	v_mov_b32_e32 v51, v0
	v_mov_b32_e32 v52, v0
	v_mov_b32_e32 v53, v0
	v_mov_b32_e32 v54, v0
	v_mov_b32_e32 v55, v0
	v_mov_b32_e32 v56, v0
	v_mov_b32_e32 v57, v0
	v_mov_b32_e32 v58, v0
	v_mov_b32_e32 v59, v0
	v_mov_b32_e32 v60, v0
	v_mov_b32_e32 v61, v0
	v_mov_b32_e32 v62, v0
	v_mov_b32_e32 v63, v0
	v_mov_b32_e32 v64, v0
	v_mov_b32_e32 v65, v0
	v_mov_b32_e32 v66, v0
	v_mov_b32_e32 v67, v0
	s_waitcnt lgkmcnt(0)
	s_barrier
	s_branch .LBB0_35

; #define LOADS(S, k0) { LD1(S, 0, k0) LD1(S, 1, k0) LD1(S, 2, k0) LD1(S, 3, k0) }
; #define STORES(S, buf) { ST1(S, 0, buf) ST1(S, 1, buf) ST1(S, 2, buf) ST1(S, 3, buf) }
; template <int AMODE, bool F16 = false, bool MASK = false>
; DI void gemm_tile(const bf16_t* __restrict__ Ab, int lda, int row0, int rlo, int rhi,
;                   const bf16_t* __restrict__ Bt, int ldb, int K, char* smem, f32x16 (&acc)[2][2]) {
;     ...
;     const int gr0 = row0 + (t >> 3);
;     const bool rv0 = gr0 >= rlo && gr0 < rhi, rv1 = gr0 + 32 >= rlo && gr0 + 32 < rhi, rv2 = gr0 + 64 >= rlo && gr0 + 64 < rhi, rv3 = gr0 + 96 >= rlo && gr0 + 96 < rhi;
;     const int nk = K >> 6;
;     const int rhm = rhi - 1;
;     const unsigned aoff0 = (unsigned)min(max(gr0, rlo), rhm) * (unsigned)lda + 8u * (t & 7);
;     const unsigned aoff1 = (unsigned)min(max(gr0 + 32, rlo), rhm) * (unsigned)lda + 8u * (t & 7);
;     const unsigned aoff2 = (unsigned)min(max(gr0 + 64, rlo), rhm) * (unsigned)lda + 8u * (t & 7);
;     const unsigned aoff3 = (unsigned)min(max(gr0 + 96, rlo), rhm) * (unsigned)lda + 8u * (t & 7);
;     const unsigned btoff = (unsigned)((t >> 3) * ldb + 8 * (t & 7));
;     __syncthreads();
;     ...
;     const int klast = (nk - 1) * 64;
;     LOADS(p0, 0);
;     LOADS(p1, 64);
;     STORES(p0, 0);
;     LOADS(p0, min(128, klast));
;     __syncthreads();
; DI void ph_up(KP p, int l, char* smem) {
;     ...
;         else gemm_tile<0, true, false>((const bf16_t*)(p->ws + OFF_XB), DM, b * SEQ + s0 - 1, b * SEQ, (b + 1) * SEQ, (const bf16_t*)(p->ws + OFF_WUP) + ((size_t)l * 2 * DFF + ct * 128) * DM, DM, DM, smem, acc);
.LBB0_66:
	s_andn2_b64 vcc, exec, s[18:19]
	s_cbranch_vccnz .LBB0_71
	s_load_dwordx2 s[16:17], s[0:1], 0xe0
	v_mov_b32_e32 v58, v182
	v_mov_b32_e32 v7, v35
	v_ashrrev_i32_e32 v52, 3, v58
	s_waitcnt lgkmcnt(0)
	s_add_u32 s18, s16, 0x2d180000
	s_addc_u32 s19, s17, 0
	s_lshl_b32 s15, s13, 7
	s_ashr_i32 s35, s15, 31
	s_add_u32 s34, s6, s15
	s_addc_u32 s35, s2, s35
	s_lshl_b64 s[34:35], s[34:35], 11
	s_add_u32 s34, s16, s34
	v_add_u32_e32 v0, s11, v52
	s_addc_u32 s35, s17, s35
	v_add_u32_e32 v1, 32, v0
	v_add_u32_e32 v2, 64, v0
	v_add_u32_e32 v3, 0x60, v0
	s_or_b32 s15, s12, 0x1fff
	v_max_i32_e32 v0, s12, v0
	v_lshlrev_b32_e32 v4, 3, v58
	v_min_i32_e32 v0, s15, v0
	v_and_b32_e32 v53, 56, v4
	v_lshl_or_b32 v34, v0, 10, v53
	v_max_i32_e32 v0, s12, v1
	v_min_i32_e32 v0, s15, v0
	v_lshl_or_b32 v4, v0, 10, v53
	v_max_i32_e32 v0, s12, v2
	v_min_i32_e32 v0, s15, v0
	v_lshl_or_b32 v16, v0, 10, v53
	v_max_i32_e32 v0, s12, v3
	v_lshl_or_b32 v6, v52, 10, v53
	v_min_i32_e32 v0, s15, v0
	v_lshl_add_u64 v[38:39], v[6:7], 1, s[34:35]
	s_mov_b32 s15, 0x3780000
	v_add_co_u32_e32 v8, vcc, s15, v38
	s_mov_b32 s15, 0x3790000
	s_nop 0
	v_addc_co_u32_e32 v9, vcc, 0, v39, vcc
	v_add_co_u32_e32 v42, vcc, s15, v38
	s_mov_b32 s15, 0x37a0000
	s_nop 0
	v_addc_co_u32_e32 v43, vcc, 0, v39, vcc
	v_add_co_u32_e32 v46, vcc, s15, v38
	v_mov_b32_e32 v5, v35
	v_mov_b32_e32 v17, v35
	v_addc_co_u32_e32 v47, vcc, 0, v39, vcc
	s_mov_b32 s15, 0x37b0000
	v_lshl_or_b32 v20, v0, 10, v53
	v_lshlrev_b64 v[36:37], 1, v[34:35]
	v_lshlrev_b64 v[40:41], 1, v[4:5]
	v_lshlrev_b64 v[44:45], 1, v[16:17]
	v_mov_b32_e32 v21, v35
	v_add_co_u32_e32 v50, vcc, s15, v38
	v_lshl_add_u64 v[148:149], s[18:19], 0, v[36:37]
	v_lshl_add_u64 v[150:151], s[18:19], 0, v[40:41]
	v_lshl_add_u64 v[152:153], s[18:19], 0, v[44:45]
	v_lshlrev_b64 v[48:49], 1, v[20:21]
	v_addc_co_u32_e32 v51, vcc, 0, v39, vcc
	global_load_dwordx4 v[0:3], v[148:149], off
	global_load_dwordx4 v[4:7], v[150:151], off
	s_nop 0
	global_load_dwordx4 v[8:11], v[8:9], off
	s_nop 0
	global_load_dwordx4 v[12:15], v[42:43], off
	global_load_dwordx4 v[16:19], v[46:47], off
	v_lshl_add_u64 v[154:155], s[18:19], 0, v[48:49]
	global_load_dwordx4 v[20:23], v[152:153], off
	global_load_dwordx4 v[24:27], v[154:155], off
	global_load_dwordx4 v[28:31], v[50:51], off
	global_load_dwordx4 v[68:71], v[46:47], off offset:128
	s_add_u32 s18, s16, 0x2d180080
	s_mov_b64 s[36:37], 0x3780000
	v_lshl_add_u64 v[156:157], v[38:39], 0, s[36:37]
	s_mov_b64 s[36:37], 0x3790000
	s_addc_u32 s19, s17, 0
	v_mul_lo_u32 v34, v52, s81
	v_lshlrev_b32_e32 v52, 1, v53
	v_lshl_add_u64 v[158:159], v[38:39], 0, s[36:37]
	s_mov_b64 s[36:37], 0x37a0000
	s_add_u32 s16, s16, 0x2d180100
	v_add3_u32 v34, 0, v34, v52
	v_lshl_add_u64 v[160:161], v[38:39], 0, s[36:37]
	s_mov_b64 s[36:37], 0x37b0000
	s_addc_u32 s17, s17, 0
	v_lshl_add_u64 v[162:163], v[38:39], 0, s[36:37]
	v_lshl_add_u64 v[38:39], s[18:19], 0, v[36:37]
	v_lshl_add_u64 v[52:53], s[18:19], 0, v[40:41]
	v_lshl_add_u64 v[54:55], s[18:19], 0, v[44:45]
	v_lshl_add_u64 v[56:57], s[18:19], 0, v[48:49]
	global_load_dwordx4 v[72:75], v[156:157], off offset:128
	global_load_dwordx4 v[76:79], v[38:39], off
	global_load_dwordx4 v[80:83], v[52:53], off
	global_load_dwordx4 v[84:87], v[54:55], off
	global_load_dwordx4 v[88:91], v[56:57], off
	global_load_dwordx4 v[92:95], v[156:157], off offset:256
	v_readfirstlane_b32 s34, v58
	v_and_b32_e32 v59, 31, v58
	s_mov_b32 s15, 0
	v_add_u32_e32 v168, 0xd800, v34
	s_mov_b32 s18, 0
	s_barrier
	s_waitcnt vmcnt(12)
	ds_write_b128 v34, v[8:11] offset:36864
	ds_write_b128 v34, v[0:3]
	ds_write_b128 v34, v[4:7] offset:4608
	s_waitcnt vmcnt(11)
	ds_write_b128 v34, v[12:15] offset:41472
	s_waitcnt vmcnt(9)
	ds_write_b128 v34, v[20:23] offset:9216
	ds_write_b128 v34, v[16:19] offset:46080
	s_waitcnt vmcnt(8)
	ds_write_b128 v34, v[24:27] offset:13824
	s_waitcnt vmcnt(7)
	ds_write_b128 v34, v[28:31] offset:50688
	v_lshl_add_u64 v[0:1], s[16:17], 0, v[36:37]
	global_load_dwordx4 v[100:103], v[46:47], off offset:256
	v_lshl_add_u64 v[2:3], s[16:17], 0, v[40:41]
	global_load_dwordx4 v[96:99], v[0:1], off
	global_load_dwordx4 v[108:111], v[2:3], off
	global_load_dwordx4 v[104:107], v[42:43], off offset:128
	global_load_dwordx4 v[112:115], v[42:43], off offset:256
	v_lshl_add_u64 v[0:1], s[16:17], 0, v[44:45]
	v_lshl_add_u64 v[2:3], s[16:17], 0, v[48:49]
	global_load_dwordx4 v[116:119], v[0:1], off
	global_load_dwordx4 v[124:127], v[2:3], off
	global_load_dwordx4 v[120:123], v[50:51], off offset:128
	global_load_dwordx4 v[128:131], v[50:51], off offset:256
	s_lshr_b32 s16, s34, 1
	s_and_b32 s16, s16, 0xfffffc0
	v_or_b32_e32 v0, s16, v59
	v_lshrrev_b32_e32 v1, 1, v58
	v_mul_lo_u32 v0, v0, s81
	v_and_b32_e32 v1, 16, v1
	v_add3_u32 v166, 0, v0, v1
	v_and_or_b32 v0, s34, 64, v59
	v_mul_u32_u24_e32 v0, 0x48, v0
	v_lshlrev_b32_e32 v0, 1, v0
	v_add3_u32 v167, 0, v0, v1
	v_mov_b32_e32 v0, 0
	v_mov_b32_e32 v1, v0
	v_mov_b32_e32 v2, v0
	v_mov_b32_e32 v3, v0
	v_mov_b32_e32 v4, v0
	v_mov_b32_e32 v5, v0
	v_mov_b32_e32 v6, v0
	v_mov_b32_e32 v7, v0
	v_mov_b32_e32 v8, v0
	v_mov_b32_e32 v9, v0
	v_mov_b32_e32 v10, v0
	v_mov_b32_e32 v11, v0
	v_mov_b32_e32 v12, v0
	v_mov_b32_e32 v13, v0
	v_mov_b32_e32 v14, v0
	v_mov_b32_e32 v15, v0
	v_mov_b32_e32 v16, v0
	v_mov_b32_e32 v17, v0
	v_mov_b32_e32 v18, v0
	v_mov_b32_e32 v19, v0
	v_mov_b32_e32 v20, v0
	v_mov_b32_e32 v21, v0
	v_mov_b32_e32 v22, v0
	v_mov_b32_e32 v23, v0
	v_mov_b32_e32 v24, v0
	v_mov_b32_e32 v25, v0
	v_mov_b32_e32 v26, v0
	v_mov_b32_e32 v27, v0
	v_mov_b32_e32 v28, v0
	v_mov_b32_e32 v29, v0
	v_mov_b32_e32 v30, v0
	v_mov_b32_e32 v31, v0
	v_mov_b32_e32 v36, v0
	v_mov_b32_e32 v37, v0
	v_mov_b32_e32 v38, v0
	v_mov_b32_e32 v39, v0
	v_mov_b32_e32 v40, v0
	v_mov_b32_e32 v41, v0
	v_mov_b32_e32 v42, v0
	v_mov_b32_e32 v43, v0
	v_mov_b32_e32 v44, v0
	v_mov_b32_e32 v45, v0
	v_mov_b32_e32 v46, v0
	v_mov_b32_e32 v47, v0
	v_mov_b32_e32 v48, v0
	v_mov_b32_e32 v49, v0
	v_mov_b32_e32 v50, v0
	v_mov_b32_e32 v51, v0
	v_mov_b32_e32 v52, v0
	v_mov_b32_e32 v53, v0
	v_mov_b32_e32 v54, v0
	v_mov_b32_e32 v55, v0
	v_mov_b32_e32 v56, v0
	v_mov_b32_e32 v57, v0
	v_mov_b32_e32 v58, v0
	v_mov_b32_e32 v59, v0
	v_mov_b32_e32 v60, v0
	v_mov_b32_e32 v61, v0
	v_mov_b32_e32 v62, v0
	v_mov_b32_e32 v63, v0
	v_mov_b32_e32 v64, v0
	v_mov_b32_e32 v65, v0
	v_mov_b32_e32 v66, v0
	v_mov_b32_e32 v67, v0
	s_waitcnt lgkmcnt(0)
	s_barrier
	s_branch .LBB0_69

; template <int AMODE, bool F16 = false, bool MASK = false>
; DI void gemm_tile(const bf16_t* __restrict__ Ab, int lda, int row0, int rlo, int rhi,
;                   const bf16_t* __restrict__ Bt, int ldb, int K, char* smem, f32x16 (&acc)[2][2]) {
;     ...
;     const int gr0 = row0 + (t >> 3);
;     const bool rv0 = gr0 >= rlo && gr0 < rhi, rv1 = gr0 + 32 >= rlo && gr0 + 32 < rhi, rv2 = gr0 + 64 >= rlo && gr0 + 64 < rhi, rv3 = gr0 + 96 >= rlo && gr0 + 96 < rhi;
;     const int nk = K >> 6;
;     const int rhm = rhi - 1;
;     const unsigned aoff0 = (unsigned)min(max(gr0, rlo), rhm) * (unsigned)lda + 8u * (t & 7);
;     const unsigned aoff1 = (unsigned)min(max(gr0 + 32, rlo), rhm) * (unsigned)lda + 8u * (t & 7);
;     const unsigned aoff2 = (unsigned)min(max(gr0 + 64, rlo), rhm) * (unsigned)lda + 8u * (t & 7);
;     const unsigned aoff3 = (unsigned)min(max(gr0 + 96, rlo), rhm) * (unsigned)lda + 8u * (t & 7);
;     const unsigned btoff = (unsigned)((t >> 3) * ldb + 8 * (t & 7));
;     __syncthreads();
; DI void ph_up(KP p, int l, char* smem) {
;     ...
;         if (rl == 0 || rl == 65) gemm_tile<0, true, true>((const bf16_t*)(p->ws + OFF_XB), DM, b * SEQ + s0 - 1, b * SEQ, (b + 1) * SEQ, (const bf16_t*)(p->ws + OFF_WUP) + ((size_t)l * 2 * DFF + ct * 128) * DM, DM, DM, smem, acc);
.LBB0_73:
	s_load_dwordx2 s[16:17], s[0:1], 0xe0
	v_mov_b32_e32 v54, v182
	v_mov_b32_e32 v7, v35
	v_ashrrev_i32_e32 v55, 3, v54
	s_waitcnt lgkmcnt(0)
	s_add_u32 s18, s16, 0x2d180000
	s_addc_u32 s19, s17, 0
	s_lshl_b32 s13, s13, 7
	s_add_i32 s15, s12, 0x2000
	s_ashr_i32 s35, s13, 31
	s_add_u32 s34, s6, s13
	s_addc_u32 s35, s2, s35
	s_lshl_b64 s[34:35], s[34:35], 11
	s_add_u32 s34, s16, s34
	v_add_u32_e32 v52, s11, v55
	s_addc_u32 s35, s17, s35
	s_or_b32 s13, s12, 0x1fff
	v_max_i32_e32 v0, s12, v52
	v_lshlrev_b32_e32 v1, 3, v54
	v_add_u32_e32 v53, 32, v52
	v_min_i32_e32 v0, s13, v0
	v_and_b32_e32 v58, 56, v1
	v_lshl_or_b32 v34, v0, 10, v58
	v_max_i32_e32 v0, s12, v53
	v_add_u32_e32 v56, 64, v52
	v_min_i32_e32 v0, s13, v0
	v_lshl_or_b32 v4, v0, 10, v58
	v_max_i32_e32 v0, s12, v56
	v_add_u32_e32 v57, 0x60, v52
	v_min_i32_e32 v0, s13, v0
	v_lshl_or_b32 v16, v0, 10, v58
	v_max_i32_e32 v0, s12, v57
	v_lshl_or_b32 v6, v55, 10, v58
	v_min_i32_e32 v0, s13, v0
	v_lshl_add_u64 v[38:39], v[6:7], 1, s[34:35]
	s_mov_b32 s13, 0x3780000
	v_add_co_u32_e32 v8, vcc, s13, v38
	s_mov_b32 s13, 0x3790000
	s_nop 0
	v_addc_co_u32_e32 v9, vcc, 0, v39, vcc
	v_lshlrev_b64 v[36:37], 1, v[34:35]
	v_mov_b32_e32 v5, v35
	v_add_co_u32_e32 v42, vcc, s13, v38
	v_lshl_add_u64 v[148:149], s[18:19], 0, v[36:37]
	v_lshlrev_b64 v[40:41], 1, v[4:5]
	v_addc_co_u32_e32 v43, vcc, 0, v39, vcc
	v_mov_b32_e32 v17, v35
	s_mov_b32 s13, 0x37a0000
	v_lshl_or_b32 v24, v0, 10, v58
	global_load_dwordx4 v[0:3], v[148:149], off
	v_lshl_add_u64 v[150:151], s[18:19], 0, v[40:41]
	v_lshlrev_b64 v[44:45], 1, v[16:17]
	v_add_co_u32_e32 v46, vcc, s13, v38
	v_mov_b32_e32 v25, v35
	global_load_dwordx4 v[4:7], v[150:151], off
	v_lshl_add_u64 v[152:153], s[18:19], 0, v[44:45]
	v_addc_co_u32_e32 v47, vcc, 0, v39, vcc
	v_lshlrev_b64 v[48:49], 1, v[24:25]
	s_mov_b32 s13, 0x37b0000
	global_load_dwordx4 v[8:11], v[8:9], off
	s_nop 0
	global_load_dwordx4 v[12:15], v[42:43], off
	global_load_dwordx4 v[16:19], v[152:153], off
	v_lshl_add_u64 v[154:155], s[18:19], 0, v[48:49]
	v_add_co_u32_e32 v50, vcc, s13, v38
	global_load_dwordx4 v[24:27], v[154:155], off
	s_nop 0
	v_addc_co_u32_e32 v51, vcc, 0, v39, vcc
	global_load_dwordx4 v[20:23], v[46:47], off
	global_load_dwordx4 v[28:31], v[50:51], off
	v_cmp_le_i32_e32 vcc, s12, v52
	v_cmp_gt_i32_e64 s[42:43], s15, v52
	s_mov_b64 s[18:19], 0x3780000
	s_and_b64 s[42:43], vcc, s[42:43]
	v_cmp_le_i32_e32 vcc, s12, v53
	v_cmp_gt_i32_e64 s[44:45], s15, v53
	v_lshl_add_u64 v[156:157], v[38:39], 0, s[18:19]
	s_and_b64 s[44:45], vcc, s[44:45]
	v_cmp_le_i32_e32 vcc, s12, v56
	v_cmp_gt_i32_e64 s[46:47], s15, v56
	s_mov_b64 s[18:19], 0x3790000
	s_and_b64 s[46:47], vcc, s[46:47]
	v_cmp_le_i32_e32 vcc, s12, v57
	v_cmp_gt_i32_e64 s[48:49], s15, v57
	v_lshl_add_u64 v[158:159], v[38:39], 0, s[18:19]
	s_mov_b64 s[18:19], 0x37a0000
	s_and_b64 s[48:49], vcc, s[48:49]
	v_lshl_add_u64 v[160:161], v[38:39], 0, s[18:19]
	s_mov_b64 s[18:19], 0x37b0000
	v_lshl_add_u64 v[162:163], v[38:39], 0, s[18:19]
	s_add_u32 s18, s16, 0x2d180080
	s_addc_u32 s19, s17, 0
	v_lshl_add_u64 v[38:39], s[18:19], 0, v[36:37]
	global_load_dwordx4 v[68:71], v[156:157], off offset:128
	global_load_dwordx4 v[92:95], v[156:157], off offset:256
	v_lshl_add_u64 v[52:53], s[18:19], 0, v[40:41]
	global_load_dwordx4 v[88:91], v[38:39], off
	global_load_dwordx4 v[80:83], v[52:53], off
	v_lshl_add_u64 v[38:39], s[18:19], 0, v[44:45]
	global_load_dwordx4 v[72:75], v[46:47], off offset:128
	v_lshl_add_u64 v[52:53], s[18:19], 0, v[48:49]
	global_load_dwordx4 v[76:79], v[38:39], off
	global_load_dwordx4 v[84:87], v[52:53], off
	v_mul_lo_u32 v34, v55, s81
	v_lshlrev_b32_e32 v38, 1, v58
	v_add3_u32 v34, 0, v34, v38
	s_add_u32 s16, s16, 0x2d180100
	s_addc_u32 s17, s17, 0
	v_readfirstlane_b32 s13, v54
	s_lshr_b32 s15, s13, 1
	v_and_b32_e32 v59, 31, v54
	s_and_b32 s15, s15, 0xfffffc0
	s_mov_b32 s12, 0
	v_add_u32_e32 v168, 0xd800, v34
	s_waitcnt vmcnt(14)
	v_cndmask_b32_e64 v1, 0, v1, s[42:43]
	v_cndmask_b32_e64 v0, 0, v0, s[42:43]
	v_cndmask_b32_e64 v3, 0, v3, s[42:43]
	v_cndmask_b32_e64 v2, 0, v2, s[42:43]
	s_barrier
; #define LOADS(S, k0) { LD1(S, 0, k0) LD1(S, 1, k0) LD1(S, 2, k0) LD1(S, 3, k0) }
; #define STORES(S, buf) { ST1(S, 0, buf) ST1(S, 1, buf) ST1(S, 2, buf) ST1(S, 3, buf) }
; template <int AMODE, bool F16 = false, bool MASK = false>
; DI void gemm_tile(const bf16_t* __restrict__ Ab, int lda, int row0, int rlo, int rhi,
;                   const bf16_t* __restrict__ Bt, int ldb, int K, char* smem, f32x16 (&acc)[2][2]) {
;     ...
;     const int klast = (nk - 1) * 64;
;     LOADS(p0, 0);
;     LOADS(p1, 64);
;     STORES(p0, 0);
;     LOADS(p0, min(128, klast));
;     __syncthreads();
	ds_write_b128 v34, v[0:3]
	s_waitcnt vmcnt(12)
	ds_write_b128 v34, v[8:11] offset:36864
	v_cndmask_b32_e64 v1, 0, v5, s[44:45]
	v_cndmask_b32_e64 v0, 0, v4, s[44:45]
	v_cndmask_b32_e64 v3, 0, v7, s[44:45]
	v_cndmask_b32_e64 v2, 0, v6, s[44:45]
	ds_write_b128 v34, v[0:3] offset:4608
	s_waitcnt vmcnt(11)
	ds_write_b128 v34, v[12:15] offset:41472
	s_waitcnt vmcnt(10)
	v_cndmask_b32_e64 v1, 0, v17, s[46:47]
	v_cndmask_b32_e64 v0, 0, v16, s[46:47]
	v_cndmask_b32_e64 v3, 0, v19, s[46:47]
	v_cndmask_b32_e64 v2, 0, v18, s[46:47]
	ds_write_b128 v34, v[0:3] offset:9216
	s_waitcnt vmcnt(8)
	ds_write_b128 v34, v[20:23] offset:46080
	v_cndmask_b32_e64 v1, 0, v25, s[48:49]
	v_cndmask_b32_e64 v0, 0, v24, s[48:49]
	v_cndmask_b32_e64 v3, 0, v27, s[48:49]
	v_cndmask_b32_e64 v2, 0, v26, s[48:49]
	ds_write_b128 v34, v[0:3] offset:13824
	s_waitcnt vmcnt(7)
	ds_write_b128 v34, v[28:31] offset:50688
	v_lshl_add_u64 v[0:1], s[16:17], 0, v[36:37]
	global_load_dwordx4 v[104:107], v[46:47], off offset:256
	v_lshl_add_u64 v[2:3], s[16:17], 0, v[40:41]
	global_load_dwordx4 v[112:115], v[0:1], off
	global_load_dwordx4 v[116:119], v[2:3], off
	global_load_dwordx4 v[96:99], v[42:43], off offset:128
	global_load_dwordx4 v[108:111], v[42:43], off offset:256
	v_lshl_add_u64 v[0:1], s[16:17], 0, v[44:45]
	v_lshl_add_u64 v[2:3], s[16:17], 0, v[48:49]
	global_load_dwordx4 v[120:123], v[0:1], off
	global_load_dwordx4 v[124:127], v[2:3], off
	global_load_dwordx4 v[100:103], v[50:51], off offset:128
	global_load_dwordx4 v[128:131], v[50:51], off offset:256
	v_or_b32_e32 v0, s15, v59
	v_lshrrev_b32_e32 v1, 1, v54
	v_mul_lo_u32 v0, v0, s81
	v_and_b32_e32 v1, 16, v1
	v_add3_u32 v166, 0, v0, v1
	v_and_or_b32 v0, s13, 64, v59
	v_mul_u32_u24_e32 v0, 0x48, v0
	v_lshlrev_b32_e32 v0, 1, v0
	v_add3_u32 v167, 0, v0, v1
	v_mov_b32_e32 v0, 0
	s_mov_b32 s13, 0
	v_mov_b32_e32 v1, v0
	v_mov_b32_e32 v2, v0
	v_mov_b32_e32 v3, v0
	v_mov_b32_e32 v4, v0
	v_mov_b32_e32 v5, v0
	v_mov_b32_e32 v6, v0
	v_mov_b32_e32 v7, v0
	v_mov_b32_e32 v8, v0
	v_mov_b32_e32 v9, v0
	v_mov_b32_e32 v10, v0
	v_mov_b32_e32 v11, v0
	v_mov_b32_e32 v12, v0
	v_mov_b32_e32 v13, v0
	v_mov_b32_e32 v14, v0
	v_mov_b32_e32 v15, v0
	v_mov_b32_e32 v16, v0
	v_mov_b32_e32 v17, v0
	v_mov_b32_e32 v18, v0
	v_mov_b32_e32 v19, v0
	v_mov_b32_e32 v20, v0
	v_mov_b32_e32 v21, v0
	v_mov_b32_e32 v22, v0
	v_mov_b32_e32 v23, v0
	v_mov_b32_e32 v24, v0
	v_mov_b32_e32 v25, v0
	v_mov_b32_e32 v26, v0
	v_mov_b32_e32 v27, v0
	v_mov_b32_e32 v28, v0
	v_mov_b32_e32 v29, v0
	v_mov_b32_e32 v30, v0
	v_mov_b32_e32 v31, v0
	v_mov_b32_e32 v36, v0
	v_mov_b32_e32 v37, v0
	v_mov_b32_e32 v38, v0
	v_mov_b32_e32 v39, v0
	v_mov_b32_e32 v40, v0
	v_mov_b32_e32 v41, v0
	v_mov_b32_e32 v42, v0
	v_mov_b32_e32 v43, v0
	v_mov_b32_e32 v44, v0
	v_mov_b32_e32 v45, v0
	v_mov_b32_e32 v46, v0
	v_mov_b32_e32 v47, v0
	v_mov_b32_e32 v48, v0
	v_mov_b32_e32 v49, v0
	v_mov_b32_e32 v50, v0
	v_mov_b32_e32 v51, v0
	v_mov_b32_e32 v52, v0
	v_mov_b32_e32 v53, v0
	v_mov_b32_e32 v54, v0
	v_mov_b32_e32 v55, v0
	v_mov_b32_e32 v56, v0
	v_mov_b32_e32 v57, v0
	v_mov_b32_e32 v58, v0
	v_mov_b32_e32 v59, v0
	v_mov_b32_e32 v60, v0
	v_mov_b32_e32 v61, v0
	v_mov_b32_e32 v62, v0
	v_mov_b32_e32 v63, v0
	v_mov_b32_e32 v64, v0
	v_mov_b32_e32 v65, v0
	v_mov_b32_e32 v66, v0
	v_mov_b32_e32 v67, v0
	s_waitcnt lgkmcnt(0)
	s_barrier
	s_branch .LBB0_75

; #define LOADS(S, k0) { LD1(S, 0, k0) LD1(S, 1, k0) LD1(S, 2, k0) LD1(S, 3, k0) }
; #define STORES(S, buf) { ST1(S, 0, buf) ST1(S, 1, buf) ST1(S, 2, buf) ST1(S, 3, buf) }
; template <int AMODE, bool F16 = false, bool MASK = false>
; DI void gemm_tile(const bf16_t* __restrict__ Ab, int lda, int row0, int rlo, int rhi,
;                   const bf16_t* __restrict__ Bt, int ldb, int K, char* smem, f32x16 (&acc)[2][2]) {
;     ...
;     const int gr0 = row0 + (t >> 3);
;     const bool rv0 = gr0 >= rlo && gr0 < rhi, rv1 = gr0 + 32 >= rlo && gr0 + 32 < rhi, rv2 = gr0 + 64 >= rlo && gr0 + 64 < rhi, rv3 = gr0 + 96 >= rlo && gr0 + 96 < rhi;
;     const int nk = K >> 6;
;     const int rhm = rhi - 1;
;     const unsigned aoff0 = (unsigned)min(max(gr0, rlo), rhm) * (unsigned)lda + 8u * (t & 7);
;     const unsigned aoff1 = (unsigned)min(max(gr0 + 32, rlo), rhm) * (unsigned)lda + 8u * (t & 7);
;     const unsigned aoff2 = (unsigned)min(max(gr0 + 64, rlo), rhm) * (unsigned)lda + 8u * (t & 7);
;     const unsigned aoff3 = (unsigned)min(max(gr0 + 96, rlo), rhm) * (unsigned)lda + 8u * (t & 7);
;     const unsigned btoff = (unsigned)((t >> 3) * ldb + 8 * (t & 7));
;     __syncthreads();
;     ...
;     const int klast = (nk - 1) * 64;
;     LOADS(p0, 0);
;     LOADS(p1, 64);
;     STORES(p0, 0);
;     LOADS(p0, min(128, klast));
;     __syncthreads();
; DI void ph_res(KP p, const bf16_t* A, int K, const bf16_t* Wt, const float* xin, char* smem, bool dry) {
;     ...
;         gemm_tile<0>(A, K, rt * 128, 0, TOK, Wt + (size_t)ct * 128 * K, K, K, smem, acc);
.LBB0_93:
	s_add_i32 s12, s11, s33
	s_cmpk_gt_i32 s12, 0xfff
	s_cbranch_scc1 .LBB0_92
	s_ashr_i32 s13, s12, 31
	s_lshr_b32 s13, s13, 26
	s_add_i32 s13, s12, s13
	s_and_b32 s34, s13, 0xffffffc0
	s_sub_i32 s12, s12, s34
	s_ashr_i32 s36, s12, 3
	s_lshl_b32 s12, s13, 4
	s_lshl_b32 s13, s11, 7
	s_and_b32 s12, s12, 0xfffffc00
	s_and_b32 s13, s13, 0x380
	v_mov_b32_e32 v48, v182
	s_or_b32 s42, s12, s13
	s_ashr_i32 s37, s36, 31
	v_ashrrev_i32_e32 v49, 3, v48
	v_add_u32_e32 v0, s42, v49
	v_lshlrev_b32_e32 v2, 3, v48
	v_max_i32_e32 v3, 0xffffffe0, v0
	s_lshl_b64 s[12:13], s[36:37], 18
	v_and_b32_e32 v2, 56, v2
	v_add_u32_e32 v3, 32, v3
	s_add_u32 s12, s2, s12
	s_waitcnt lgkmcnt(0)
	v_med3_i32 v1, v0, 0, v192
	v_min_u32_e32 v8, 0xffff, v3
	v_max_i32_e32 v3, 0xffffffc0, v0
	v_max_i32_e32 v0, 0xffffffa0, v0
	v_lshlrev_b32_e32 v50, 1, v2
	s_addc_u32 s13, s6, s13
	v_add_u32_e32 v3, 64, v3
	v_add_u32_e32 v0, 0x60, v0
	v_lshl_or_b32 v4, v49, 10, v2
	v_lshl_or_b32 v34, v1, 11, v50
	v_mov_b32_e32 v5, v35
	v_min_u32_e32 v16, 0xffff, v3
	v_min_u32_e32 v24, 0xffff, v0
	global_load_dwordx4 v[0:3], v34, s[14:15]
	global_load_dwordx4 v[68:71], v34, s[16:17]
	s_waitcnt vmcnt(9)
	v_lshl_add_u64 v[32:33], v[4:5], 1, s[12:13]
	s_mov_b32 s12, 0x10000
	global_load_dwordx4 v[4:7], v[32:33], off
	v_lshl_or_b32 v36, v8, 11, v50
	v_add_co_u32_e32 v38, vcc, s12, v32
	global_load_dwordx4 v[8:11], v36, s[14:15]
	s_nop 0
	v_addc_co_u32_e32 v39, vcc, 0, v33, vcc
	v_lshl_or_b32 v40, v16, 11, v50
	s_mov_b32 s12, 0x20000
	global_load_dwordx4 v[16:19], v40, s[14:15]
	v_add_co_u32_e32 v42, vcc, s12, v32
	v_lshl_or_b32 v44, v24, 11, v50
	s_nop 0
	v_addc_co_u32_e32 v43, vcc, 0, v33, vcc
	global_load_dwordx4 v[24:27], v44, s[14:15]
	s_mov_b32 s12, 0x30000
	global_load_dwordx4 v[12:15], v[38:39], off
	global_load_dwordx4 v[20:23], v[42:43], off
	v_add_co_u32_e32 v46, vcc, s12, v32
	v_mul_lo_u32 v49, v49, s81
	s_nop 0
	v_addc_co_u32_e32 v47, vcc, 0, v33, vcc
	global_load_dwordx4 v[28:31], v[46:47], off
	v_add3_u32 v146, 0, v49, v50
	global_load_dwordx4 v[72:75], v[32:33], off offset:128
	global_load_dwordx4 v[76:79], v40, s[16:17]
	global_load_dwordx4 v[80:83], v34, s[18:19]
	global_load_dwordx4 v[92:95], v40, s[18:19]
	global_load_dwordx4 v[88:91], v[42:43], off offset:128
	global_load_dwordx4 v[84:87], v[32:33], off offset:256
	global_load_dwordx4 v[96:99], v[42:43], off offset:256
	s_mov_b64 s[34:35], 0x10000
	s_waitcnt vmcnt(20)
	v_lshl_add_u64 v[136:137], v[32:33], 0, s[34:35]
	s_mov_b64 s[34:35], 0x20000
	v_readfirstlane_b32 s13, v48
	s_waitcnt vmcnt(18)
	v_lshl_add_u64 v[140:141], v[32:33], 0, s[34:35]
	s_mov_b64 s[34:35], 0x30000
	s_waitcnt vmcnt(16)
	v_lshl_add_u64 v[144:145], v[32:33], 0, s[34:35]
	s_lshr_b32 s34, s13, 1
	s_and_b32 s34, s34, 0xfffffc0
	v_mov_b32_e32 v37, v35
	v_mov_b32_e32 v41, v35
	v_mov_b32_e32 v45, v35
	s_mov_b32 s12, 0
	v_lshl_add_u64 v[132:133], s[14:15], 0, v[34:35]
	v_lshl_add_u64 v[134:135], s[14:15], 0, v[36:37]
	v_lshl_add_u64 v[138:139], s[14:15], 0, v[40:41]
	v_lshl_add_u64 v[142:143], s[14:15], 0, v[44:45]
	v_add_u32_e32 v148, 0xd800, v146
	s_barrier
	s_waitcnt vmcnt(15)
	ds_write_b128 v146, v[0:3]
	s_waitcnt vmcnt(13)
	ds_write_b128 v146, v[4:7] offset:36864
	s_waitcnt vmcnt(12)
	ds_write_b128 v146, v[8:11] offset:4608
	s_waitcnt vmcnt(11)
	ds_write_b128 v146, v[16:19] offset:9216
	s_waitcnt vmcnt(10)
	ds_write_b128 v146, v[24:27] offset:13824
	s_waitcnt vmcnt(9)
	ds_write_b128 v146, v[12:15] offset:41472
	s_waitcnt vmcnt(8)
	ds_write_b128 v146, v[20:23] offset:46080
	s_waitcnt vmcnt(7)
	ds_write_b128 v146, v[28:31] offset:50688
	global_load_dwordx4 v[100:103], v36, s[16:17]
	global_load_dwordx4 v[104:107], v36, s[18:19]
	global_load_dwordx4 v[108:111], v[38:39], off offset:128
	global_load_dwordx4 v[112:115], v[38:39], off offset:256
	global_load_dwordx4 v[116:119], v44, s[16:17]
	global_load_dwordx4 v[124:127], v44, s[18:19]
	global_load_dwordx4 v[120:123], v[46:47], off offset:128
	global_load_dwordx4 v[128:131], v[46:47], off offset:256
	v_and_b32_e32 v0, 31, v48
	v_or_b32_e32 v1, s34, v0
	v_and_or_b32 v0, s13, 64, v0
	v_lshrrev_b32_e32 v2, 1, v48
	v_mul_u32_u24_e32 v0, 0x48, v0
	v_and_b32_e32 v2, 16, v2
	v_lshlrev_b32_e32 v0, 1, v0
	v_mul_lo_u32 v1, v1, s81
	v_add3_u32 v147, 0, v0, v2
	v_mov_b32_e32 v0, 0
	v_add3_u32 v34, 0, v1, v2
	s_mov_b32 s13, 0
	v_mov_b32_e32 v1, v0
	v_mov_b32_e32 v2, v0
	v_mov_b32_e32 v3, v0
	v_mov_b32_e32 v4, v0
	v_mov_b32_e32 v5, v0
	v_mov_b32_e32 v6, v0
	v_mov_b32_e32 v7, v0
	v_mov_b32_e32 v8, v0
	v_mov_b32_e32 v9, v0
	v_mov_b32_e32 v10, v0
	v_mov_b32_e32 v11, v0
	v_mov_b32_e32 v12, v0
	v_mov_b32_e32 v13, v0
	v_mov_b32_e32 v14, v0
	v_mov_b32_e32 v15, v0
	v_mov_b32_e32 v16, v0
	v_mov_b32_e32 v17, v0
	v_mov_b32_e32 v18, v0
	v_mov_b32_e32 v19, v0
	v_mov_b32_e32 v20, v0
	v_mov_b32_e32 v21, v0
	v_mov_b32_e32 v22, v0
	v_mov_b32_e32 v23, v0
	v_mov_b32_e32 v24, v0
	v_mov_b32_e32 v25, v0
	v_mov_b32_e32 v26, v0
	v_mov_b32_e32 v27, v0
	v_mov_b32_e32 v28, v0
	v_mov_b32_e32 v29, v0
	v_mov_b32_e32 v30, v0
	v_mov_b32_e32 v31, v0
	v_mov_b32_e32 v36, v0
	v_mov_b32_e32 v37, v0
	v_mov_b32_e32 v38, v0
	v_mov_b32_e32 v39, v0
	v_mov_b32_e32 v40, v0
	v_mov_b32_e32 v41, v0
	v_mov_b32_e32 v42, v0
	v_mov_b32_e32 v43, v0
	v_mov_b32_e32 v44, v0
	v_mov_b32_e32 v45, v0
	v_mov_b32_e32 v46, v0
	v_mov_b32_e32 v47, v0
	v_mov_b32_e32 v48, v0
	v_mov_b32_e32 v49, v0
	v_mov_b32_e32 v50, v0
	v_mov_b32_e32 v51, v0
	v_mov_b32_e32 v52, v0
	v_mov_b32_e32 v53, v0
	v_mov_b32_e32 v54, v0
	v_mov_b32_e32 v55, v0
	v_mov_b32_e32 v56, v0
	v_mov_b32_e32 v57, v0
	v_mov_b32_e32 v58, v0
	v_mov_b32_e32 v59, v0
	v_mov_b32_e32 v60, v0
	v_mov_b32_e32 v61, v0
	v_mov_b32_e32 v62, v0
	v_mov_b32_e32 v63, v0
	v_mov_b32_e32 v64, v0
	v_mov_b32_e32 v65, v0
	v_mov_b32_e32 v66, v0
	v_mov_b32_e32 v67, v0
	s_waitcnt lgkmcnt(0)
	s_barrier
	s_branch .LBB0_96

; #define SKJ(buf, i, R) { int c = t + 256 * (i), row = c / CPR, cc = c - row * CPR; *(uint4*)(Ks + (buf) * 64 * KP + swap23(row) * KP + cc * 8) = R; }
; template <int DQK, int DV, int NBUF, bool QREG, int QW, int LDQ, int LDK, int LDV, int LDO>
; DI void flash_item(const bf16_t* __restrict__ Qp, const bf16_t* __restrict__ Kp, const bf16_t* __restrict__ Vtp, int nkt,
;                    bf16_t* __restrict__ Op, char* smem, float& ssq) {
;     ...
;         if constexpr (NBUF == 1) {
;             __syncthreads();
;             LKJ(kt, 0, rk0) LKJ(kt, 1, rk1) LKJ(kt, 2, rk2) LKJ(kt, 3, rk3)
;             LKJ(kt, 4, rk4) LKJ(kt, 5, rk5) LKJ(kt, 6, rk6) LKJ(kt, 7, rk7)
;             SKJ(0, 0, rk0) SKJ(0, 1, rk1) SKJ(0, 2, rk2) SKJ(0, 3, rk3)
;             asm volatile("" ::: "memory");
;             LVJ(kt, 0, rk0) LVJ(kt, 1, rk1) LVJ(kt, 2, rk2) LVJ(kt, 3, rk3)
;             SKJ(0, 4, rk4) SKJ(0, 5, rk5) SKJ(0, 6, rk6) SKJ(0, 7, rk7)
;             asm volatile("" ::: "memory");
;             LVJ(kt, 4, rk4) LVJ(kt, 5, rk5) LVJ(kt, 6, rk6) LVJ(kt, 7, rk7)
;             SVJ(0, 0, rk0) SVJ(0, 1, rk1) SVJ(0, 2, rk2) SVJ(0, 3, rk3)
;             asm volatile("" ::: "memory");
;             SVJ(0, 4, rk4) SVJ(0, 5, rk5) SVJ(0, 6, rk6) SVJ(0, 7, rk7)
.LBB0_123:
	v_lshl_add_u64 v[48:49], v[178:179], 0, s[36:37]
	v_add_co_u32_e32 v36, vcc, 0x8180000, v48
	s_nop 1
	v_addc_co_u32_e32 v37, vcc, 0, v49, vcc
	v_add_co_u32_e32 v40, vcc, 0x8181000, v48
	s_nop 0
	v_addc_co_u32_e32 v41, vcc, 0, v49, vcc
	v_add_co_u32_e32 v44, vcc, 0x8182000, v48
	s_nop 1
	v_addc_co_u32_e32 v45, vcc, 0, v49, vcc
	v_add_co_u32_e32 v82, vcc, 0x8183000, v48
	global_load_dwordx4 v[36:39], v[36:37], off
	s_nop 0
	global_load_dwordx4 v[40:43], v[40:41], off
	v_addc_co_u32_e32 v83, vcc, 0, v49, vcc
	v_add_co_u32_e32 v86, vcc, 0x8184000, v48
	global_load_dwordx4 v[44:47], v[44:45], off
	s_nop 0
	global_load_dwordx4 v[82:85], v[82:83], off
	v_addc_co_u32_e32 v87, vcc, 0, v49, vcc
	v_add_co_u32_e32 v90, vcc, 0x8185000, v48
	v_xor_b32_e32 v34, 32, v184
	s_nop 0
	v_addc_co_u32_e32 v91, vcc, 0, v49, vcc
	s_waitcnt vmcnt(26)
	v_add_co_u32_e32 v94, vcc, 0x8186000, v48
	global_load_dwordx4 v[86:89], v[86:87], off
	s_nop 0
	global_load_dwordx4 v[90:93], v[90:91], off
	v_addc_co_u32_e32 v95, vcc, 0, v49, vcc
	v_add_co_u32_e32 v48, vcc, 0x8187000, v48
	s_nop 1
	v_addc_co_u32_e32 v49, vcc, 0, v49, vcc
	global_load_dwordx4 v[94:97], v[94:95], off
	s_nop 0
	global_load_dwordx4 v[98:101], v[48:49], off
	v_lshl_add_u64 v[48:49], v[180:181], 0, s[36:37]
	s_waitcnt vmcnt(25)
	v_add_co_u32_e32 v102, vcc, 0x9180000, v48
	s_barrier
	s_waitcnt vmcnt(7)
	ds_write_b128 v198, v[36:39]
	s_waitcnt vmcnt(6)
	ds_write_b128 v199, v[40:43]
	s_waitcnt vmcnt(5)
	ds_write_b128 v200, v[44:47]
	s_waitcnt vmcnt(4)
	ds_write_b128 v201, v[82:85]
	v_addc_co_u32_e32 v103, vcc, 0, v49, vcc
	v_add_co_u32_e32 v104, vcc, 0x9184000, v48
	s_waitcnt vmcnt(3)
	ds_write_b128 v202, v[86:89]
	v_addc_co_u32_e32 v105, vcc, 0, v49, vcc
	v_add_co_u32_e32 v106, vcc, 0x9188000, v48
	s_nop 1
	v_addc_co_u32_e32 v107, vcc, 0, v49, vcc
	v_add_co_u32_e32 v108, vcc, 0x918c000, v48
	s_nop 1
	v_addc_co_u32_e32 v109, vcc, 0, v49, vcc
	v_add_co_u32_e32 v110, vcc, 0x9190000, v48
	global_load_dwordx4 v[36:39], v[102:103], off
	global_load_dwordx4 v[40:43], v[104:105], off
	global_load_dwordx4 v[44:47], v[106:107], off
	global_load_dwordx4 v[82:85], v[108:109], off
	v_addc_co_u32_e32 v111, vcc, 0, v49, vcc
	s_waitcnt vmcnt(6)
	ds_write_b128 v203, v[90:93]
	s_waitcnt vmcnt(5)
	ds_write_b128 v204, v[94:97]
	s_waitcnt vmcnt(4)
	ds_write_b128 v205, v[98:101]
	v_add_co_u32_e32 v90, vcc, 0x9194000, v48
	s_nop 1
	v_addc_co_u32_e32 v91, vcc, 0, v49, vcc
	v_add_co_u32_e32 v94, vcc, 0x9198000, v48
	global_load_dwordx4 v[86:89], v[110:111], off
	s_nop 0
	global_load_dwordx4 v[90:93], v[90:91], off
	v_addc_co_u32_e32 v95, vcc, 0, v49, vcc
	v_add_co_u32_e32 v48, vcc, 0x919c000, v48
	s_nop 1
	v_addc_co_u32_e32 v49, vcc, 0, v49, vcc
	global_load_dwordx4 v[94:97], v[94:95], off
	s_nop 0
	global_load_dwordx4 v[98:101], v[48:49], off
	v_cmp_lt_i32_e32 vcc, v34, v187
	s_waitcnt vmcnt(7)
	ds_write_b128 v206, v[36:39] offset:33792
	s_waitcnt vmcnt(6)
	ds_write_b128 v207, v[40:43] offset:33792
	s_waitcnt vmcnt(5)
	ds_write_b128 v208, v[44:47] offset:33792
	s_waitcnt vmcnt(4)
	ds_write_b128 v209, v[82:85] offset:33792
	s_waitcnt vmcnt(3)
	ds_write_b128 v210, v[86:89] offset:33792
	s_waitcnt vmcnt(2)
	ds_write_b128 v211, v[90:93] offset:33792
	s_waitcnt vmcnt(1)
	ds_write_b128 v212, v[94:97] offset:33792
	s_waitcnt vmcnt(0)
	ds_write_b128 v213, v[98:101] offset:33792
	s_waitcnt lgkmcnt(0)
	s_barrier
; #define MFMA(a, b, c) __builtin_amdgcn_mfma_f32_32x32x16_bf16((a), (b), (c), 0, 0, 0)
; DI float ex2(float x) { return __builtin_amdgcn_exp2f(x); }
; template <int DQK, int DV, int NBUF, bool QREG, int QW, int LDQ, int LDK, int LDV, int LDO>
; DI void flash_item(const bf16_t* __restrict__ Qp, const bf16_t* __restrict__ Kp, const bf16_t* __restrict__ Vtp, int nkt,
;                    bf16_t* __restrict__ Op, char* smem, float& ssq) {
;     ...
;         const bf16_t* kb = Ks + buf * 64 * KP + l32 * KP + 8 * h;
;         f32x16 s0, s1;
; #pragma unroll
;         for (int r = 0; r < 16; ++r) { s0[r] = 0.f; s1[r] = 0.f; }
; #pragma unroll
;         for (int ks = 0; ks < NKS; ++ks) {
;             bf16x8 qq;
;             if constexpr (QREG) qq = qf[ks]; else qq = *(const bf16x8*)(Qp + (size_t)q * LDQ + ks * 16 + 8 * h);
;             bf16x8 k0 = *(const bf16x8*)(kb + ks * 16);
;             bf16x8 k1 = *(const bf16x8*)(kb + 32 * KP + ks * 16);
;             s0 = MFMA(k0, qq, s0);
;             s1 = MFMA(k1, qq, s1);
;         }
;         float mx = s0[0];
; #pragma unroll
;         for (int r = 1; r < 16; ++r) mx = fmaxf(mx, s0[r]);
; #pragma unroll
;         for (int r = 0; r < 16; ++r) mx = fmaxf(mx, s1[r]);
;         mx = fmaxf(mx, __shfl_xor(mx, 32));
;         const float mn = fmaxf(m, mx);
;         const float alpha = ex2(m - mn);
;         m = mn;
;         float psum = 0.f;
; #pragma unroll
;         for (int r = 0; r < 16; ++r) { s0[r] = ex2(s0[r] - mn); psum += s0[r]; }
; #pragma unroll
;         for (int r = 0; r < 16; ++r) { s1[r] = ex2(s1[r] - mn); psum += s1[r]; }
;         lsum = lsum * alpha + psum;
;         if (__builtin_amdgcn_ballot_w64(alpha != 1.f) != 0ull) {
; #pragma unroll
;             for (int mt = 0; mt < NMT; ++mt)
; #pragma unroll
;                 for (int r = 0; r < 16; ++r) o[mt][r] *= alpha;
;         }
	ds_read_b128 v[36:39], v214
	ds_read_b128 v[40:43], v214 offset:32
	s_waitcnt lgkmcnt(1)
	v_mfma_f32_32x32x16_bf16 v[82:97], v[36:39], v[170:173], 0
	ds_read_b128 v[36:39], v214 offset:16896
	ds_read_b128 v[44:47], v214 offset:16928
	v_cndmask_b32_e32 v34, v184, v34, vcc
	s_waitcnt lgkmcnt(2)
	v_mfma_f32_32x32x16_bf16 v[82:97], v[40:43], v[114:117], v[82:97]
	s_waitcnt lgkmcnt(1)
	v_mfma_f32_32x32x16_bf16 v[98:113], v[36:39], v[170:173], 0
	ds_read_b128 v[36:39], v214 offset:64
	ds_read_b128 v[40:43], v214 offset:96
	s_waitcnt lgkmcnt(1)
	v_mfma_f32_32x32x16_bf16 v[82:97], v[36:39], v[118:121], v[82:97]
	v_mfma_f32_32x32x16_bf16 v[98:113], v[44:47], v[114:117], v[98:113]
	ds_read_b128 v[36:39], v214 offset:16960
	ds_read_b128 v[44:47], v214 offset:16992
	s_waitcnt lgkmcnt(2)
	v_mfma_f32_32x32x16_bf16 v[82:97], v[40:43], v[122:125], v[82:97]
	s_waitcnt lgkmcnt(1)
	v_mfma_f32_32x32x16_bf16 v[98:113], v[36:39], v[118:121], v[98:113]
	ds_read_b128 v[36:39], v214 offset:128
	ds_read_b128 v[40:43], v214 offset:160
	s_waitcnt lgkmcnt(1)
	v_mfma_f32_32x32x16_bf16 v[82:97], v[36:39], v[126:129], v[82:97]
	v_mfma_f32_32x32x16_bf16 v[98:113], v[44:47], v[122:125], v[98:113]
	ds_read_b128 v[36:39], v214 offset:17024
	ds_read_b128 v[44:47], v214 offset:17056
	s_waitcnt lgkmcnt(2)
	v_mfma_f32_32x32x16_bf16 v[82:97], v[40:43], v[130:133], v[82:97]
	s_waitcnt lgkmcnt(1)
	v_mfma_f32_32x32x16_bf16 v[98:113], v[36:39], v[126:129], v[98:113]
	ds_read_b128 v[36:39], v214 offset:192
	ds_read_b128 v[40:43], v214 offset:224
	s_waitcnt lgkmcnt(1)
	v_mfma_f32_32x32x16_bf16 v[82:97], v[36:39], v[134:137], v[82:97]
	v_mfma_f32_32x32x16_bf16 v[98:113], v[44:47], v[130:133], v[98:113]
	ds_read_b128 v[36:39], v214 offset:17088
	ds_read_b128 v[44:47], v214 offset:17120
	s_waitcnt lgkmcnt(2)
	v_mfma_f32_32x32x16_bf16 v[82:97], v[40:43], v[138:141], v[82:97]
	s_waitcnt lgkmcnt(1)
	v_mfma_f32_32x32x16_bf16 v[98:113], v[36:39], v[134:137], v[98:113]
	ds_read_b128 v[36:39], v214 offset:256
	ds_read_b128 v[40:43], v214 offset:288
	s_waitcnt lgkmcnt(1)
	v_mfma_f32_32x32x16_bf16 v[82:97], v[36:39], v[142:145], v[82:97]
	v_mfma_f32_32x32x16_bf16 v[98:113], v[44:47], v[138:141], v[98:113]
	ds_read_b128 v[36:39], v214 offset:17152
	ds_read_b128 v[44:47], v214 offset:17184
	s_waitcnt lgkmcnt(2)
	v_mfma_f32_32x32x16_bf16 v[82:97], v[40:43], v[146:149], v[82:97]
	s_waitcnt lgkmcnt(1)
	v_mfma_f32_32x32x16_bf16 v[98:113], v[36:39], v[142:145], v[98:113]
	ds_read_b128 v[36:39], v214 offset:320
	ds_read_b128 v[40:43], v214 offset:352
	s_waitcnt lgkmcnt(1)
	v_mfma_f32_32x32x16_bf16 v[82:97], v[36:39], v[150:153], v[82:97]
	v_mfma_f32_32x32x16_bf16 v[98:113], v[44:47], v[146:149], v[98:113]
	ds_read_b128 v[36:39], v214 offset:17216
	ds_read_b128 v[44:47], v214 offset:17248
	s_waitcnt lgkmcnt(2)
	v_mfma_f32_32x32x16_bf16 v[82:97], v[40:43], v[154:157], v[82:97]
	s_waitcnt lgkmcnt(1)
	v_mfma_f32_32x32x16_bf16 v[98:113], v[36:39], v[150:153], v[98:113]
	ds_read_b128 v[36:39], v214 offset:384
	ds_read_b128 v[40:43], v214 offset:416
	s_waitcnt lgkmcnt(1)
	v_mfma_f32_32x32x16_bf16 v[82:97], v[36:39], v[158:161], v[82:97]
	v_mfma_f32_32x32x16_bf16 v[98:113], v[44:47], v[154:157], v[98:113]
	ds_read_b128 v[36:39], v214 offset:17280
	ds_read_b128 v[44:47], v214 offset:17312
	s_waitcnt lgkmcnt(2)
	v_mfma_f32_32x32x16_bf16 v[82:97], v[40:43], v[162:165], v[82:97]
	s_waitcnt lgkmcnt(1)
	v_mfma_f32_32x32x16_bf16 v[98:113], v[36:39], v[158:161], v[98:113]
	ds_read_b128 v[36:39], v214 offset:448
	ds_read_b128 v[40:43], v214 offset:480
	s_waitcnt lgkmcnt(1)
	v_mfma_f32_32x32x16_bf16 v[82:97], v[36:39], v[166:169], v[82:97]
	v_mfma_f32_32x32x16_bf16 v[98:113], v[44:47], v[162:165], v[98:113]
	ds_read_b128 v[36:39], v214 offset:17344
	ds_read_b128 v[44:47], v214 offset:17376
	s_waitcnt lgkmcnt(2)
	v_mfma_f32_32x32x16_bf16 v[82:97], v[40:43], v[174:177], v[82:97]
	v_lshlrev_b32_e32 v40, 2, v34
	s_waitcnt lgkmcnt(1)
	v_mfma_f32_32x32x16_bf16 v[98:113], v[36:39], v[166:169], v[98:113]
	s_nop 8
	v_max_f32_e32 v36, v83, v83
	v_max_f32_e32 v37, v82, v82
	v_max_f32_e32 v36, v37, v36
	v_max3_f32 v36, v36, v84, v85
	v_max3_f32 v36, v36, v86, v87
	v_max3_f32 v36, v36, v88, v89
	v_max3_f32 v36, v36, v90, v91
	s_waitcnt lgkmcnt(0)
	v_mfma_f32_32x32x16_bf16 v[98:113], v[44:47], v[174:177], v[98:113]
	v_max3_f32 v36, v36, v92, v93
	v_max3_f32 v36, v36, v94, v95
	v_max3_f32 v36, v36, v96, v97
	v_mov_b32_e32 v37, v216
	s_nop 7
	v_max3_f32 v36, v36, v98, v99
	v_max3_f32 v36, v36, v100, v101
	v_max3_f32 v36, v36, v102, v103
	v_max3_f32 v36, v36, v104, v105
	v_max3_f32 v36, v36, v106, v107
	v_max3_f32 v36, v36, v108, v109
	v_max3_f32 v36, v36, v110, v111
	v_max3_f32 v36, v36, v112, v113
	ds_bpermute_b32 v34, v40, v36
	s_waitcnt lgkmcnt(0)
	v_max3_f32 v216, v37, v36, v34
	v_sub_f32_e32 v34, v37, v216
	v_exp_f32_e32 v34, v34
	s_nop 0
	v_cmp_neq_f32_e32 vcc, 1.0, v34
	s_cbranch_vccz .LBB0_125
	v_pk_mul_f32 v[80:81], v[80:81], v[34:35] op_sel_hi:[1,0]
	v_pk_mul_f32 v[78:79], v[78:79], v[34:35] op_sel_hi:[1,0]
	v_pk_mul_f32 v[76:77], v[76:77], v[34:35] op_sel_hi:[1,0]
	v_pk_mul_f32 v[74:75], v[74:75], v[34:35] op_sel_hi:[1,0]
	v_pk_mul_f32 v[72:73], v[72:73], v[34:35] op_sel_hi:[1,0]
	v_pk_mul_f32 v[70:71], v[70:71], v[34:35] op_sel_hi:[1,0]
	v_pk_mul_f32 v[68:69], v[68:69], v[34:35] op_sel_hi:[1,0]
	v_pk_mul_f32 v[66:67], v[66:67], v[34:35] op_sel_hi:[1,0]
	v_pk_mul_f32 v[64:65], v[64:65], v[34:35] op_sel_hi:[1,0]
	v_pk_mul_f32 v[62:63], v[62:63], v[34:35] op_sel_hi:[1,0]
	v_pk_mul_f32 v[60:61], v[60:61], v[34:35] op_sel_hi:[1,0]
	v_pk_mul_f32 v[58:59], v[58:59], v[34:35] op_sel_hi:[1,0]
	v_pk_mul_f32 v[56:57], v[56:57], v[34:35] op_sel_hi:[1,0]
	v_pk_mul_f32 v[54:55], v[54:55], v[34:35] op_sel_hi:[1,0]
	v_pk_mul_f32 v[52:53], v[52:53], v[34:35] op_sel_hi:[1,0]
	v_pk_mul_f32 v[50:51], v[50:51], v[34:35] op_sel_hi:[1,0]
	v_pk_mul_f32 v[30:31], v[30:31], v[34:35] op_sel_hi:[1,0]
	v_pk_mul_f32 v[28:29], v[28:29], v[34:35] op_sel_hi:[1,0]
	v_pk_mul_f32 v[26:27], v[26:27], v[34:35] op_sel_hi:[1,0]
	v_pk_mul_f32 v[24:25], v[24:25], v[34:35] op_sel_hi:[1,0]
	v_pk_mul_f32 v[22:23], v[22:23], v[34:35] op_sel_hi:[1,0]
	v_pk_mul_f32 v[20:21], v[20:21], v[34:35] op_sel_hi:[1,0]
	v_pk_mul_f32 v[18:19], v[18:19], v[34:35] op_sel_hi:[1,0]
	v_pk_mul_f32 v[16:17], v[16:17], v[34:35] op_sel_hi:[1,0]
	v_pk_mul_f32 v[14:15], v[14:15], v[34:35] op_sel_hi:[1,0]
	v_pk_mul_f32 v[12:13], v[12:13], v[34:35] op_sel_hi:[1,0]
	v_pk_mul_f32 v[10:11], v[10:11], v[34:35] op_sel_hi:[1,0]
	v_pk_mul_f32 v[8:9], v[8:9], v[34:35] op_sel_hi:[1,0]
	v_pk_mul_f32 v[6:7], v[6:7], v[34:35] op_sel_hi:[1,0]
	v_pk_mul_f32 v[4:5], v[4:5], v[34:35] op_sel_hi:[1,0]
	v_pk_mul_f32 v[2:3], v[2:3], v[34:35] op_sel_hi:[1,0]
	v_pk_mul_f32 v[0:1], v[0:1], v[34:35] op_sel_hi:[1,0]

; #define LOADS(S, k0) { LD1(S, 0, k0) LD1(S, 1, k0) LD1(S, 2, k0) LD1(S, 3, k0) }
; #define STORES(S, buf) { ST1(S, 0, buf) ST1(S, 1, buf) ST1(S, 2, buf) ST1(S, 3, buf) }
; template <int AMODE, bool F16 = false, bool MASK = false>
; DI void gemm_tile(const bf16_t* __restrict__ Ab, int lda, int row0, int rlo, int rhi,
;                   const bf16_t* __restrict__ Bt, int ldb, int K, char* smem, f32x16 (&acc)[2][2]) {
;     ...
;     const int gr0 = row0 + (t >> 3);
;     const bool rv0 = gr0 >= rlo && gr0 < rhi, rv1 = gr0 + 32 >= rlo && gr0 + 32 < rhi, rv2 = gr0 + 64 >= rlo && gr0 + 64 < rhi, rv3 = gr0 + 96 >= rlo && gr0 + 96 < rhi;
;     const int nk = K >> 6;
;     const int rhm = rhi - 1;
;     const unsigned aoff0 = (unsigned)min(max(gr0, rlo), rhm) * (unsigned)lda + 8u * (t & 7);
;     const unsigned aoff1 = (unsigned)min(max(gr0 + 32, rlo), rhm) * (unsigned)lda + 8u * (t & 7);
;     const unsigned aoff2 = (unsigned)min(max(gr0 + 64, rlo), rhm) * (unsigned)lda + 8u * (t & 7);
;     const unsigned aoff3 = (unsigned)min(max(gr0 + 96, rlo), rhm) * (unsigned)lda + 8u * (t & 7);
;     const unsigned btoff = (unsigned)((t >> 3) * ldb + 8 * (t & 7));
;     __syncthreads();
;     ...
;     const int klast = (nk - 1) * 64;
;     LOADS(p0, 0);
;     LOADS(p1, 64);
;     STORES(p0, 0);
;     LOADS(p0, min(128, klast));
;     __syncthreads();
; DI void ph_qm(KP p, int l, char* smem) {
;     ...
;         gemm_tile<0, true>((const bf16_t*)(p->ws + OFF_XB), DM, rt * 128, 0, TOK, (const bf16_t*)(p->ws + OFF_WMQ) + ((size_t)l * DM + ct * 128) * DM, DM, DM, smem, acc);
.LBB0_141:
	s_or_b64 exec, exec, s[16:17]
	s_add_u32 s18, s14, 0x2d180000
	s_addc_u32 s19, s15, 0
	s_lshl_b32 s7, s7, 4
	s_sub_i32 s7, s7, s8
	s_and_b32 s16, s7, 0xffffff80
	s_ashr_i32 s17, s16, 31
	s_add_u32 s7, s14, s68
	v_mov_b32_e32 v37, v182
	s_addc_u32 s10, s15, s69
	s_lshl_b64 s[8:9], s[16:17], 11
	s_add_u32 s8, s7, s8
	v_lshlrev_b32_e32 v2, 3, v37
	s_waitcnt vmcnt(7)
	v_ashrrev_i32_e32 v32, 3, v37
	v_and_b32_e32 v2, 56, v2
	s_addc_u32 s9, s10, s9
	v_lshl_or_b32 v4, v32, 10, v2
	v_mov_b32_e32 v5, v35
	v_lshl_add_u64 v[38:39], v[4:5], 1, s[8:9]
	s_mov_b32 s7, 0x1780000
	v_add_u32_e32 v0, s6, v32
	v_add_co_u32_e32 v4, vcc, s7, v38
	v_max_i32_e32 v3, 0xffffffe0, v0
	s_nop 0
	v_addc_co_u32_e32 v5, vcc, 0, v39, vcc
	s_mov_b32 s7, 0x1790000
	v_add_u32_e32 v3, 32, v3
	v_add_co_u32_e32 v42, vcc, s7, v38
	v_med3_i32 v1, v0, 0, v192
	v_min_u32_e32 v8, 0xffff, v3
	v_max_i32_e32 v3, 0xffffffc0, v0
	v_max_i32_e32 v0, 0xffffffa0, v0
	v_addc_co_u32_e32 v43, vcc, 0, v39, vcc
	s_mov_b32 s7, 0x17a0000
	v_add_u32_e32 v3, 64, v3
	v_add_u32_e32 v0, 0x60, v0
	v_lshlrev_b32_e32 v33, 1, v2
	v_add_co_u32_e32 v46, vcc, s7, v38
	v_min_u32_e32 v16, 0xffff, v3
	v_min_u32_e32 v24, 0xffff, v0
	v_lshl_or_b32 v34, v1, 11, v33
	v_addc_co_u32_e32 v47, vcc, 0, v39, vcc
	s_mov_b32 s7, 0x17b0000
	global_load_dwordx4 v[0:3], v34, s[18:19]
	v_lshl_or_b32 v40, v8, 11, v33
	v_lshl_or_b32 v44, v16, 11, v33
	v_lshl_or_b32 v48, v24, 11, v33
	v_add_co_u32_e32 v50, vcc, s7, v38
	global_load_dwordx4 v[8:11], v40, s[18:19]
	global_load_dwordx4 v[16:19], v44, s[18:19]
	global_load_dwordx4 v[24:27], v48, s[18:19]
	global_load_dwordx4 v[20:23], v[46:47], off
	v_addc_co_u32_e32 v51, vcc, 0, v39, vcc
	global_load_dwordx4 v[4:7], v[4:5], off
	s_mov_b64 s[10:11], 0x1780000
	global_load_dwordx4 v[28:31], v[50:51], off
	global_load_dwordx4 v[12:15], v[42:43], off
	s_waitcnt vmcnt(11)
	v_lshl_add_u64 v[138:139], v[38:39], 0, s[10:11]
	s_mov_b64 s[10:11], 0x1790000
	s_add_u32 s8, s14, 0x2d180080
	s_waitcnt vmcnt(10)
	v_lshl_add_u64 v[140:141], v[38:39], 0, s[10:11]
	s_mov_b64 s[10:11], 0x17a0000
	s_waitcnt vmcnt(9)
	v_lshl_add_u64 v[142:143], v[38:39], 0, s[10:11]
	s_mov_b64 s[10:11], 0x17b0000
	s_addc_u32 s9, s15, 0
	v_mul_lo_u32 v32, v32, s81
	s_waitcnt vmcnt(8)
	v_lshl_add_u64 v[144:145], v[38:39], 0, s[10:11]
	s_add_u32 s10, s14, 0x2d180100
	v_add3_u32 v147, 0, v32, v33
	s_addc_u32 s11, s15, 0
	global_load_dwordx4 v[68:71], v34, s[8:9]
	global_load_dwordx4 v[72:75], v[42:43], off offset:128
	global_load_dwordx4 v[76:79], v44, s[8:9]
	global_load_dwordx4 v[80:83], v[50:51], off offset:128
	global_load_dwordx4 v[84:87], v34, s[10:11]
	global_load_dwordx4 v[88:91], v44, s[10:11]
	v_readfirstlane_b32 s12, v37
	v_and_b32_e32 v52, 31, v37
	v_lshl_add_u64 v[32:33], s[18:19], 0, v[34:35]
	v_mov_b32_e32 v41, v35
	v_mov_b32_e32 v45, v35
	v_mov_b32_e32 v49, v35
	s_mov_b32 s7, 0
	v_lshl_add_u64 v[132:133], s[18:19], 0, v[40:41]
	v_lshl_add_u64 v[134:135], s[18:19], 0, v[44:45]
	s_barrier
	s_waitcnt vmcnt(13)
	ds_write_b128 v147, v[0:3]
	s_waitcnt vmcnt(12)
	ds_write_b128 v147, v[8:11] offset:4608
	s_waitcnt vmcnt(8)
	ds_write_b128 v147, v[4:7] offset:36864
	s_waitcnt vmcnt(6)
	ds_write_b128 v147, v[12:15] offset:41472
	ds_write_b128 v147, v[16:19] offset:9216
	global_load_dwordx4 v[92:95], v[42:43], off offset:256
	global_load_dwordx4 v[112:115], v[50:51], off offset:256
	ds_write_b128 v147, v[20:23] offset:46080
	ds_write_b128 v147, v[24:27] offset:13824
	ds_write_b128 v147, v[28:31] offset:50688
	global_load_dwordx4 v[96:99], v[138:139], off offset:128
	global_load_dwordx4 v[100:103], v[138:139], off offset:256
	global_load_dwordx4 v[104:107], v40, s[8:9]
	global_load_dwordx4 v[108:111], v40, s[10:11]
	global_load_dwordx4 v[116:119], v[46:47], off offset:128
	global_load_dwordx4 v[120:123], v[46:47], off offset:256
	global_load_dwordx4 v[124:127], v48, s[8:9]
	global_load_dwordx4 v[128:131], v48, s[10:11]
	s_lshr_b32 s8, s12, 1
	s_and_b32 s8, s8, 0xfffffc0
	v_or_b32_e32 v0, s8, v52
	v_lshrrev_b32_e32 v1, 1, v37
	v_mul_lo_u32 v0, v0, s81
	v_and_b32_e32 v1, 16, v1
	v_add3_u32 v34, 0, v0, v1
	v_and_or_b32 v0, s12, 64, v52
	v_mul_u32_u24_e32 v0, 0x48, v0
	v_lshlrev_b32_e32 v0, 1, v0
	v_lshl_add_u64 v[136:137], s[18:19], 0, v[48:49]
	v_add3_u32 v148, 0, v0, v1
	v_add_u32_e32 v149, 0xd800, v147
	s_mov_b32 s8, 0
	v_mov_b32_e32 v37, v36
	v_mov_b32_e32 v38, v36
	v_mov_b32_e32 v39, v36
	v_mov_b32_e32 v40, v36
	v_mov_b32_e32 v41, v36
	v_mov_b32_e32 v42, v36
	v_mov_b32_e32 v43, v36
	v_mov_b32_e32 v44, v36
	v_mov_b32_e32 v45, v36
	v_mov_b32_e32 v46, v36
	v_mov_b32_e32 v47, v36
	v_mov_b32_e32 v48, v36
	v_mov_b32_e32 v49, v36
	v_mov_b32_e32 v50, v36
	v_mov_b32_e32 v51, v36
	v_mov_b32_e32 v52, v36
	v_mov_b32_e32 v53, v36
	v_mov_b32_e32 v54, v36
	v_mov_b32_e32 v55, v36
	v_mov_b32_e32 v56, v36
	v_mov_b32_e32 v57, v36
	v_mov_b32_e32 v58, v36
	v_mov_b32_e32 v59, v36
	v_mov_b32_e32 v60, v36
	v_mov_b32_e32 v61, v36
	v_mov_b32_e32 v62, v36
	v_mov_b32_e32 v63, v36
	v_mov_b32_e32 v64, v36
	v_mov_b32_e32 v65, v36
	v_mov_b32_e32 v66, v36
	v_mov_b32_e32 v67, v36
	v_mov_b32_e32 v16, v36
	v_mov_b32_e32 v17, v36
	v_mov_b32_e32 v18, v36
	v_mov_b32_e32 v19, v36
	v_mov_b32_e32 v20, v36
	v_mov_b32_e32 v21, v36
	v_mov_b32_e32 v22, v36
	v_mov_b32_e32 v23, v36
	v_mov_b32_e32 v24, v36
	v_mov_b32_e32 v25, v36
	v_mov_b32_e32 v26, v36
	v_mov_b32_e32 v27, v36
	v_mov_b32_e32 v28, v36
	v_mov_b32_e32 v29, v36
	v_mov_b32_e32 v30, v36
	v_mov_b32_e32 v31, v36
	v_mov_b32_e32 v0, v36
	v_mov_b32_e32 v1, v36
	v_mov_b32_e32 v2, v36
	v_mov_b32_e32 v3, v36
	v_mov_b32_e32 v4, v36
	v_mov_b32_e32 v5, v36
	v_mov_b32_e32 v6, v36
	v_mov_b32_e32 v7, v36
	v_mov_b32_e32 v8, v36
	v_mov_b32_e32 v9, v36
	v_mov_b32_e32 v10, v36
	v_mov_b32_e32 v11, v36
	v_mov_b32_e32 v12, v36
	v_mov_b32_e32 v13, v36
	v_mov_b32_e32 v14, v36
	v_mov_b32_e32 v15, v36
	s_waitcnt lgkmcnt(0)
	s_barrier
	s_branch .LBB0_143

; #define LOADS(S, k0) { LD1(S, 0, k0) LD1(S, 1, k0) LD1(S, 2, k0) LD1(S, 3, k0) }
; #define STORES(S, buf) { ST1(S, 0, buf) ST1(S, 1, buf) ST1(S, 2, buf) ST1(S, 3, buf) }
; template <int AMODE, bool F16 = false, bool MASK = false>
; DI void gemm_tile(const bf16_t* __restrict__ Ab, int lda, int row0, int rlo, int rhi,
;                   const bf16_t* __restrict__ Bt, int ldb, int K, char* smem, f32x16 (&acc)[2][2]) {
;     ...
;     const int gr0 = row0 + (t >> 3);
;     const bool rv0 = gr0 >= rlo && gr0 < rhi, rv1 = gr0 + 32 >= rlo && gr0 + 32 < rhi, rv2 = gr0 + 64 >= rlo && gr0 + 64 < rhi, rv3 = gr0 + 96 >= rlo && gr0 + 96 < rhi;
;     const int nk = K >> 6;
;     const int rhm = rhi - 1;
;     const unsigned aoff0 = (unsigned)min(max(gr0, rlo), rhm) * (unsigned)lda + 8u * (t & 7);
;     const unsigned aoff1 = (unsigned)min(max(gr0 + 32, rlo), rhm) * (unsigned)lda + 8u * (t & 7);
;     const unsigned aoff2 = (unsigned)min(max(gr0 + 64, rlo), rhm) * (unsigned)lda + 8u * (t & 7);
;     const unsigned aoff3 = (unsigned)min(max(gr0 + 96, rlo), rhm) * (unsigned)lda + 8u * (t & 7);
;     const unsigned btoff = (unsigned)((t >> 3) * ldb + 8 * (t & 7));
;     __syncthreads();
;     ...
;     const int klast = (nk - 1) * 64;
;     LOADS(p0, 0);
;     LOADS(p1, 64);
;     STORES(p0, 0);
;     LOADS(p0, min(128, klast));
;     __syncthreads();
; DI void ph_res(KP p, const bf16_t* A, int K, const bf16_t* Wt, const float* xin, char* smem, bool dry) {
;     ...
;         gemm_tile<0>(A, K, rt * 128, 0, TOK, Wt + (size_t)ct * 128 * K, K, K, smem, acc);
.LBB0_149:
	s_add_i32 s12, s11, s33
	s_cmpk_gt_i32 s12, 0xfff
	s_cbranch_scc1 .LBB0_148
	s_ashr_i32 s13, s12, 31
	s_lshr_b32 s13, s13, 26
	s_add_i32 s13, s12, s13
	s_and_b32 s34, s13, 0xffffffc0
	s_sub_i32 s12, s12, s34
	s_ashr_i32 s36, s12, 3
	s_lshl_b32 s12, s13, 4
	s_lshl_b32 s13, s11, 7
	s_and_b32 s12, s12, 0xfffffc00
	s_and_b32 s13, s13, 0x380
	v_mov_b32_e32 v48, v182
	s_or_b32 s42, s12, s13
	s_ashr_i32 s37, s36, 31
	v_ashrrev_i32_e32 v49, 3, v48
	v_add_u32_e32 v0, s42, v49
	v_lshlrev_b32_e32 v2, 3, v48
	v_max_i32_e32 v3, 0xffffffe0, v0
	s_lshl_b64 s[12:13], s[36:37], 18
	v_and_b32_e32 v2, 56, v2
	v_add_u32_e32 v3, 32, v3
	s_add_u32 s12, s2, s12
	s_waitcnt lgkmcnt(0)
	v_med3_i32 v1, v0, 0, v192
	v_min_u32_e32 v8, 0xffff, v3
	v_max_i32_e32 v3, 0xffffffc0, v0
	v_max_i32_e32 v0, 0xffffffa0, v0
	v_lshlrev_b32_e32 v50, 1, v2
	s_addc_u32 s13, s6, s13
	v_add_u32_e32 v3, 64, v3
	v_add_u32_e32 v0, 0x60, v0
	v_lshl_or_b32 v4, v49, 10, v2
	v_lshl_or_b32 v34, v1, 11, v50
	v_mov_b32_e32 v5, v35
	v_min_u32_e32 v16, 0xffff, v3
	v_min_u32_e32 v24, 0xffff, v0
	global_load_dwordx4 v[0:3], v34, s[14:15]
	s_waitcnt vmcnt(8)
	v_lshl_add_u64 v[32:33], v[4:5], 1, s[12:13]
	s_mov_b32 s12, 0x10000
	global_load_dwordx4 v[4:7], v[32:33], off
	v_lshl_or_b32 v36, v8, 11, v50
	v_add_co_u32_e32 v38, vcc, s12, v32
	global_load_dwordx4 v[8:11], v36, s[14:15]
	s_nop 0
	v_addc_co_u32_e32 v39, vcc, 0, v33, vcc
	v_lshl_or_b32 v40, v16, 11, v50
	s_mov_b32 s12, 0x20000
	global_load_dwordx4 v[16:19], v40, s[14:15]
	v_add_co_u32_e32 v42, vcc, s12, v32
	v_lshl_or_b32 v44, v24, 11, v50
	s_nop 0
	v_addc_co_u32_e32 v43, vcc, 0, v33, vcc
	global_load_dwordx4 v[24:27], v44, s[14:15]
	s_mov_b32 s12, 0x30000
	global_load_dwordx4 v[12:15], v[38:39], off
	v_add_co_u32_e32 v46, vcc, s12, v32
	global_load_dwordx4 v[20:23], v[42:43], off
	s_nop 0
	v_addc_co_u32_e32 v47, vcc, 0, v33, vcc
	global_load_dwordx4 v[28:31], v[46:47], off
	v_mul_lo_u32 v49, v49, s81
	v_add3_u32 v146, 0, v49, v50
	global_load_dwordx4 v[68:71], v[32:33], off offset:128
	global_load_dwordx4 v[76:79], v40, s[16:17]
	global_load_dwordx4 v[72:75], v[32:33], off offset:256
	global_load_dwordx4 v[84:87], v40, s[18:19]
	global_load_dwordx4 v[80:83], v[38:39], off offset:128
	global_load_dwordx4 v[92:95], v[46:47], off offset:128
	global_load_dwordx4 v[88:91], v[38:39], off offset:256
	global_load_dwordx4 v[96:99], v[46:47], off offset:256
	s_mov_b64 s[34:35], 0x10000
	s_waitcnt vmcnt(20)
	v_lshl_add_u64 v[136:137], v[32:33], 0, s[34:35]
	s_mov_b64 s[34:35], 0x20000
	v_readfirstlane_b32 s13, v48
	s_waitcnt vmcnt(18)
	v_lshl_add_u64 v[140:141], v[32:33], 0, s[34:35]
	s_mov_b64 s[34:35], 0x30000
	s_waitcnt vmcnt(16)
	v_lshl_add_u64 v[144:145], v[32:33], 0, s[34:35]
	s_lshr_b32 s34, s13, 1
	s_and_b32 s34, s34, 0xfffffc0
	v_mov_b32_e32 v37, v35
	v_mov_b32_e32 v41, v35
	v_mov_b32_e32 v45, v35
	s_mov_b32 s12, 0
	v_lshl_add_u64 v[132:133], s[14:15], 0, v[34:35]
	v_lshl_add_u64 v[134:135], s[14:15], 0, v[36:37]
	v_lshl_add_u64 v[138:139], s[14:15], 0, v[40:41]
	v_lshl_add_u64 v[142:143], s[14:15], 0, v[44:45]
	v_add_u32_e32 v148, 0xd800, v146
	s_barrier
	s_waitcnt vmcnt(15)
	ds_write_b128 v146, v[0:3]
	s_waitcnt vmcnt(14)
	ds_write_b128 v146, v[4:7] offset:36864
	s_waitcnt vmcnt(13)
	ds_write_b128 v146, v[8:11] offset:4608
	s_waitcnt vmcnt(12)
	ds_write_b128 v146, v[16:19] offset:9216
	s_waitcnt vmcnt(11)
	ds_write_b128 v146, v[24:27] offset:13824
	s_waitcnt vmcnt(10)
	ds_write_b128 v146, v[12:15] offset:41472
	s_waitcnt vmcnt(9)
	ds_write_b128 v146, v[20:23] offset:46080
	s_waitcnt vmcnt(8)
	ds_write_b128 v146, v[28:31] offset:50688
	global_load_dwordx4 v[100:103], v34, s[16:17]
	global_load_dwordx4 v[104:107], v34, s[18:19]
	global_load_dwordx4 v[108:111], v36, s[16:17]
	global_load_dwordx4 v[112:115], v36, s[18:19]
	global_load_dwordx4 v[116:119], v[42:43], off offset:128
	global_load_dwordx4 v[120:123], v[42:43], off offset:256
	global_load_dwordx4 v[124:127], v44, s[16:17]
	global_load_dwordx4 v[128:131], v44, s[18:19]
	v_and_b32_e32 v0, 31, v48
	v_or_b32_e32 v1, s34, v0
	v_and_or_b32 v0, s13, 64, v0
	v_lshrrev_b32_e32 v2, 1, v48
	v_mul_u32_u24_e32 v0, 0x48, v0
	v_and_b32_e32 v2, 16, v2
	v_lshlrev_b32_e32 v0, 1, v0
	v_mul_lo_u32 v1, v1, s81
	v_add3_u32 v147, 0, v0, v2
	v_mov_b32_e32 v0, 0
	v_add3_u32 v34, 0, v1, v2
	s_mov_b32 s13, 0
	v_mov_b32_e32 v1, v0
	v_mov_b32_e32 v2, v0
	v_mov_b32_e32 v3, v0
	v_mov_b32_e32 v4, v0
	v_mov_b32_e32 v5, v0
	v_mov_b32_e32 v6, v0
	v_mov_b32_e32 v7, v0
	v_mov_b32_e32 v8, v0
	v_mov_b32_e32 v9, v0
	v_mov_b32_e32 v10, v0
	v_mov_b32_e32 v11, v0
	v_mov_b32_e32 v12, v0
	v_mov_b32_e32 v13, v0
	v_mov_b32_e32 v14, v0
	v_mov_b32_e32 v15, v0
	v_mov_b32_e32 v16, v0
	v_mov_b32_e32 v17, v0
	v_mov_b32_e32 v18, v0
	v_mov_b32_e32 v19, v0
	v_mov_b32_e32 v20, v0
	v_mov_b32_e32 v21, v0
	v_mov_b32_e32 v22, v0
	v_mov_b32_e32 v23, v0
	v_mov_b32_e32 v24, v0
	v_mov_b32_e32 v25, v0
	v_mov_b32_e32 v26, v0
	v_mov_b32_e32 v27, v0
	v_mov_b32_e32 v28, v0
	v_mov_b32_e32 v29, v0
	v_mov_b32_e32 v30, v0
	v_mov_b32_e32 v31, v0
	v_mov_b32_e32 v36, v0
	v_mov_b32_e32 v37, v0
	v_mov_b32_e32 v38, v0
	v_mov_b32_e32 v39, v0
	v_mov_b32_e32 v40, v0
	v_mov_b32_e32 v41, v0
	v_mov_b32_e32 v42, v0
	v_mov_b32_e32 v43, v0
	v_mov_b32_e32 v44, v0
	v_mov_b32_e32 v45, v0
	v_mov_b32_e32 v46, v0
	v_mov_b32_e32 v47, v0
	v_mov_b32_e32 v48, v0
	v_mov_b32_e32 v49, v0
	v_mov_b32_e32 v50, v0
	v_mov_b32_e32 v51, v0
	v_mov_b32_e32 v52, v0
	v_mov_b32_e32 v53, v0
	v_mov_b32_e32 v54, v0
	v_mov_b32_e32 v55, v0
	v_mov_b32_e32 v56, v0
	v_mov_b32_e32 v57, v0
	v_mov_b32_e32 v58, v0
	v_mov_b32_e32 v59, v0
	v_mov_b32_e32 v60, v0
	v_mov_b32_e32 v61, v0
	v_mov_b32_e32 v62, v0
	v_mov_b32_e32 v63, v0
	v_mov_b32_e32 v64, v0
	v_mov_b32_e32 v65, v0
	v_mov_b32_e32 v66, v0
	v_mov_b32_e32 v67, v0
	s_waitcnt lgkmcnt(0)
	s_barrier
	s_branch .LBB0_152

; DI int tid() { int t = threadIdx.x; asm volatile("" : "+v"(t)); return t; }
; #define M2_STORE(S, buf) { M2_SK(0, S##k0, buf) M2_SK(1, S##k1, buf) M2_SK(2, S##k2, buf) M2_SV(0, S##v0, buf) M2_SV(1, S##v1, buf) }
; DI void flash_mla2(const bf16_t* __restrict__ Qp, const bf16_t* __restrict__ Kp, const bf16_t* __restrict__ Vtp,
;                    bf16_t* __restrict__ Op, char* smem, float& ssq) {
;     ...
;     const int t = tid(), lane = t & 63, w = __builtin_amdgcn_readfirstlane(t >> 6), l32 = lane & 31, h = lane >> 5;
;     const int q = w * 32 + l32;
;     const unsigned ktoff = (unsigned)(t * 8);
;     const unsigned vtoff = (unsigned)((t >> 3) * LDV + (t & 7) * 8);
;     bf16x8 qf[NKS];
; #pragma unroll
;     for (int ks = 0; ks < NKS; ++ks) qf[ks] = *(const bf16x8*)(Qp + (size_t)q * LDQ + ks * 16 + 8 * h);
;     f32x16 o[NMT];
; #pragma unroll
;     for (int mt = 0; mt < NMT; ++mt)
; #pragma unroll
;         for (int r = 0; r < 16; ++r) o[mt][r] = 0.f;
;     float m = 0.f, lsum = 0.f;
;     uint4 ak0, ak1, ak2, av0, av1, bk0, bk1, bk2, bv0, bv1;
;     ...
;     float alpha = 1.f;
;     __syncthreads();
;     M2_LOAD(a, 0);
;     M2_LOAD(b, 1);
;     {
;         M2_STORE(a, 0);
;         __syncthreads();
.LBB0_182:
	s_add_i32 s18, s34, s13
	s_ashr_i32 s19, s18, 31
	s_lshl_b64 s[16:17], s[18:19], 13
	s_or_b32 s16, s16, s12
	s_mulk_i32 s17, 0xc0
	s_mul_hi_u32 s35, s16, 0xc0
	s_add_i32 s35, s35, s17
	s_mulk_i32 s16, 0xc0
	s_add_u32 s36, s6, s16
	s_addc_u32 s37, s7, s35
	s_mul_i32 s16, s18, 0x180000
	s_mul_hi_i32 s17, s18, 0x180000
	s_add_u32 s16, s8, s16
	s_addc_u32 s17, s9, s17
	s_lshl_b64 s[18:19], s[18:19], 20
	v_mov_b32_e32 v1, v182
	s_add_u32 s18, s10, s18
	s_addc_u32 s19, s11, s19
	v_readfirstlane_b32 s35, v1
	s_ashr_i32 s35, s35, 1
	s_waitcnt vmcnt(1)
	v_bfe_u32 v142, v1, 5, 1
	v_mov_b32_e32 v2, s35
	v_bfi_b32 v132, s80, v2, v1
	v_mov_b64_e32 v[2:3], s[36:37]
	v_mad_i64_i32 v[2:3], s[36:37], v132, s86, v[2:3]
	v_lshlrev_b32_e32 v4, 4, v142
	v_mov_b32_e32 v5, v35
	v_lshlrev_b32_e32 v34, 3, v1
	v_lshl_add_u64 v[2:3], v[2:3], 0, v[4:5]
	global_load_dwordx4 v[68:71], v[2:3], off
	global_load_dwordx4 v[72:75], v[2:3], off offset:32
	global_load_dwordx4 v[76:79], v[2:3], off offset:64
	global_load_dwordx4 v[80:83], v[2:3], off offset:96
	global_load_dwordx4 v[84:87], v[2:3], off offset:128
	global_load_dwordx4 v[88:91], v[2:3], off offset:160
	v_lshl_add_u64 v[2:3], v[34:35], 1, s[16:17]
	v_add_co_u32_e32 v6, vcc, s84, v2
	v_ashrrev_i32_e32 v5, 3, v1
	v_and_b32_e32 v12, 56, v34
	v_addc_co_u32_e32 v7, vcc, 0, v3, vcc
	v_lshl_or_b32 v134, v5, 6, v12
	v_mov_b32_e32 v135, v35
	global_load_dwordx4 v[92:95], v[2:3], off
	global_load_dwordx4 v[100:103], v[6:7], off offset:-4096
	global_load_dwordx4 v[96:99], v[6:7], off
	v_lshl_add_u64 v[6:7], v[134:135], 1, s[18:19]
	s_mov_b32 s35, 0x1000
	v_add_co_u32_e32 v8, vcc, s35, v6
	global_load_dwordx4 v[104:107], v[6:7], off
	s_nop 0
	v_addc_co_u32_e32 v9, vcc, 0, v7, vcc
	global_load_dwordx4 v[108:111], v[8:9], off
	v_mul_hi_i32 v10, v1, s87
	v_add_u32_e32 v13, 0x100, v1
	v_lshrrev_b32_e32 v11, 31, v10
	v_ashrrev_i32_e32 v10, 1, v10
	v_mul_hi_i32 v14, v13, s87
	v_add_u32_e32 v10, v10, v11
	v_lshrrev_b32_e32 v11, 31, v14
	v_ashrrev_i32_e32 v14, 1, v14
	v_mul_lo_u32 v15, v10, -12
	v_and_b32_e32 v16, 0xffffff3, v10
	v_lshlrev_b32_e32 v17, 1, v10
	v_lshrrev_b32_e32 v10, 1, v10
	v_add_u32_e32 v14, v14, v11
	v_and_b32_e32 v11, 8, v17
	v_and_b32_e32 v10, 4, v10
	v_or3_b32 v10, v11, v16, v10
	v_add_lshl_u32 v15, v15, v1, 4
	v_mul_lo_u32 v10, v10, s88
	s_movk_i32 s35, 0x4000
	s_waitcnt vmcnt(11)
	v_add3_u32 v144, 0, v10, v15
	v_add_co_u32_e32 v10, vcc, s35, v2
	v_lshlrev_b32_e32 v19, 1, v14
	s_nop 0
	v_addc_co_u32_e32 v11, vcc, 0, v3, vcc
	v_add_co_u32_e32 v2, vcc, s83, v2
	v_and_b32_e32 v18, 0xffffff3, v14
	s_nop 0
	v_addc_co_u32_e32 v3, vcc, 0, v3, vcc
	v_add_co_u32_e32 v6, vcc, 0x2000, v6
	s_nop 1
	v_addc_co_u32_e32 v7, vcc, 0, v7, vcc
	v_add_co_u32_e32 v8, vcc, 0x2000, v8
	s_nop 1
	v_addc_co_u32_e32 v9, vcc, 0, v9, vcc
	global_load_dwordx4 v[112:115], v[10:11], off offset:-4096
	global_load_dwordx4 v[116:119], v[10:11], off
	global_load_dwordx4 v[120:123], v[6:7], off
	global_load_dwordx4 v[124:127], v[2:3], off
	global_load_dwordx4 v[128:131], v[8:9], off
	v_lshrrev_b32_e32 v2, 1, v14
	v_and_b32_e32 v16, 8, v19
	v_and_b32_e32 v2, 4, v2
	v_mul_lo_u32 v17, v14, -12
	v_or3_b32 v2, v16, v18, v2
	v_and_b32_e32 v44, 31, v1
	v_mul_lo_u32 v2, v2, s88
	v_add_lshl_u32 v3, v17, v13, 4
	v_add_u32_e32 v1, 0x200, v1
	v_add3_u32 v145, 0, v2, v3
	v_mul_hi_i32 v2, v1, s87
	v_lshrrev_b32_e32 v3, 31, v2
	v_ashrrev_i32_e32 v2, 1, v2
	v_add_u32_e32 v2, v2, v3
	v_mul_lo_u32 v3, v2, -12
	v_and_b32_e32 v6, 0xffffff3, v2
	v_lshlrev_b32_e32 v7, 1, v2
	v_lshrrev_b32_e32 v2, 1, v2
	v_and_b32_e32 v7, 8, v7
	v_and_b32_e32 v2, 4, v2
	v_or3_b32 v2, v7, v6, v2
	v_mul_lo_u32 v2, v2, s88
	v_add_lshl_u32 v1, v3, v1, 4
	v_add3_u32 v146, 0, v2, v1
	v_mul_lo_u32 v1, v5, s81
	v_lshlrev_b32_e32 v2, 1, v12
	v_add3_u32 v147, 0, v1, v2
	v_lshrrev_b32_e32 v1, 3, v13
	v_mul_lo_u32 v1, v1, s81
	v_add3_u32 v148, 0, v1, v2
	v_mul_u32_u24_e32 v1, 0x68, v44
	v_lshlrev_b32_e32 v1, 1, v1
	v_add3_u32 v149, 0, v1, v4
	v_ashrrev_i32_e32 v133, 31, v132
	v_mov_b32_e32 v138, 1.0
	s_mov_b32 s35, -2
	v_mov_b32_e32 v140, 0
	s_barrier
	s_waitcnt vmcnt(9)
	ds_write_b128 v144, v[92:95]
	s_waitcnt vmcnt(8)
	ds_write_b128 v145, v[100:103]
	s_waitcnt vmcnt(7)
	ds_write_b128 v146, v[96:99]
	s_waitcnt vmcnt(6)
	ds_write_b128 v147, v[104:107] offset:26624
	s_waitcnt vmcnt(5)
	ds_write_b128 v148, v[108:111] offset:26624
	s_add_u32 s36, s16, 0x6000
	s_addc_u32 s37, s17, 0
	s_mov_b32 s41, 2
	v_lshl_add_u64 v[36:37], v[34:35], 1, s[36:37]
	s_lshl_b32 s36, s41, 13
	global_load_dwordx4 v[92:95], v[36:37], off
	v_add_co_u32_e32 v36, vcc, s84, v36
	s_add_u32 s36, s18, s36
	s_nop 0
	v_addc_co_u32_e32 v37, vcc, 0, v37, vcc
	s_addc_u32 s37, s19, 0
	global_load_dwordx4 v[100:103], v[36:37], off offset:-4096
	global_load_dwordx4 v[96:99], v[36:37], off
	v_lshl_add_u64 v[36:37], v[134:135], 1, s[36:37]
	global_load_dwordx4 v[104:107], v[36:37], off
	v_add_co_u32_e32 v36, vcc, 0x1000, v36
	s_nop 1
	v_addc_co_u32_e32 v37, vcc, 0, v37, vcc
	global_load_dwordx4 v[108:111], v[36:37], off
	s_waitcnt lgkmcnt(0)
	s_barrier
; #define MFMA(a, b, c) __builtin_amdgcn_mfma_f32_32x32x16_bf16((a), (b), (c), 0, 0, 0)
; DI void flash_mla2(const bf16_t* __restrict__ Qp, const bf16_t* __restrict__ Kp, const bf16_t* __restrict__ Vtp,
;                    bf16_t* __restrict__ Op, char* smem, float& ssq) {
;     ...
;         const bf16_t* kb = Ks + l32 * KP + 8 * h;
;         f32x16 s0, s1;
; #pragma unroll
;         for (int r = 0; r < 16; ++r) { s0[r] = 0.f; s1[r] = 0.f; }
; #pragma unroll
;         for (int ks = 0; ks < NKS; ++ks) { bf16x8 k0 = *(const bf16x8*)(kb + ks * 16); bf16x8 k1 = *(const bf16x8*)(kb + 32 * KP + ks * 16); s0 = MFMA(k0, qf[ks], s0); s1 = MFMA(k1, qf[ks], s1); }
;         float mx = s0[0];
; #pragma unroll
;         for (int r = 1; r < 16; ++r) mx = fmaxf(mx, s0[r]);
; #pragma unroll
;         for (int r = 0; r < 16; ++r) mx = fmaxf(mx, s1[r]);
;         m = fmaxf(mx, __shfl_xor(mx, 32));
;         __syncthreads();
	ds_read_b128 v[2:5], v149
	ds_read_b128 v[18:21], v149 offset:32
	s_waitcnt lgkmcnt(1)
	v_mfma_f32_32x32x16_bf16 v[2:17], v[2:5], v[68:71], 0
	s_waitcnt lgkmcnt(0)
	v_mfma_f32_32x32x16_bf16 v[2:17], v[18:21], v[72:75], v[2:17]
	ds_read_b128 v[18:21], v149 offset:64
	ds_read_b128 v[22:25], v149 offset:96
	s_waitcnt lgkmcnt(1)
	v_mfma_f32_32x32x16_bf16 v[2:17], v[18:21], v[76:79], v[2:17]
	s_waitcnt lgkmcnt(0)
	v_mfma_f32_32x32x16_bf16 v[2:17], v[22:25], v[80:83], v[2:17]
	ds_read_b128 v[18:21], v149 offset:128
	ds_read_b128 v[22:25], v149 offset:160
	s_waitcnt lgkmcnt(1)
	v_mfma_f32_32x32x16_bf16 v[2:17], v[18:21], v[84:87], v[2:17]
	ds_read_b128 v[18:21], v149 offset:6656
	ds_read_b128 v[36:39], v149 offset:6688
	s_waitcnt lgkmcnt(2)
	v_mfma_f32_32x32x16_bf16 v[2:17], v[22:25], v[88:91], v[2:17]
	s_waitcnt lgkmcnt(1)
	v_mfma_f32_32x32x16_bf16 v[18:33], v[18:21], v[68:71], 0
	s_nop 9
	v_max_f32_e32 v1, v3, v3
	v_max_f32_e32 v2, v2, v2
	v_max_f32_e32 v1, v2, v1
	v_max3_f32 v1, v1, v4, v5
	v_max3_f32 v1, v1, v6, v7
	v_max3_f32 v1, v1, v8, v9
	v_max3_f32 v1, v1, v10, v11
	s_waitcnt lgkmcnt(0)
	v_mfma_f32_32x32x16_bf16 v[18:33], v[36:39], v[72:75], v[18:33]
	ds_read_b128 v[36:39], v149 offset:6720
	ds_read_b128 v[40:43], v149 offset:6752
	v_max3_f32 v1, v1, v12, v13
	v_max3_f32 v1, v1, v14, v15
	v_max3_f32 v1, v1, v16, v17
	v_xor_b32_e32 v2, 32, v184
	v_cmp_lt_i32_e32 vcc, v2, v187
	v_mov_b32_e32 v3, v0
	s_waitcnt lgkmcnt(1)
	v_mfma_f32_32x32x16_bf16 v[18:33], v[36:39], v[76:79], v[18:33]
	v_cndmask_b32_e32 v2, v184, v2, vcc
	v_lshlrev_b32_e32 v143, 2, v2
	v_mov_b32_e32 v4, v0
	v_mov_b32_e32 v5, v0
	v_mov_b32_e32 v6, v0
	v_mov_b32_e32 v7, v0
	v_mov_b32_e32 v8, v0
	s_waitcnt lgkmcnt(0)
	v_mfma_f32_32x32x16_bf16 v[18:33], v[40:43], v[80:83], v[18:33]
	ds_read_b128 v[36:39], v149 offset:6784
	ds_read_b128 v[40:43], v149 offset:6816
	v_mov_b32_e32 v9, v0
	v_mov_b32_e32 v10, v0
	v_mov_b32_e32 v11, v0
	v_mov_b32_e32 v12, v0
	v_mov_b32_e32 v13, v0
	v_mov_b32_e32 v14, v0
	s_waitcnt lgkmcnt(1)
	v_mfma_f32_32x32x16_bf16 v[18:33], v[36:39], v[84:87], v[18:33]
	v_mov_b32_e32 v15, v0
	v_mov_b32_e32 v16, v0
	v_mov_b32_e32 v17, v0
	s_waitcnt lgkmcnt(0)
	s_barrier
	v_mfma_f32_32x32x16_bf16 v[18:33], v[40:43], v[88:91], v[18:33]
	s_nop 11
	v_max3_f32 v1, v1, v18, v19
	v_max3_f32 v1, v1, v20, v21
	v_max3_f32 v1, v1, v22, v23
	v_max3_f32 v1, v1, v24, v25
	v_max3_f32 v1, v1, v26, v27
	v_max3_f32 v1, v1, v28, v29
	v_max3_f32 v1, v1, v30, v31
	v_max3_f32 v1, v1, v32, v33
	ds_bpermute_b32 v2, v143, v1
	v_mov_b32_e32 v18, v0
	v_mov_b32_e32 v19, v0
	v_mov_b32_e32 v20, v0
	v_mov_b32_e32 v21, v0
	s_waitcnt lgkmcnt(0)
	v_max_f32_e32 v2, v2, v2
	v_max_f32_e32 v141, v1, v2
	v_lshlrev_b32_e32 v1, 6, v44
	v_mov_b32_e32 v2, v0
	v_mov_b32_e32 v22, v0
	v_mov_b32_e32 v23, v0
	v_mov_b32_e32 v24, v0
	v_mov_b32_e32 v25, v0
	v_mov_b32_e32 v26, v0
	v_mov_b32_e32 v27, v0
	v_mov_b32_e32 v28, v0
	v_mov_b32_e32 v29, v0
	v_mov_b32_e32 v30, v0
	v_mov_b32_e32 v31, v0
	v_sub_u32_e32 v150, v149, v1
	v_mov_b32_e32 v1, v0
	v_mov_b64_e32 v[32:33], v[30:31]
	v_mov_b64_e32 v[30:31], v[28:29]
	v_mov_b64_e32 v[28:29], v[26:27]
	v_mov_b64_e32 v[26:27], v[24:25]
	v_mov_b64_e32 v[24:25], v[22:23]
	v_mov_b64_e32 v[22:23], v[20:21]
	v_mov_b64_e32 v[20:21], v[18:19]
	v_mov_b64_e32 v[18:19], v[16:17]
	v_mov_b64_e32 v[16:17], v[14:15]
	v_mov_b64_e32 v[14:15], v[12:13]
	v_mov_b64_e32 v[12:13], v[10:11]
	v_mov_b64_e32 v[10:11], v[8:9]
	v_mov_b64_e32 v[8:9], v[6:7]
	v_mov_b64_e32 v[6:7], v[4:5]
	v_mov_b64_e32 v[4:5], v[2:3]
	v_mov_b64_e32 v[2:3], v[0:1]
	v_lshlrev_b32_e32 v136, 1, v34
	v_lshlrev_b32_e32 v151, 1, v134
	v_add_u32_e32 v137, 0x2000, v136
	v_xor_b32_e32 v179, 0x80000000, v141
	v_mov_b32_e32 v232, v179
	v_mov_b32_e32 v233, v179
	v_mov_b32_e32 v234, v179
	v_mov_b32_e32 v235, v179
	v_mov_b32_e32 v236, v179
	v_mov_b32_e32 v237, v179
	v_mov_b32_e32 v238, v179
	v_mov_b32_e32 v239, v179
	v_mov_b32_e32 v240, v179
	v_mov_b32_e32 v241, v179
	v_mov_b32_e32 v242, v179
	v_mov_b32_e32 v243, v179
	v_mov_b32_e32 v244, v179
	v_mov_b32_e32 v245, v179
	v_mov_b32_e32 v246, v179
	v_mov_b32_e32 v247, v179
	s_branch .LBB0_184

; DI unsigned pack2(float a, float b) { f32v2_t v = {a, b}; return __builtin_bit_cast(unsigned, __builtin_convertvector(v, bf16v2_t)); }
; DI float bflo(unsigned u) { return __uint_as_float(u << 16); }
; DI float bfhi(unsigned u) { return __uint_as_float(u & 0xffff0000u); }
; DI int tid() { int t = threadIdx.x; asm volatile("" : "+v"(t)); return t; }
; DI void mla_item(KP p, int item, char* smem) {
;     ...
;     ssq += __shfl_xor(ssq, 32);
;     const float sc = rsqrtf(ssq * (1.f / 512.f) + EPS);
;     const int lane = tid() & 63, w = tid() >> 6, q = w * 32 + (lane & 31), h = lane >> 5;
;     for (int i = 0; i < 64; ++i) {
;         uint2* ptr = (uint2*)(om + (size_t)q * DM + (i >> 3) * 64 + ((i >> 2) & 1) * 32 + (i & 3) * 8 + 4 * h);
;         uint2 v = *ptr;
;         v.x = pack2(bflo(v.x) * sc, bfhi(v.x) * sc);
;         v.y = pack2(bflo(v.y) * sc, bfhi(v.y) * sc);
;         *ptr = v;
;     }
.LBB0_189:
	v_lshl_add_u64 v[4:5], v[2:3], 0, v[34:35]
	s_mov_b32 s6, 0
.Lmla_rms:
	global_load_dwordx2 v[36:37], v[4:5], off offset:0
	global_load_dwordx2 v[38:39], v[4:5], off offset:16
	global_load_dwordx2 v[40:41], v[4:5], off offset:32
	global_load_dwordx2 v[42:43], v[4:5], off offset:48
	global_load_dwordx2 v[44:45], v[4:5], off offset:64
	global_load_dwordx2 v[46:47], v[4:5], off offset:80
	global_load_dwordx2 v[48:49], v[4:5], off offset:96
	global_load_dwordx2 v[50:51], v[4:5], off offset:112
	s_waitcnt vmcnt(0)
	v_lshlrev_b32_e32 v8, 16, v36
	v_and_b32_e32 v9, 0xffff0000, v36
	v_lshlrev_b32_e32 v10, 16, v37
	v_and_b32_e32 v11, 0xffff0000, v37
	v_pk_mul_f32 v[8:9], v[0:1], v[8:9]
	v_pk_mul_f32 v[10:11], v[0:1], v[10:11]
	v_cvt_pk_bf16_f32 v36, v8, v9
	v_cvt_pk_bf16_f32 v37, v10, v11
	global_store_dwordx2 v[4:5], v[36:37], off offset:0
	v_lshlrev_b32_e32 v8, 16, v38
	v_and_b32_e32 v9, 0xffff0000, v38
	v_lshlrev_b32_e32 v10, 16, v39
	v_and_b32_e32 v11, 0xffff0000, v39
	v_pk_mul_f32 v[8:9], v[0:1], v[8:9]
	v_pk_mul_f32 v[10:11], v[0:1], v[10:11]
	v_cvt_pk_bf16_f32 v38, v8, v9
	v_cvt_pk_bf16_f32 v39, v10, v11
	global_store_dwordx2 v[4:5], v[38:39], off offset:16
	v_lshlrev_b32_e32 v8, 16, v40
	v_and_b32_e32 v9, 0xffff0000, v40
	v_lshlrev_b32_e32 v10, 16, v41
	v_and_b32_e32 v11, 0xffff0000, v41
	v_pk_mul_f32 v[8:9], v[0:1], v[8:9]
	v_pk_mul_f32 v[10:11], v[0:1], v[10:11]
	v_cvt_pk_bf16_f32 v40, v8, v9
	v_cvt_pk_bf16_f32 v41, v10, v11
	global_store_dwordx2 v[4:5], v[40:41], off offset:32
	v_lshlrev_b32_e32 v8, 16, v42
	v_and_b32_e32 v9, 0xffff0000, v42
	v_lshlrev_b32_e32 v10, 16, v43
	v_and_b32_e32 v11, 0xffff0000, v43
	v_pk_mul_f32 v[8:9], v[0:1], v[8:9]
	v_pk_mul_f32 v[10:11], v[0:1], v[10:11]
	v_cvt_pk_bf16_f32 v42, v8, v9
	v_cvt_pk_bf16_f32 v43, v10, v11
	global_store_dwordx2 v[4:5], v[42:43], off offset:48
	v_lshlrev_b32_e32 v8, 16, v44
	v_and_b32_e32 v9, 0xffff0000, v44
	v_lshlrev_b32_e32 v10, 16, v45
	v_and_b32_e32 v11, 0xffff0000, v45
	v_pk_mul_f32 v[8:9], v[0:1], v[8:9]
	v_pk_mul_f32 v[10:11], v[0:1], v[10:11]
	v_cvt_pk_bf16_f32 v44, v8, v9
	v_cvt_pk_bf16_f32 v45, v10, v11
	global_store_dwordx2 v[4:5], v[44:45], off offset:64
	v_lshlrev_b32_e32 v8, 16, v46
	v_and_b32_e32 v9, 0xffff0000, v46
	v_lshlrev_b32_e32 v10, 16, v47
	v_and_b32_e32 v11, 0xffff0000, v47
	v_pk_mul_f32 v[8:9], v[0:1], v[8:9]
	v_pk_mul_f32 v[10:11], v[0:1], v[10:11]
	v_cvt_pk_bf16_f32 v46, v8, v9
	v_cvt_pk_bf16_f32 v47, v10, v11
	global_store_dwordx2 v[4:5], v[46:47], off offset:80
	v_lshlrev_b32_e32 v8, 16, v48
	v_and_b32_e32 v9, 0xffff0000, v48
	v_lshlrev_b32_e32 v10, 16, v49
	v_and_b32_e32 v11, 0xffff0000, v49
	v_pk_mul_f32 v[8:9], v[0:1], v[8:9]
	v_pk_mul_f32 v[10:11], v[0:1], v[10:11]
	v_cvt_pk_bf16_f32 v48, v8, v9
	v_cvt_pk_bf16_f32 v49, v10, v11
	global_store_dwordx2 v[4:5], v[48:49], off offset:96
	v_lshlrev_b32_e32 v8, 16, v50
	v_and_b32_e32 v9, 0xffff0000, v50
	v_lshlrev_b32_e32 v10, 16, v51
	v_and_b32_e32 v11, 0xffff0000, v51
	v_pk_mul_f32 v[8:9], v[0:1], v[8:9]
	v_pk_mul_f32 v[10:11], v[0:1], v[10:11]
	v_cvt_pk_bf16_f32 v50, v8, v9
	v_cvt_pk_bf16_f32 v51, v10, v11
	global_store_dwordx2 v[4:5], v[50:51], off offset:112
	v_add_co_u32_e32 v4, vcc, 0x80, v4
	s_add_i32 s6, s6, 1
	s_cmp_lg_u32 s6, 8
	v_addc_co_u32_e32 v5, vcc, 0, v5, vcc
	s_cbranch_scc1 .Lmla_rms
	s_branch .LBB0_178

; #define LOADS(S, k0) { LD1(S, 0, k0) LD1(S, 1, k0) LD1(S, 2, k0) LD1(S, 3, k0) }
; #define STORES(S, buf) { ST1(S, 0, buf) ST1(S, 1, buf) ST1(S, 2, buf) ST1(S, 3, buf) }
; template <int AMODE, bool F16 = false, bool MASK = false>
; DI void gemm_tile(const bf16_t* __restrict__ Ab, int lda, int row0, int rlo, int rhi,
;                   const bf16_t* __restrict__ Bt, int ldb, int K, char* smem, f32x16 (&acc)[2][2]) {
;     ...
;     const int gr0 = row0 + (t >> 3);
;     const bool rv0 = gr0 >= rlo && gr0 < rhi, rv1 = gr0 + 32 >= rlo && gr0 + 32 < rhi, rv2 = gr0 + 64 >= rlo && gr0 + 64 < rhi, rv3 = gr0 + 96 >= rlo && gr0 + 96 < rhi;
;     const int nk = K >> 6;
;     const int rhm = rhi - 1;
;     const unsigned aoff0 = (unsigned)min(max(gr0, rlo), rhm) * (unsigned)lda + 8u * (t & 7);
;     const unsigned aoff1 = (unsigned)min(max(gr0 + 32, rlo), rhm) * (unsigned)lda + 8u * (t & 7);
;     const unsigned aoff2 = (unsigned)min(max(gr0 + 64, rlo), rhm) * (unsigned)lda + 8u * (t & 7);
;     const unsigned aoff3 = (unsigned)min(max(gr0 + 96, rlo), rhm) * (unsigned)lda + 8u * (t & 7);
;     const unsigned btoff = (unsigned)((t >> 3) * ldb + 8 * (t & 7));
;     __syncthreads();
;     ...
;     const int klast = (nk - 1) * 64;
;     LOADS(p0, 0);
;     LOADS(p1, 64);
;     STORES(p0, 0);
;     LOADS(p0, min(128, klast));
;     __syncthreads();
; DI void ph_qkv(KP p, int l, char* smem) {
;     ...
;             gemm_tile<1>((const bf16_t*)(p->ws + OFF_HKV), KVL, rt * 128, 0, TOK, (const bf16_t*)(p->ws + OFF_WUKV) + ((size_t)l * 1024 + c2 * 128) * KVL, KVL, KVL, smem, acc);
.LBB0_192:
	v_readlane_b32 s6, v231, 6
	s_add_i32 s6, s6, s2
	s_cmpk_gt_i32 s6, 0x1bff
	s_cbranch_scc1 .LBB0_191
	s_mul_hi_i32 s7, s6, 0x92492493
	s_add_i32 s7, s7, s6
	s_lshr_b32 s8, s7, 31
	s_ashr_i32 s7, s7, 6
	s_add_i32 s8, s7, s8
	s_mul_i32 s7, s8, 0xffffff90
	s_add_i32 s6, s6, s7
	s_lshl_b32 s9, s8, 3
	s_ashr_i32 s7, s6, 3
	s_and_b32 s6, s2, 7
	s_or_b32 s6, s9, s6
	s_cmp_gt_i32 s7, 5
	s_mov_b64 s[14:15], -1
	s_cbranch_scc0 .LBB0_203
	s_load_dwordx2 s[14:15], s[0:1], 0xe0
	s_add_i32 s9, s7, -6
	v_mov_b32_e32 v24, v182
	s_waitcnt lgkmcnt(0)
	s_add_u32 s18, s14, 0x2c180000
	s_addc_u32 s19, s15, 0
	s_lshl_b32 s10, s6, 7
	s_lshl_b32 s56, s9, 7
	s_add_u32 s11, s14, s48
	s_waitcnt vmcnt(7)
	v_ashrrev_i32_e32 v32, 3, v24
	s_addc_u32 s16, s15, s49
	s_lshl_b64 s[12:13], s[56:57], 8
	v_add_u32_e32 v0, s10, v32
	v_and_b32_e32 v33, 7, v24
	s_add_u32 s12, s11, s12
	v_lshlrev_b32_e32 v2, 3, v33
	v_max_i32_e32 v3, 0xffffffe0, v0
	s_addc_u32 s13, s16, s13
	v_add_u32_e32 v3, 32, v3
	v_lshl_or_b32 v34, v32, 7, v2
	v_med3_i32 v1, v0, 0, v192
	v_min_u32_e32 v4, 0xffff, v3
	v_max_i32_e32 v3, 0xffffffc0, v0
	v_max_i32_e32 v0, 0xffffffa0, v0
	v_lshl_add_u64 v[12:13], v[34:35], 1, s[12:13]
	s_mov_b64 s[12:13], 0xd80000
	v_add_u32_e32 v0, 0x60, v0
	v_lshl_add_u64 v[16:17], v[12:13], 0, s[12:13]
	s_mov_b32 s12, 0xd80000
	v_min_u32_e32 v14, 0xffff, v0
	v_lshlrev_b32_e32 v25, 4, v33
	v_add_co_u32_e32 v0, vcc, s12, v12
	v_lshl_or_b32 v26, v1, 8, v25
	s_nop 0
	v_addc_co_u32_e32 v1, vcc, 0, v13, vcc
	s_mov_b32 s12, 0xd82000
	v_add_co_u32_e32 v18, vcc, s12, v12
	s_mov_b32 s12, 0xd84000
	s_nop 0
	v_addc_co_u32_e32 v19, vcc, 0, v13, vcc
	v_add_co_u32_e32 v20, vcc, s12, v12
	s_mov_b32 s12, 0xd86000
	s_nop 0
	v_addc_co_u32_e32 v21, vcc, 0, v13, vcc
	v_add_u32_e32 v3, 64, v3
	v_add_co_u32_e32 v22, vcc, s12, v12
	v_min_u32_e32 v8, 0xffff, v3
	s_nop 0
	v_addc_co_u32_e32 v23, vcc, 0, v13, vcc
	global_load_dwordx4 v[0:3], v[0:1], off
	v_lshl_or_b32 v27, v4, 8, v25
	global_load_dwordx4 v[4:7], v[18:19], off
	v_lshl_or_b32 v28, v8, 8, v25
	global_load_dwordx4 v[8:11], v[20:21], off
	v_lshl_or_b32 v29, v14, 8, v25
	global_load_dwordx4 v[12:15], v[22:23], off
	global_load_dwordx4 v[92:95], v[16:17], off offset:128
	global_load_dwordx4 v[88:91], v[18:19], off offset:128
	global_load_dwordx4 v[84:87], v[20:21], off offset:128
	global_load_dwordx4 v[80:83], v[22:23], off offset:128
	v_mul_lo_u32 v16, v32, s81
	v_add3_u32 v34, 0, v16, v25
	global_load_dwordx4 v[16:19], v26, s[18:19]
	s_add_u32 s16, s14, 0x2c180080
	s_addc_u32 s17, s15, 0
	v_readfirstlane_b32 s11, v24
	s_lshr_b32 s12, s11, 1
	s_and_b32 s12, s12, 0xfffffc0
	s_waitcnt vmcnt(13)
	v_add_u32_e32 v112, 0x1200, v34
	s_barrier
	s_waitcnt vmcnt(0)
	ds_write_b128 v34, v[16:19]
	ds_write_b128 v34, v[0:3] offset:36864
	global_load_dwordx4 v[76:79], v27, s[18:19]
	v_and_b32_e32 v3, 0xffff0000, v18
	v_lshlrev_b32_e32 v2, 16, v19
	v_and_b32_e32 v0, 31, v24
	v_and_b32_e32 v1, 0xffff0000, v19
	s_waitcnt vmcnt(0)
	ds_write_b128 v34, v[76:79] offset:4608
	ds_write_b128 v34, v[4:7] offset:41472
	global_load_dwordx4 v[72:75], v28, s[18:19]
	v_and_b32_e32 v7, 0xffff0000, v16
	v_lshlrev_b32_e32 v6, 16, v16
	v_mul_f32_e32 v7, v7, v7
	v_fmac_f32_e32 v7, v6, v6
	v_lshlrev_b32_e32 v6, 16, v17
	v_and_b32_e32 v5, 0xffff0000, v17
	v_fmac_f32_e32 v7, v6, v6
	v_lshlrev_b32_e32 v4, 16, v18
	v_fmac_f32_e32 v7, v5, v5
	v_fmac_f32_e32 v7, v4, v4
	v_fmac_f32_e32 v7, v3, v3
	v_fmac_f32_e32 v7, v2, v2
	v_fmac_f32_e32 v7, v1, v1
	v_or_b32_e32 v1, s12, v0
	v_lshrrev_b32_e32 v2, 1, v24
	v_and_or_b32 v0, s11, 64, v0
	v_mul_lo_u32 v1, v1, s81
	v_and_b32_e32 v2, 16, v2
	v_mul_u32_u24_e32 v0, 0x48, v0
	v_add3_u32 v113, 0, v1, v2
	v_lshlrev_b32_e32 v0, 1, v0
	v_add3_u32 v114, 0, v0, v2
	s_waitcnt vmcnt(0)
	ds_write_b128 v34, v[72:75] offset:9216
	ds_write_b128 v34, v[8:11] offset:46080
	global_load_dwordx4 v[68:71], v29, s[18:19]
	s_waitcnt vmcnt(0)
	ds_write_b128 v34, v[68:71] offset:13824
	ds_write_b128 v34, v[12:15] offset:50688
	global_load_dwordx4 v[108:111], v26, s[16:17]
	global_load_dwordx4 v[104:107], v27, s[16:17]
	global_load_dwordx4 v[100:103], v28, s[16:17]
	global_load_dwordx4 v[96:99], v29, s[16:17]
	s_waitcnt lgkmcnt(0)
	s_barrier
; #define LOADS(S, k0) { LD1(S, 0, k0) LD1(S, 1, k0) LD1(S, 2, k0) LD1(S, 3, k0) }
; #define STORES(S, buf) { ST1(S, 0, buf) ST1(S, 1, buf) ST1(S, 2, buf) ST1(S, 3, buf) }
; #define RS1(j) { float s = ss##j; s += __shfl_xor(s, 1); s += __shfl_xor(s, 2); s += __shfl_xor(s, 4); if ((t & 7) == 0) rs[(t >> 3) + 32 * j] = rsqrtf(s / (float)K + EPS); }
; template <int AMODE, bool F16 = false, bool MASK = false>
; DI void gemm_tile(const bf16_t* __restrict__ Ab, int lda, int row0, int rlo, int rhi,
;                   const bf16_t* __restrict__ Bt, int ldb, int K, char* smem, f32x16 (&acc)[2][2]) {
;     ...
;     const int klast = (nk - 1) * 64;
;     LOADS(p0, 0);
;     LOADS(p1, 64);
;     STORES(p0, 0);
;     LOADS(p0, min(128, klast));
;     __syncthreads();
;     for (int kt = 0; kt < nk; kt += 2) {
;         COMPUTE(0);
;         STORES(p1, 1);
;         LOADS(p1, min((kt + 3) * 64, klast));
;         __syncthreads();
;         COMPUTE(1);
;         if (kt + 2 < nk) STORES(p0, 0);
;         LOADS(p0, min((kt + 4) * 64, klast));
;         __syncthreads();
;     }
;     ...
;     if (AMODE == 1) {
;     ...
;         RS1(0) RS1(1) RS1(2) RS1(3)
	s_waitcnt vmcnt(3)
	v_and_b32_e32 v1, 0xffff0000, v108
	v_lshlrev_b32_e32 v0, 16, v108
	v_mul_f32_e32 v1, v1, v1
	v_lshlrev_b32_e32 v2, 16, v109
	v_fmac_f32_e32 v1, v0, v0
	v_and_b32_e32 v3, 0xffff0000, v109
	v_fmac_f32_e32 v1, v2, v2
	v_fmac_f32_e32 v1, v3, v3
	v_lshlrev_b32_e32 v0, 16, v110
	v_and_b32_e32 v2, 0xffff0000, v110
	v_fmac_f32_e32 v1, v0, v0
	v_lshlrev_b32_e32 v3, 16, v111
	v_fmac_f32_e32 v1, v2, v2
	v_and_b32_e32 v4, 0xffff0000, v111
	v_fmac_f32_e32 v1, v3, v3
	v_fmac_f32_e32 v1, v4, v4
	v_add_f32_e32 v148, v7, v1
	ds_read_b128 v[0:3], v113 offset:4608
	ds_read_b128 v[4:7], v114 offset:41472
	ds_read_b128 v[8:11], v113
	ds_read_b128 v[116:119], v113 offset:32
	ds_read_b128 v[120:123], v113 offset:4640
	ds_read_b128 v[12:15], v114 offset:36864
	ds_read_b128 v[124:127], v114 offset:36896
	ds_read_b128 v[128:131], v114 offset:41504
	s_setprio 1
	s_waitcnt lgkmcnt(2)
	v_mfma_f32_32x32x16_bf16 v[52:67], v[8:11], v[12:15], 0
	v_mfma_f32_32x32x16_bf16 v[36:51], v[8:11], v[4:7], 0
	v_mfma_f32_32x32x16_bf16 v[16:31], v[0:3], v[12:15], 0
	v_mfma_f32_32x32x16_bf16 v[0:15], v[0:3], v[4:7], 0
	s_setprio 0
	ds_read_b128 v[132:135], v113 offset:64
	ds_read_b128 v[136:139], v113 offset:4672
	ds_read_b128 v[140:143], v114 offset:36928
	ds_read_b128 v[144:147], v114 offset:41536
	s_setprio 1
	s_waitcnt lgkmcnt(5)
	v_mfma_f32_32x32x16_bf16 v[52:67], v[116:119], v[124:127], v[52:67]
	s_waitcnt lgkmcnt(4)
	v_mfma_f32_32x32x16_bf16 v[36:51], v[116:119], v[128:131], v[36:51]
	v_mfma_f32_32x32x16_bf16 v[16:31], v[120:123], v[124:127], v[16:31]
	v_mfma_f32_32x32x16_bf16 v[0:15], v[120:123], v[128:131], v[0:15]
	s_setprio 0
	ds_read_b128 v[116:119], v113 offset:96
	ds_read_b128 v[120:123], v113 offset:4704
	ds_read_b128 v[124:127], v114 offset:36960
	ds_read_b128 v[128:131], v114 offset:41568
	s_setprio 1
	s_waitcnt lgkmcnt(5)
	v_mfma_f32_32x32x16_bf16 v[52:67], v[132:135], v[140:143], v[52:67]
	s_waitcnt lgkmcnt(4)
	v_mfma_f32_32x32x16_bf16 v[36:51], v[132:135], v[144:147], v[36:51]
	v_mfma_f32_32x32x16_bf16 v[16:31], v[136:139], v[140:143], v[16:31]
	v_mfma_f32_32x32x16_bf16 v[0:15], v[136:139], v[144:147], v[0:15]
	s_setprio 0
	s_setprio 1
	s_waitcnt lgkmcnt(1)
	v_mfma_f32_32x32x16_bf16 v[52:67], v[116:119], v[124:127], v[52:67]
	s_waitcnt lgkmcnt(0)
	v_mfma_f32_32x32x16_bf16 v[36:51], v[116:119], v[128:131], v[36:51]
	v_mfma_f32_32x32x16_bf16 v[16:31], v[120:123], v[124:127], v[16:31]
	v_mfma_f32_32x32x16_bf16 v[0:15], v[120:123], v[128:131], v[0:15]
	s_setprio 0
	ds_write_b128 v34, v[108:111] offset:18432
	ds_write_b128 v34, v[92:95] offset:55296
	s_waitcnt vmcnt(2)
	ds_write_b128 v34, v[104:107] offset:23040
	ds_write_b128 v34, v[88:91] offset:59904
	s_waitcnt vmcnt(1)
	ds_write_b128 v34, v[100:103] offset:27648
	ds_write_b128 v34, v[84:87] offset:64512
	s_waitcnt vmcnt(0)
	ds_write_b128 v34, v[96:99] offset:32256
	ds_write_b128 v112, v[80:83] offset:64512
	s_waitcnt lgkmcnt(0)
	s_barrier
	ds_read_b128 v[80:83], v113 offset:18432
	ds_read_b128 v[84:87], v113 offset:18464
	ds_read_b128 v[88:91], v113 offset:23040
	ds_read_b128 v[92:95], v113 offset:23072
	ds_read_b128 v[108:111], v114 offset:55296
	ds_read_b128 v[116:119], v114 offset:55328
	ds_read_b128 v[120:123], v114 offset:59904
	ds_read_b128 v[124:127], v114 offset:59936
	s_setprio 1
	s_waitcnt lgkmcnt(3)
	v_mfma_f32_32x32x16_bf16 v[52:67], v[80:83], v[108:111], v[52:67]
	s_waitcnt lgkmcnt(1)
	v_mfma_f32_32x32x16_bf16 v[36:51], v[80:83], v[120:123], v[36:51]
	v_mfma_f32_32x32x16_bf16 v[16:31], v[88:91], v[108:111], v[16:31]
	v_mfma_f32_32x32x16_bf16 v[0:15], v[88:91], v[120:123], v[0:15]
	s_setprio 0
	ds_read_b128 v[80:83], v113 offset:18496
	ds_read_b128 v[88:91], v113 offset:23104
	ds_read_b128 v[108:111], v114 offset:55360
	ds_read_b128 v[120:123], v114 offset:59968
	s_setprio 1
	v_mfma_f32_32x32x16_bf16 v[52:67], v[84:87], v[116:119], v[52:67]
	s_waitcnt lgkmcnt(4)
	v_mfma_f32_32x32x16_bf16 v[36:51], v[84:87], v[124:127], v[36:51]
	v_mfma_f32_32x32x16_bf16 v[16:31], v[92:95], v[116:119], v[16:31]
	v_mfma_f32_32x32x16_bf16 v[0:15], v[92:95], v[124:127], v[0:15]
	s_setprio 0
	ds_read_b128 v[84:87], v113 offset:18528
	ds_read_b128 v[92:95], v113 offset:23136
	ds_read_b128 v[116:119], v114 offset:55392
	ds_read_b128 v[112:115], v114 offset:60000
	s_setprio 1
	s_waitcnt lgkmcnt(5)
	v_mfma_f32_32x32x16_bf16 v[52:67], v[80:83], v[108:111], v[52:67]
	s_waitcnt lgkmcnt(4)
	v_mfma_f32_32x32x16_bf16 v[36:51], v[80:83], v[120:123], v[36:51]
	v_mfma_f32_32x32x16_bf16 v[16:31], v[88:91], v[108:111], v[16:31]
	v_mfma_f32_32x32x16_bf16 v[0:15], v[88:91], v[120:123], v[0:15]
	s_setprio 0
	s_setprio 1
	s_waitcnt lgkmcnt(1)
	v_mfma_f32_32x32x16_bf16 v[52:67], v[84:87], v[116:119], v[52:67]
	s_waitcnt lgkmcnt(0)
	v_mfma_f32_32x32x16_bf16 v[36:51], v[84:87], v[112:115], v[36:51]
	v_mfma_f32_32x32x16_bf16 v[16:31], v[92:95], v[116:119], v[16:31]
	v_mfma_f32_32x32x16_bf16 v[0:15], v[92:95], v[112:115], v[0:15]
	s_setprio 0
	v_cmp_lt_i32_e32 vcc, v186, v187
	v_lshl_add_u32 v32, v32, 2, 0
	s_nop 0
	v_cndmask_b32_e32 v34, v184, v186, vcc
	v_lshlrev_b32_e32 v34, 2, v34
	ds_bpermute_b32 v80, v34, v148
	v_cmp_lt_i32_e32 vcc, v188, v187
	s_barrier
	s_waitcnt lgkmcnt(0)
	v_add_f32_e32 v81, v148, v80
	v_cndmask_b32_e32 v80, v184, v188, vcc
	v_lshlrev_b32_e32 v80, 2, v80
	ds_bpermute_b32 v82, v80, v81
	v_cmp_lt_i32_e32 vcc, v189, v187
	s_waitcnt lgkmcnt(0)
	v_add_f32_e32 v82, v81, v82
	v_cndmask_b32_e32 v81, v184, v189, vcc
	v_lshlrev_b32_e32 v81, 2, v81
	ds_bpermute_b32 v83, v81, v82
	v_cmp_eq_u32_e32 vcc, 0, v33
	s_and_saveexec_b64 s[16:17], vcc
	s_cbranch_execz .LBB0_196
	s_waitcnt lgkmcnt(0)
	v_add_f32_e32 v33, v82, v83
	v_fmamk_f32 v33, v33, 0x3c000000, v183
	v_mul_f32_e32 v82, 0x4b800000, v33
	v_cmp_gt_f32_e64 s[42:43], s3, v33
	s_nop 1
	v_cndmask_b32_e64 v33, v33, v82, s[42:43]
	v_rsq_f32_e32 v33, v33
	s_nop 0
	v_mul_f32_e32 v82, 0x45800000, v33
	v_cndmask_b32_e64 v33, v33, v82, s[42:43]
	v_add_u32_e32 v82, 0x12000, v32
	ds_write_b32 v82, v33

; #define LOADS(S, k0) { LD1(S, 0, k0) LD1(S, 1, k0) LD1(S, 2, k0) LD1(S, 3, k0) }
; #define STORES(S, buf) { ST1(S, 0, buf) ST1(S, 1, buf) ST1(S, 2, buf) ST1(S, 3, buf) }
; template <int AMODE, bool F16 = false, bool MASK = false>
; DI void gemm_tile(const bf16_t* __restrict__ Ab, int lda, int row0, int rlo, int rhi,
;                   const bf16_t* __restrict__ Bt, int ldb, int K, char* smem, f32x16 (&acc)[2][2]) {
;     ...
;     const int gr0 = row0 + (t >> 3);
;     const bool rv0 = gr0 >= rlo && gr0 < rhi, rv1 = gr0 + 32 >= rlo && gr0 + 32 < rhi, rv2 = gr0 + 64 >= rlo && gr0 + 64 < rhi, rv3 = gr0 + 96 >= rlo && gr0 + 96 < rhi;
;     const int nk = K >> 6;
;     const int rhm = rhi - 1;
;     const unsigned aoff0 = (unsigned)min(max(gr0, rlo), rhm) * (unsigned)lda + 8u * (t & 7);
;     const unsigned aoff1 = (unsigned)min(max(gr0 + 32, rlo), rhm) * (unsigned)lda + 8u * (t & 7);
;     const unsigned aoff2 = (unsigned)min(max(gr0 + 64, rlo), rhm) * (unsigned)lda + 8u * (t & 7);
;     const unsigned aoff3 = (unsigned)min(max(gr0 + 96, rlo), rhm) * (unsigned)lda + 8u * (t & 7);
;     const unsigned btoff = (unsigned)((t >> 3) * ldb + 8 * (t & 7));
;     __syncthreads();
;     ...
;     const int klast = (nk - 1) * 64;
;     LOADS(p0, 0);
;     LOADS(p1, 64);
;     STORES(p0, 0);
;     LOADS(p0, min(128, klast));
;     __syncthreads();
;     for (int kt = 0; kt < nk; kt += 2) {
;         COMPUTE(0);
;         STORES(p1, 1);
;         LOADS(p1, min((kt + 3) * 64, klast));
;         __syncthreads();
.LBB0_203:
	s_and_b64 vcc, exec, s[14:15]
	s_cbranch_vccz .LBB0_191
	s_load_dwordx2 s[14:15], s[0:1], 0xe0
	v_mov_b32_e32 v24, v182
	s_mul_i32 s10, s40, 0x300
	s_mul_hi_i32 s12, s40, 0x300
	s_waitcnt lgkmcnt(0)
	s_add_u32 s8, s14, 0x2a180000
	s_addc_u32 s9, s15, 0
	s_lshl_b32 s7, s7, 7
	s_lshl_b32 s6, s6, 7
	s_ashr_i32 s11, s7, 31
	s_add_u32 s10, s10, s7
	s_waitcnt vmcnt(7)
	v_ashrrev_i32_e32 v32, 3, v24
	s_addc_u32 s11, s12, s11
	v_add_u32_e32 v0, s6, v32
	s_lshl_b64 s[10:11], s[10:11], 9
	v_and_b32_e32 v33, 7, v24
	v_max_i32_e32 v3, 0xffffffe0, v0
	s_add_u32 s10, s14, s10
	v_lshlrev_b32_e32 v2, 3, v33
	v_add_u32_e32 v3, 32, v3
	s_addc_u32 s11, s15, s11
	v_med3_i32 v1, v0, 0, v192
	v_min_u32_e32 v4, 0xffff, v3
	v_max_i32_e32 v3, 0xffffffc0, v0
	v_max_i32_e32 v0, 0xffffffa0, v0
	v_lshl_or_b32 v34, v32, 8, v2
	v_add_u32_e32 v0, 0x60, v0
	v_lshl_add_u64 v[16:17], v[34:35], 1, s[10:11]
	s_mov_b32 s10, 0xc00000
	v_min_u32_e32 v12, 0xffff, v0
	v_lshlrev_b32_e32 v25, 4, v33
	v_add_co_u32_e32 v0, vcc, s10, v16
	v_lshl_or_b32 v197, v1, 9, v25
	s_nop 0
	v_addc_co_u32_e32 v1, vcc, 0, v17, vcc
	s_mov_b32 s10, 0xc04000
	v_add_co_u32_e32 v18, vcc, s10, v16
	s_mov_b32 s10, 0xc08000
	s_nop 0
	v_addc_co_u32_e32 v19, vcc, 0, v17, vcc
	v_add_u32_e32 v3, 64, v3
	v_add_co_u32_e32 v20, vcc, s10, v16
	v_min_u32_e32 v8, 0xffff, v3
	s_nop 0
	v_addc_co_u32_e32 v21, vcc, 0, v17, vcc
	global_load_dwordx4 v[0:3], v[0:1], off
	v_lshl_or_b32 v34, v4, 9, v25
	global_load_dwordx4 v[4:7], v[18:19], off
	v_lshl_or_b32 v204, v8, 9, v25
	global_load_dwordx4 v[8:11], v[20:21], off
	v_lshl_or_b32 v205, v12, 9, v25
	global_load_dwordx4 v[112:115], v197, s[8:9]
	global_load_dwordx4 v[96:99], v34, s[8:9]
	global_load_dwordx4 v[80:83], v204, s[8:9]
	global_load_dwordx4 v[68:71], v205, s[8:9]
	s_mov_b32 s8, 0xc0c000
	v_add_co_u32_e32 v22, vcc, s8, v16
	s_mov_b64 s[8:9], 0xc00000
	v_lshl_add_u64 v[180:181], v[16:17], 0, s[8:9]
	s_add_u32 s8, s14, 0x2a180080
	s_addc_u32 s9, s15, 0
	v_addc_co_u32_e32 v23, vcc, 0, v17, vcc
	s_add_u32 s10, s14, 0x2a180100
	global_load_dwordx4 v[12:15], v[22:23], off
	s_addc_u32 s11, s15, 0
	global_load_dwordx4 v[128:131], v[180:181], off offset:256
	global_load_dwordx4 v[132:135], v[18:19], off offset:128
	global_load_dwordx4 v[136:139], v[18:19], off offset:256
	global_load_dwordx4 v[140:143], v[20:21], off offset:128
	global_load_dwordx4 v[144:147], v[20:21], off offset:256
	global_load_dwordx4 v[148:151], v[22:23], off offset:128
	global_load_dwordx4 v[152:155], v[22:23], off offset:256
	global_load_dwordx4 v[156:159], v[180:181], off offset:128
	global_load_dwordx4 v[124:127], v197, s[10:11]
	global_load_dwordx4 v[108:111], v34, s[10:11]
	global_load_dwordx4 v[92:95], v204, s[10:11]
	global_load_dwordx4 v[120:123], v197, s[8:9]
	global_load_dwordx4 v[104:107], v34, s[8:9]
	global_load_dwordx4 v[88:91], v204, s[8:9]
	global_load_dwordx4 v[72:75], v205, s[8:9]
	global_load_dwordx4 v[76:79], v205, s[10:11]
	s_mov_b64 s[8:9], 0xc04000
	v_readfirstlane_b32 s10, v24
	v_lshl_add_u64 v[198:199], v[16:17], 0, s[8:9]
	s_mov_b64 s[8:9], 0xc08000
	v_mul_lo_u32 v19, v32, s81
	v_lshl_add_u64 v[200:201], v[16:17], 0, s[8:9]
	s_lshr_b32 s8, s10, 1
	v_and_b32_e32 v18, 31, v24
	v_add3_u32 v214, 0, v19, v25
	s_and_b32 s8, s8, 0xfffffc0
	v_add_u32_e32 v217, 0x1200, v214
	s_barrier
	s_waitcnt vmcnt(20)
	ds_write_b128 v214, v[112:115]
	s_waitcnt vmcnt(19)
	ds_write_b128 v214, v[96:99] offset:4608
	s_waitcnt vmcnt(18)
	ds_write_b128 v214, v[80:83] offset:9216
	s_waitcnt vmcnt(17)
	ds_write_b128 v214, v[68:71] offset:13824
	ds_write_b128 v214, v[0:3] offset:36864
	ds_write_b128 v214, v[4:7] offset:41472
	ds_write_b128 v214, v[8:11] offset:46080
	s_waitcnt vmcnt(16)
	ds_write_b128 v214, v[12:15] offset:50688
	v_or_b32_e32 v0, s8, v18
	v_lshrrev_b32_e32 v1, 1, v24
	v_mul_lo_u32 v0, v0, s81
	v_and_b32_e32 v1, 16, v1
	v_add3_u32 v215, 0, v0, v1
	v_and_or_b32 v0, s10, 64, v18
	v_mul_u32_u24_e32 v0, 0x48, v0
	v_lshlrev_b32_e32 v0, 1, v0
	v_add3_u32 v216, 0, v0, v1
	s_waitcnt lgkmcnt(0)
	s_barrier
	ds_read_b128 v[0:3], v215
	ds_read_b128 v[84:87], v215 offset:32
	ds_read_b128 v[4:7], v215 offset:4608
	ds_read_b128 v[100:103], v215 offset:4640
	ds_read_b128 v[8:11], v216 offset:36864
	ds_read_b128 v[116:119], v216 offset:36896
	ds_read_b128 v[12:15], v216 offset:41472
	ds_read_b128 v[160:163], v216 offset:41504
	s_mov_b64 s[8:9], 0xc0c000
	v_lshl_add_u64 v[202:203], v[16:17], 0, s[8:9]
	s_add_u32 s8, s14, 0x2a180180
	s_addc_u32 s9, s15, 0
	s_setprio 1
	s_waitcnt lgkmcnt(3)
	v_mfma_f32_32x32x16_bf16 v[52:67], v[0:3], v[8:11], 0
	s_waitcnt lgkmcnt(1)
	v_mfma_f32_32x32x16_bf16 v[36:51], v[0:3], v[12:15], 0
	v_mfma_f32_32x32x16_bf16 v[16:31], v[4:7], v[8:11], 0
	v_mfma_f32_32x32x16_bf16 v[0:15], v[4:7], v[12:15], 0
	s_setprio 0
	ds_read_b128 v[164:167], v215 offset:64
	ds_read_b128 v[168:171], v215 offset:4672
	ds_read_b128 v[172:175], v216 offset:36928
	ds_read_b128 v[176:179], v216 offset:41536
	s_setprio 1
	v_mfma_f32_32x32x16_bf16 v[52:67], v[84:87], v[116:119], v[52:67]
	s_waitcnt lgkmcnt(4)
	v_mfma_f32_32x32x16_bf16 v[36:51], v[84:87], v[160:163], v[36:51]
	v_mfma_f32_32x32x16_bf16 v[16:31], v[100:103], v[116:119], v[16:31]
	v_mfma_f32_32x32x16_bf16 v[0:15], v[100:103], v[160:163], v[0:15]
	s_setprio 0
	ds_read_b128 v[84:87], v215 offset:96
	ds_read_b128 v[100:103], v215 offset:4704
	ds_read_b128 v[116:119], v216 offset:36960
	ds_read_b128 v[160:163], v216 offset:41568
	s_setprio 1
	s_waitcnt lgkmcnt(5)
	v_mfma_f32_32x32x16_bf16 v[52:67], v[164:167], v[172:175], v[52:67]
	s_waitcnt lgkmcnt(4)
	v_mfma_f32_32x32x16_bf16 v[36:51], v[164:167], v[176:179], v[36:51]
	v_mfma_f32_32x32x16_bf16 v[16:31], v[168:171], v[172:175], v[16:31]
	v_mfma_f32_32x32x16_bf16 v[0:15], v[168:171], v[176:179], v[0:15]
	s_setprio 0
	s_setprio 1
	s_waitcnt lgkmcnt(1)
	v_mfma_f32_32x32x16_bf16 v[52:67], v[84:87], v[116:119], v[52:67]
	s_waitcnt lgkmcnt(0)
	v_mfma_f32_32x32x16_bf16 v[36:51], v[84:87], v[160:163], v[36:51]
	v_mfma_f32_32x32x16_bf16 v[16:31], v[100:103], v[116:119], v[16:31]
	v_mfma_f32_32x32x16_bf16 v[0:15], v[100:103], v[160:163], v[0:15]
	s_setprio 0
	global_load_dwordx4 v[160:163], v[180:181], off offset:384
	global_load_dwordx4 v[164:167], v197, s[8:9]
	global_load_dwordx4 v[168:171], v[198:199], off offset:384
	global_load_dwordx4 v[116:119], v34, s[8:9]
	global_load_dwordx4 v[172:175], v[200:201], off offset:384
	global_load_dwordx4 v[100:103], v204, s[8:9]
	global_load_dwordx4 v[176:179], v[202:203], off offset:384
	global_load_dwordx4 v[84:87], v205, s[8:9]
	s_waitcnt vmcnt(12)
	ds_write_b128 v214, v[120:123] offset:18432
	ds_write_b128 v214, v[156:159] offset:55296
	s_waitcnt vmcnt(11)
	ds_write_b128 v214, v[104:107] offset:23040
	ds_write_b128 v214, v[132:135] offset:59904
	s_waitcnt vmcnt(10)
	ds_write_b128 v214, v[88:91] offset:27648
	ds_write_b128 v214, v[140:143] offset:64512
	s_waitcnt vmcnt(9)
	ds_write_b128 v214, v[72:75] offset:32256
	ds_write_b128 v217, v[148:151] offset:64512
	s_waitcnt lgkmcnt(0)
	s_barrier
; #define LOADS(S, k0) { LD1(S, 0, k0) LD1(S, 1, k0) LD1(S, 2, k0) LD1(S, 3, k0) }
; #define STORES(S, buf) { ST1(S, 0, buf) ST1(S, 1, buf) ST1(S, 2, buf) ST1(S, 3, buf) }
; template <int AMODE, bool F16 = false, bool MASK = false>
; DI void gemm_tile(const bf16_t* __restrict__ Ab, int lda, int row0, int rlo, int rhi,
;                   const bf16_t* __restrict__ Bt, int ldb, int K, char* smem, f32x16 (&acc)[2][2]) {
;     ...
;     const int klast = (nk - 1) * 64;
;     LOADS(p0, 0);
;     LOADS(p1, 64);
;     STORES(p0, 0);
;     LOADS(p0, min(128, klast));
;     __syncthreads();
;     for (int kt = 0; kt < nk; kt += 2) {
;         COMPUTE(0);
;         STORES(p1, 1);
;         LOADS(p1, min((kt + 3) * 64, klast));
;         __syncthreads();
;         COMPUTE(1);
;         if (kt + 2 < nk) STORES(p0, 0);
;         LOADS(p0, min((kt + 4) * 64, klast));
;         __syncthreads();
	ds_read_b128 v[132:135], v215 offset:18432
	ds_read_b128 v[140:143], v215 offset:18464
	ds_read_b128 v[148:151], v215 offset:23040
	ds_read_b128 v[156:159], v215 offset:23072
	ds_read_b128 v[198:201], v216 offset:55296
	ds_read_b128 v[202:205], v216 offset:55328
	ds_read_b128 v[206:209], v216 offset:59904
	ds_read_b128 v[210:213], v216 offset:59936
	s_setprio 1
	s_waitcnt lgkmcnt(3)
	v_mfma_f32_32x32x16_bf16 v[52:67], v[132:135], v[198:201], v[52:67]
	s_waitcnt lgkmcnt(1)
	v_mfma_f32_32x32x16_bf16 v[36:51], v[132:135], v[206:209], v[36:51]
	v_mfma_f32_32x32x16_bf16 v[16:31], v[148:151], v[198:201], v[16:31]
	v_mfma_f32_32x32x16_bf16 v[0:15], v[148:151], v[206:209], v[0:15]
	s_setprio 0
	ds_read_b128 v[132:135], v215 offset:18496
	ds_read_b128 v[148:151], v215 offset:23104
	ds_read_b128 v[198:201], v216 offset:55360
	ds_read_b128 v[206:209], v216 offset:59968
	s_setprio 1
	v_mfma_f32_32x32x16_bf16 v[52:67], v[140:143], v[202:205], v[52:67]
	s_waitcnt lgkmcnt(4)
	v_mfma_f32_32x32x16_bf16 v[36:51], v[140:143], v[210:213], v[36:51]
	v_mfma_f32_32x32x16_bf16 v[16:31], v[156:159], v[202:205], v[16:31]
	v_mfma_f32_32x32x16_bf16 v[0:15], v[156:159], v[210:213], v[0:15]
	s_setprio 0
	ds_read_b128 v[140:143], v215 offset:18528
	ds_read_b128 v[156:159], v215 offset:23136
	ds_read_b128 v[202:205], v216 offset:55392
	ds_read_b128 v[210:213], v216 offset:60000
	s_setprio 1
	s_waitcnt lgkmcnt(5)
	v_mfma_f32_32x32x16_bf16 v[52:67], v[132:135], v[198:201], v[52:67]
	s_waitcnt lgkmcnt(4)
	v_mfma_f32_32x32x16_bf16 v[36:51], v[132:135], v[206:209], v[36:51]
	v_mfma_f32_32x32x16_bf16 v[16:31], v[148:151], v[198:201], v[16:31]
	v_mfma_f32_32x32x16_bf16 v[0:15], v[148:151], v[206:209], v[0:15]
	s_setprio 0
	s_setprio 1
	s_waitcnt lgkmcnt(1)
	v_mfma_f32_32x32x16_bf16 v[52:67], v[140:143], v[202:205], v[52:67]
	s_waitcnt lgkmcnt(0)
	v_mfma_f32_32x32x16_bf16 v[36:51], v[140:143], v[210:213], v[36:51]
	v_mfma_f32_32x32x16_bf16 v[16:31], v[156:159], v[202:205], v[16:31]
	v_mfma_f32_32x32x16_bf16 v[0:15], v[156:159], v[210:213], v[0:15]
	s_setprio 0
	ds_write_b128 v214, v[124:127]
	ds_write_b128 v214, v[128:131] offset:36864
	ds_write_b128 v214, v[108:111] offset:4608
	ds_write_b128 v214, v[136:139] offset:41472
	ds_write_b128 v214, v[92:95] offset:9216
	ds_write_b128 v214, v[144:147] offset:46080
	s_waitcnt vmcnt(8)
	ds_write_b128 v214, v[76:79] offset:13824
	ds_write_b128 v214, v[152:155] offset:50688
	s_waitcnt lgkmcnt(0)
	s_barrier
	ds_read_b128 v[128:131], v215
	ds_read_b128 v[132:135], v215 offset:32
	ds_read_b128 v[136:139], v215 offset:4608
	ds_read_b128 v[140:143], v215 offset:4640
	ds_read_b128 v[144:147], v216 offset:36864
	ds_read_b128 v[148:151], v216 offset:36896
	ds_read_b128 v[152:155], v216 offset:41472
	ds_read_b128 v[156:159], v216 offset:41504
	s_setprio 1
	s_waitcnt lgkmcnt(3)
	v_mfma_f32_32x32x16_bf16 v[52:67], v[128:131], v[144:147], v[52:67]
	s_waitcnt lgkmcnt(1)
	v_mfma_f32_32x32x16_bf16 v[36:51], v[128:131], v[152:155], v[36:51]
	v_mfma_f32_32x32x16_bf16 v[16:31], v[136:139], v[144:147], v[16:31]
	v_mfma_f32_32x32x16_bf16 v[0:15], v[136:139], v[152:155], v[0:15]
	s_setprio 0
	ds_read_b128 v[128:131], v215 offset:64
	ds_read_b128 v[136:139], v215 offset:4672
	ds_read_b128 v[144:147], v216 offset:36928
	ds_read_b128 v[152:155], v216 offset:41536
	s_setprio 1
	v_mfma_f32_32x32x16_bf16 v[52:67], v[132:135], v[148:151], v[52:67]
	s_waitcnt lgkmcnt(4)
	v_mfma_f32_32x32x16_bf16 v[36:51], v[132:135], v[156:159], v[36:51]
	v_mfma_f32_32x32x16_bf16 v[16:31], v[140:143], v[148:151], v[16:31]
	v_mfma_f32_32x32x16_bf16 v[0:15], v[140:143], v[156:159], v[0:15]
	s_setprio 0
	ds_read_b128 v[132:135], v215 offset:96
	ds_read_b128 v[140:143], v215 offset:4704
	ds_read_b128 v[148:151], v216 offset:36960
	ds_read_b128 v[156:159], v216 offset:41568
	s_setprio 1
	s_waitcnt lgkmcnt(5)
	v_mfma_f32_32x32x16_bf16 v[52:67], v[128:131], v[144:147], v[52:67]
	s_waitcnt lgkmcnt(4)
	v_mfma_f32_32x32x16_bf16 v[36:51], v[128:131], v[152:155], v[36:51]
	v_mfma_f32_32x32x16_bf16 v[16:31], v[136:139], v[144:147], v[16:31]
	v_mfma_f32_32x32x16_bf16 v[0:15], v[136:139], v[152:155], v[0:15]
	s_setprio 0
	s_setprio 1
	s_waitcnt lgkmcnt(1)
	v_mfma_f32_32x32x16_bf16 v[52:67], v[132:135], v[148:151], v[52:67]
	s_waitcnt lgkmcnt(0)
	v_mfma_f32_32x32x16_bf16 v[36:51], v[132:135], v[156:159], v[36:51]
	v_mfma_f32_32x32x16_bf16 v[16:31], v[140:143], v[148:151], v[16:31]
	v_mfma_f32_32x32x16_bf16 v[0:15], v[140:143], v[156:159], v[0:15]
	s_setprio 0
	s_waitcnt vmcnt(6)
	ds_write_b128 v214, v[164:167] offset:18432
	ds_write_b128 v214, v[160:163] offset:55296
	s_waitcnt vmcnt(4)
	ds_write_b128 v214, v[116:119] offset:23040
	ds_write_b128 v214, v[168:171] offset:59904
	s_waitcnt vmcnt(2)
	ds_write_b128 v214, v[100:103] offset:27648
	ds_write_b128 v214, v[172:175] offset:64512
	s_waitcnt vmcnt(0)
	ds_write_b128 v214, v[84:87] offset:32256
	ds_write_b128 v217, v[176:179] offset:64512
	s_waitcnt lgkmcnt(0)
	s_barrier
; #define LOADS(S, k0) { LD1(S, 0, k0) LD1(S, 1, k0) LD1(S, 2, k0) LD1(S, 3, k0) }
; #define STORES(S, buf) { ST1(S, 0, buf) ST1(S, 1, buf) ST1(S, 2, buf) ST1(S, 3, buf) }
; #define RS1(j) { float s = ss##j; s += __shfl_xor(s, 1); s += __shfl_xor(s, 2); s += __shfl_xor(s, 4); if ((t & 7) == 0) rs[(t >> 3) + 32 * j] = rsqrtf(s / (float)K + EPS); }
; template <int AMODE, bool F16 = false, bool MASK = false>
; DI void gemm_tile(const bf16_t* __restrict__ Ab, int lda, int row0, int rlo, int rhi,
;                   const bf16_t* __restrict__ Bt, int ldb, int K, char* smem, f32x16 (&acc)[2][2]) {
;     ...
;     const int klast = (nk - 1) * 64;
;     LOADS(p0, 0);
;     LOADS(p1, 64);
;     STORES(p0, 0);
;     LOADS(p0, min(128, klast));
;     __syncthreads();
;     for (int kt = 0; kt < nk; kt += 2) {
;         COMPUTE(0);
;         STORES(p1, 1);
;         LOADS(p1, min((kt + 3) * 64, klast));
;         __syncthreads();
;         COMPUTE(1);
;         if (kt + 2 < nk) STORES(p0, 0);
;         LOADS(p0, min((kt + 4) * 64, klast));
;         __syncthreads();
;     }
;     ...
;     if (AMODE == 1) {
;     ...
;         RS1(0) RS1(1) RS1(2) RS1(3)
	ds_read_b128 v[128:131], v215 offset:18432
	ds_read_b128 v[132:135], v215 offset:18464
	ds_read_b128 v[136:139], v215 offset:23040
	ds_read_b128 v[140:143], v215 offset:23072
	ds_read_b128 v[144:147], v216 offset:55296
	ds_read_b128 v[148:151], v216 offset:55328
	ds_read_b128 v[152:155], v216 offset:59904
	ds_read_b128 v[156:159], v216 offset:59936
	s_setprio 1
	s_waitcnt lgkmcnt(3)
	v_mfma_f32_32x32x16_bf16 v[52:67], v[128:131], v[144:147], v[52:67]
	s_waitcnt lgkmcnt(1)
	v_mfma_f32_32x32x16_bf16 v[36:51], v[128:131], v[152:155], v[36:51]
	v_mfma_f32_32x32x16_bf16 v[16:31], v[136:139], v[144:147], v[16:31]
	v_mfma_f32_32x32x16_bf16 v[0:15], v[136:139], v[152:155], v[0:15]
	s_setprio 0
	ds_read_b128 v[128:131], v215 offset:18496
	ds_read_b128 v[136:139], v215 offset:23104
	ds_read_b128 v[144:147], v216 offset:55360
	ds_read_b128 v[152:155], v216 offset:59968
	s_setprio 1
	v_mfma_f32_32x32x16_bf16 v[52:67], v[132:135], v[148:151], v[52:67]
	s_waitcnt lgkmcnt(4)
	v_mfma_f32_32x32x16_bf16 v[36:51], v[132:135], v[156:159], v[36:51]
	v_mfma_f32_32x32x16_bf16 v[16:31], v[140:143], v[148:151], v[16:31]
	v_mfma_f32_32x32x16_bf16 v[0:15], v[140:143], v[156:159], v[0:15]
	s_setprio 0
	ds_read_b128 v[132:135], v215 offset:18528
	ds_read_b128 v[140:143], v215 offset:23136
	ds_read_b128 v[148:151], v216 offset:55392
	ds_read_b128 v[156:159], v216 offset:60000
	s_setprio 1
	s_waitcnt lgkmcnt(5)
	v_mfma_f32_32x32x16_bf16 v[52:67], v[128:131], v[144:147], v[52:67]
	s_waitcnt lgkmcnt(4)
	v_mfma_f32_32x32x16_bf16 v[36:51], v[128:131], v[152:155], v[36:51]
	v_mfma_f32_32x32x16_bf16 v[16:31], v[136:139], v[144:147], v[16:31]
	v_mfma_f32_32x32x16_bf16 v[0:15], v[136:139], v[152:155], v[0:15]
	s_setprio 0
	s_setprio 1
	s_waitcnt lgkmcnt(1)
	v_mfma_f32_32x32x16_bf16 v[52:67], v[132:135], v[148:151], v[52:67]
	s_waitcnt lgkmcnt(0)
	v_mfma_f32_32x32x16_bf16 v[36:51], v[132:135], v[156:159], v[36:51]
	v_mfma_f32_32x32x16_bf16 v[16:31], v[140:143], v[148:151], v[16:31]
	v_mfma_f32_32x32x16_bf16 v[0:15], v[140:143], v[156:159], v[0:15]
	s_setprio 0
	v_and_b32_e32 v134, 0xffff0000, v164
	v_lshlrev_b32_e32 v133, 16, v164
	v_mul_f32_e32 v134, v134, v134
	v_lshlrev_b32_e32 v132, 16, v165
	v_fmac_f32_e32 v134, v133, v133
	v_and_b32_e32 v131, 0xffff0000, v165
	v_fmac_f32_e32 v134, v132, v132
	v_lshlrev_b32_e32 v130, 16, v166
	v_fmac_f32_e32 v134, v131, v131
	v_fmac_f32_e32 v134, v130, v130
	v_lshlrev_b32_e32 v130, 16, v124
	v_and_b32_e32 v124, 0xffff0000, v124
	v_and_b32_e32 v129, 0xffff0000, v166
	v_mul_f32_e32 v124, v124, v124
	v_fmac_f32_e32 v134, v129, v129
	v_and_b32_e32 v129, 0xffff0000, v125
	v_lshlrev_b32_e32 v125, 16, v125
	v_fmac_f32_e32 v124, v130, v130
	v_lshlrev_b32_e32 v128, 16, v167
	v_fmac_f32_e32 v124, v125, v125
	v_fmac_f32_e32 v134, v128, v128
	v_and_b32_e32 v128, 0xffff0000, v126
	v_lshlrev_b32_e32 v126, 16, v126
	v_fmac_f32_e32 v124, v129, v129
	v_and_b32_e32 v34, 0xffff0000, v167
	v_fmac_f32_e32 v124, v126, v126
	v_fmac_f32_e32 v134, v34, v34
	v_and_b32_e32 v34, 0xffff0000, v127
	v_lshlrev_b32_e32 v127, 16, v127
	v_fmac_f32_e32 v124, v128, v128
	v_fmac_f32_e32 v124, v127, v127
	v_lshlrev_b32_e32 v127, 16, v120
	v_and_b32_e32 v120, 0xffff0000, v120
	v_mul_f32_e32 v120, v120, v120
	v_and_b32_e32 v126, 0xffff0000, v121
	v_lshlrev_b32_e32 v121, 16, v121
	v_fmac_f32_e32 v120, v127, v127
	v_fmac_f32_e32 v120, v121, v121
	v_and_b32_e32 v125, 0xffff0000, v122
	v_lshlrev_b32_e32 v122, 16, v122
	v_fmac_f32_e32 v120, v126, v126
	v_fmac_f32_e32 v120, v122, v122
	v_fmac_f32_e32 v124, v34, v34
	v_and_b32_e32 v34, 0xffff0000, v123
	v_lshlrev_b32_e32 v123, 16, v123
	v_fmac_f32_e32 v120, v125, v125
	v_fmac_f32_e32 v120, v123, v123
	v_lshlrev_b32_e32 v123, 16, v112
	v_and_b32_e32 v112, 0xffff0000, v112
	v_mul_f32_e32 v112, v112, v112
	v_and_b32_e32 v122, 0xffff0000, v113
	v_fmac_f32_e32 v112, v123, v123
	v_lshlrev_b32_e32 v113, 16, v113
	v_fmac_f32_e32 v112, v113, v113
	v_and_b32_e32 v121, 0xffff0000, v114
	v_lshlrev_b32_e32 v114, 16, v114
	v_fmac_f32_e32 v112, v122, v122
	v_fmac_f32_e32 v112, v114, v114
	v_fmac_f32_e32 v120, v34, v34
	v_and_b32_e32 v34, 0xffff0000, v115
	v_lshlrev_b32_e32 v115, 16, v115
	v_fmac_f32_e32 v112, v121, v121
	v_fmac_f32_e32 v112, v115, v115
	v_fmac_f32_e32 v112, v34, v34
	v_add_f32_e32 v34, v112, v120
	v_add_f32_e32 v34, v34, v124
	v_cmp_lt_i32_e32 vcc, v186, v187
	v_add_f32_e32 v112, v34, v134
	v_lshl_add_u32 v32, v32, 2, 0
	v_cndmask_b32_e32 v34, v184, v186, vcc
	v_lshlrev_b32_e32 v34, 2, v34
	ds_bpermute_b32 v113, v34, v112
	v_cmp_lt_i32_e32 vcc, v188, v187
	s_waitcnt lgkmcnt(0)
	s_barrier
	v_add_f32_e32 v113, v112, v113
	v_cndmask_b32_e32 v112, v184, v188, vcc
	v_lshlrev_b32_e32 v112, 2, v112
	ds_bpermute_b32 v114, v112, v113
	v_cmp_lt_i32_e32 vcc, v189, v187
	s_waitcnt lgkmcnt(0)
	v_add_f32_e32 v114, v113, v114
	v_cndmask_b32_e32 v113, v184, v189, vcc
	v_lshlrev_b32_e32 v113, 2, v113
	ds_bpermute_b32 v115, v113, v114
	v_cmp_eq_u32_e32 vcc, 0, v33
	s_and_saveexec_b64 s[16:17], vcc
	s_cbranch_execz .LBB0_206
	s_waitcnt lgkmcnt(0)
	v_add_f32_e32 v33, v114, v115
	v_fmamk_f32 v33, v33, 0x3b800000, v183
	v_mul_f32_e32 v114, 0x4b800000, v33
	v_cmp_gt_f32_e64 s[42:43], s3, v33
	s_nop 1
	v_cndmask_b32_e64 v33, v33, v114, s[42:43]
	v_rsq_f32_e32 v33, v33
	s_nop 0
	v_mul_f32_e32 v114, 0x45800000, v33
	v_cndmask_b32_e64 v33, v33, v114, s[42:43]
	v_add_u32_e32 v114, 0x12000, v32
	ds_write_b32 v114, v33

; #define LOADS(S, k0) { LD1(S, 0, k0) LD1(S, 1, k0) LD1(S, 2, k0) LD1(S, 3, k0) }
; #define STORES(S, buf) { ST1(S, 0, buf) ST1(S, 1, buf) ST1(S, 2, buf) ST1(S, 3, buf) }
; template <int AMODE, bool F16 = false, bool MASK = false>
; DI void gemm_tile(const bf16_t* __restrict__ Ab, int lda, int row0, int rlo, int rhi,
;                   const bf16_t* __restrict__ Bt, int ldb, int K, char* smem, f32x16 (&acc)[2][2]) {
;     ...
;     const int gr0 = row0 + (t >> 3);
;     const bool rv0 = gr0 >= rlo && gr0 < rhi, rv1 = gr0 + 32 >= rlo && gr0 + 32 < rhi, rv2 = gr0 + 64 >= rlo && gr0 + 64 < rhi, rv3 = gr0 + 96 >= rlo && gr0 + 96 < rhi;
;     const int nk = K >> 6;
;     const int rhm = rhi - 1;
;     const unsigned aoff0 = (unsigned)min(max(gr0, rlo), rhm) * (unsigned)lda + 8u * (t & 7);
;     const unsigned aoff1 = (unsigned)min(max(gr0 + 32, rlo), rhm) * (unsigned)lda + 8u * (t & 7);
;     const unsigned aoff2 = (unsigned)min(max(gr0 + 64, rlo), rhm) * (unsigned)lda + 8u * (t & 7);
;     const unsigned aoff3 = (unsigned)min(max(gr0 + 96, rlo), rhm) * (unsigned)lda + 8u * (t & 7);
;     const unsigned btoff = (unsigned)((t >> 3) * ldb + 8 * (t & 7));
;     __syncthreads();
;     ...
;     const int klast = (nk - 1) * 64;
;     LOADS(p0, 0);
;     LOADS(p1, 64);
;     STORES(p0, 0);
;     LOADS(p0, min(128, klast));
;     __syncthreads();
.LBB0_238:
	s_or_b64 exec, exec, s[14:15]
	s_mulk_i32 s10, 0xffa0
	s_add_i32 s10, s10, s9
	s_waitcnt lgkmcnt(0)
	s_add_u32 s14, s18, 0x2d180000
	s_addc_u32 s15, s19, 0
	s_lshl_b32 s9, s10, 4
	s_and_b32 s10, s9, 0xffffff80
	v_mov_b32_e32 v1, v182
	s_ashr_i32 s11, s10, 31
	s_add_u32 s12, s6, s10
	v_ashrrev_i32_e32 v50, 3, v1
	v_add_u32_e32 v2, s8, v50
	s_addc_u32 s13, s2, s11
	v_lshlrev_b32_e32 v4, 3, v1
	v_max_i32_e32 v5, 0xffffffe0, v2
	s_lshl_b64 s[12:13], s[12:13], 11
	v_and_b32_e32 v4, 56, v4
	v_add_u32_e32 v5, 32, v5
	s_add_u32 s12, s18, s12
	v_med3_i32 v3, v2, 0, v192
	v_min_u32_e32 v10, 0xffff, v5
	v_max_i32_e32 v5, 0xffffffc0, v2
	v_max_i32_e32 v2, 0xffffffa0, v2
	v_lshlrev_b32_e32 v51, 1, v4
	s_addc_u32 s13, s19, s13
	v_add_u32_e32 v5, 64, v5
	v_add_u32_e32 v2, 0x60, v2
	v_lshl_or_b32 v6, v50, 10, v4
	v_lshl_or_b32 v34, v3, 11, v51
	v_mov_b32_e32 v7, v35
	v_min_u32_e32 v18, 0xffff, v5
	v_min_u32_e32 v26, 0xffff, v2
	global_load_dwordx4 v[2:5], v34, s[14:15]
	s_waitcnt vmcnt(8)
	v_lshl_add_u64 v[32:33], v[6:7], 1, s[12:13]
	v_lshl_or_b32 v30, v10, 11, v51
	s_mov_b32 s11, 0x10000
	global_load_dwordx4 v[10:13], v30, s[14:15]
	v_add_co_u32_e32 v40, vcc, s11, v32
	v_lshl_or_b32 v42, v18, 11, v51
	s_nop 0
	v_addc_co_u32_e32 v41, vcc, 0, v33, vcc
	global_load_dwordx4 v[18:21], v42, s[14:15]
	s_mov_b32 s11, 0x20000
	v_lshl_or_b32 v46, v26, 11, v51
	v_add_co_u32_e32 v44, vcc, s11, v32
	global_load_dwordx4 v[26:29], v46, s[14:15]
	global_load_dwordx4 v[6:9], v[32:33], off
	global_load_dwordx4 v[14:17], v[40:41], off
	v_addc_co_u32_e32 v45, vcc, 0, v33, vcc
	s_mov_b32 s11, 0x30000
	v_add_co_u32_e32 v48, vcc, s11, v32
	global_load_dwordx4 v[22:25], v[44:45], off
	s_nop 0
	v_addc_co_u32_e32 v49, vcc, 0, v33, vcc
	global_load_dwordx4 v[36:39], v[48:49], off
	v_mov_b32_e32 v31, v35
	v_mov_b32_e32 v43, v35
	v_mov_b32_e32 v47, v35
	s_waitcnt vmcnt(14)
	v_lshl_add_u64 v[132:133], s[14:15], 0, v[34:35]
	s_waitcnt vmcnt(13)
	v_lshl_add_u64 v[134:135], s[14:15], 0, v[30:31]
	s_waitcnt vmcnt(12)
	v_lshl_add_u64 v[136:137], s[14:15], 0, v[42:43]
	s_waitcnt vmcnt(11)
	v_lshl_add_u64 v[138:139], s[14:15], 0, v[46:47]
	s_mov_b64 s[14:15], 0x10000
	s_add_u32 s12, s18, 0x2d180080
	s_waitcnt vmcnt(10)
	v_lshl_add_u64 v[140:141], v[32:33], 0, s[14:15]
	s_mov_b64 s[14:15], 0x20000
	s_waitcnt vmcnt(9)
	v_lshl_add_u64 v[142:143], v[32:33], 0, s[14:15]
	s_mov_b64 s[14:15], 0x30000
	s_addc_u32 s13, s19, 0
	v_mul_lo_u32 v50, v50, s81
	s_waitcnt vmcnt(8)
	v_lshl_add_u64 v[144:145], v[32:33], 0, s[14:15]
	s_add_u32 s14, s18, 0x2d180100
	v_add3_u32 v147, 0, v50, v51
	s_addc_u32 s15, s19, 0
	global_load_dwordx4 v[68:71], v[32:33], off offset:128
	global_load_dwordx4 v[72:75], v[32:33], off offset:256
	global_load_dwordx4 v[76:79], v[40:41], off offset:128
	global_load_dwordx4 v[80:83], v42, s[12:13]
	global_load_dwordx4 v[88:91], v[48:49], off offset:128
	global_load_dwordx4 v[84:87], v[40:41], off offset:256
	global_load_dwordx4 v[96:99], v[48:49], off offset:256
	global_load_dwordx4 v[92:95], v42, s[14:15]
	v_readfirstlane_b32 s16, v1
	v_and_b32_e32 v52, 31, v1
	v_lshrrev_b32_e32 v1, 1, v1
	v_and_b32_e32 v1, 16, v1
	s_mov_b32 s11, 0
	v_add_u32_e32 v149, 0xd800, v147
	v_mov_b32_e32 v53, v0
	s_barrier
	s_waitcnt vmcnt(15)
	ds_write_b128 v147, v[2:5]
	s_waitcnt vmcnt(14)
	ds_write_b128 v147, v[10:13] offset:4608
	s_waitcnt vmcnt(13)
	ds_write_b128 v147, v[18:21] offset:9216
	s_waitcnt vmcnt(12)
	ds_write_b128 v147, v[26:29] offset:13824
	s_waitcnt vmcnt(11)
	ds_write_b128 v147, v[6:9] offset:36864
	s_waitcnt vmcnt(10)
	ds_write_b128 v147, v[14:17] offset:41472
	s_waitcnt vmcnt(9)
	ds_write_b128 v147, v[22:25] offset:46080
	s_waitcnt vmcnt(8)
	ds_write_b128 v147, v[36:39] offset:50688
	global_load_dwordx4 v[100:103], v34, s[12:13]
	global_load_dwordx4 v[104:107], v34, s[14:15]
	global_load_dwordx4 v[108:111], v30, s[12:13]
	global_load_dwordx4 v[112:115], v30, s[14:15]
	global_load_dwordx4 v[116:119], v[44:45], off offset:128
	global_load_dwordx4 v[120:123], v[44:45], off offset:256
	global_load_dwordx4 v[124:127], v46, s[12:13]
	global_load_dwordx4 v[128:131], v46, s[14:15]
	s_lshr_b32 s12, s16, 1
	s_and_b32 s12, s12, 0xfffffc0
	v_or_b32_e32 v2, s12, v52
	v_mul_lo_u32 v2, v2, s81
	v_add3_u32 v34, 0, v2, v1
	v_and_or_b32 v2, s16, 64, v52
	v_mul_u32_u24_e32 v2, 0x48, v2
	v_lshlrev_b32_e32 v2, 1, v2
	v_add3_u32 v148, 0, v2, v1
	s_mov_b32 s12, 0
	v_mov_b32_e32 v1, v0
	v_mov_b32_e32 v2, v0
	v_mov_b32_e32 v3, v0
	v_mov_b32_e32 v4, v0
	v_mov_b32_e32 v5, v0
	v_mov_b32_e32 v6, v0
	v_mov_b32_e32 v7, v0
	v_mov_b32_e32 v8, v0
	v_mov_b32_e32 v9, v0
	v_mov_b32_e32 v10, v0
	v_mov_b32_e32 v11, v0
	v_mov_b32_e32 v12, v0
	v_mov_b32_e32 v13, v0
	v_mov_b32_e32 v14, v0
	v_mov_b32_e32 v15, v0
	v_mov_b32_e32 v52, v0
	v_mov_b32_e32 v54, v0
	v_mov_b32_e32 v55, v0
	v_mov_b32_e32 v56, v0
	v_mov_b32_e32 v57, v0
	v_mov_b32_e32 v58, v0
	v_mov_b32_e32 v59, v0
	v_mov_b32_e32 v60, v0
	v_mov_b32_e32 v61, v0
	v_mov_b32_e32 v62, v0
	v_mov_b32_e32 v63, v0
	v_mov_b32_e32 v64, v0
	v_mov_b32_e32 v65, v0
	v_mov_b32_e32 v66, v0
	v_mov_b32_e32 v67, v0
	v_mov_b32_e32 v36, v0
	v_mov_b32_e32 v37, v0
	v_mov_b32_e32 v38, v0
	v_mov_b32_e32 v39, v0
	v_mov_b32_e32 v40, v0
	v_mov_b32_e32 v41, v0
	v_mov_b32_e32 v42, v0
	v_mov_b32_e32 v43, v0
	v_mov_b32_e32 v44, v0
	v_mov_b32_e32 v45, v0
	v_mov_b32_e32 v46, v0
	v_mov_b32_e32 v47, v0
	v_mov_b32_e32 v48, v0
	v_mov_b32_e32 v49, v0
	v_mov_b32_e32 v50, v0
	v_mov_b32_e32 v51, v0
	v_mov_b32_e32 v16, v0
	v_mov_b32_e32 v17, v0
	v_mov_b32_e32 v18, v0
	v_mov_b32_e32 v19, v0
	v_mov_b32_e32 v20, v0
	v_mov_b32_e32 v21, v0
	v_mov_b32_e32 v22, v0
	v_mov_b32_e32 v23, v0
	v_mov_b32_e32 v24, v0
	v_mov_b32_e32 v25, v0
	v_mov_b32_e32 v26, v0
	v_mov_b32_e32 v27, v0
	v_mov_b32_e32 v28, v0
	v_mov_b32_e32 v29, v0
	v_mov_b32_e32 v30, v0
	v_mov_b32_e32 v31, v0
	s_waitcnt lgkmcnt(0)
	s_barrier
	s_branch .LBB0_240

; #define LOADS(S, k0) { LD1(S, 0, k0) LD1(S, 1, k0) LD1(S, 2, k0) LD1(S, 3, k0) }
; #define STORES(S, buf) { ST1(S, 0, buf) ST1(S, 1, buf) ST1(S, 2, buf) ST1(S, 3, buf) }
; template <int AMODE, bool F16 = false, bool MASK = false>
; DI void gemm_tile(const bf16_t* __restrict__ Ab, int lda, int row0, int rlo, int rhi,
;                   const bf16_t* __restrict__ Bt, int ldb, int K, char* smem, f32x16 (&acc)[2][2]) {
;     ...
;     const int gr0 = row0 + (t >> 3);
;     const bool rv0 = gr0 >= rlo && gr0 < rhi, rv1 = gr0 + 32 >= rlo && gr0 + 32 < rhi, rv2 = gr0 + 64 >= rlo && gr0 + 64 < rhi, rv3 = gr0 + 96 >= rlo && gr0 + 96 < rhi;
;     const int nk = K >> 6;
;     const int rhm = rhi - 1;
;     const unsigned aoff0 = (unsigned)min(max(gr0, rlo), rhm) * (unsigned)lda + 8u * (t & 7);
;     const unsigned aoff1 = (unsigned)min(max(gr0 + 32, rlo), rhm) * (unsigned)lda + 8u * (t & 7);
;     const unsigned aoff2 = (unsigned)min(max(gr0 + 64, rlo), rhm) * (unsigned)lda + 8u * (t & 7);
;     const unsigned aoff3 = (unsigned)min(max(gr0 + 96, rlo), rhm) * (unsigned)lda + 8u * (t & 7);
;     const unsigned btoff = (unsigned)((t >> 3) * ldb + 8 * (t & 7));
;     __syncthreads();
;     ...
;     const int klast = (nk - 1) * 64;
;     LOADS(p0, 0);
;     LOADS(p1, 64);
;     STORES(p0, 0);
;     LOADS(p0, min(128, klast));
;     __syncthreads();
; DI void ph_memkv(KP p, char* smem) {
;     for_tiles(DEPTH * 16 * 16, [&](int t) __attribute__((always_inline)) {
;         const int l = t >> 8, rt = (t >> 4) & 15, ct = t & 15;
;         f32x16 acc[2][2];
;         gemm_tile<1>((const bf16_t*)(p->ws + OFF_MEMB), DM, rt * 128, 0, NBATCH * NMEM, (const bf16_t*)(p->ws + OFF_WMKV) + ((size_t)l * 2048 + ct * 128) * DM, DM, DM, smem, acc);
.LBB0_1374:
	s_add_i32 s6, s2, s77
	s_cmpk_gt_i32 s6, 0x3ff
	s_cbranch_scc1 .LBB0_1373
	s_load_dwordx2 s[14:15], s[0:1], 0xe0
	s_ashr_i32 s8, s6, 8
	v_mov_b32_e32 v50, v182
	s_waitcnt lgkmcnt(0)
	v_mov_b32_e32 v1, v35
	s_add_u32 s18, s14, 0x35180000
	s_addc_u32 s19, s15, 0
	s_lshl_b32 s6, s6, 3
	s_ashr_i32 s9, s8, 31
	s_lshl_b32 s7, s2, 7
	s_and_b32 s6, s6, 0x780
	s_and_b32 s7, s7, 0x780
	s_lshl_b64 s[16:17], s[8:9], 22
	s_add_u32 s8, s14, s16
	s_addc_u32 s9, s15, s17
	s_lshl_b32 s10, s7, 11
	v_and_b32_e32 v151, 7, v50
	s_add_u32 s8, s8, s10
	v_ashrrev_i32_e32 v150, 3, v50
	v_lshlrev_b32_e32 v0, 3, v151
	s_addc_u32 s9, s9, 0
	v_lshl_or_b32 v0, v150, 10, v0
	v_lshl_add_u64 v[36:37], v[0:1], 1, s[8:9]
	s_mov_b32 s8, 0x1f80000
	v_add_co_u32_e32 v0, vcc, s8, v36
	s_mov_b32 s8, 0x1f90000
	s_nop 0
	v_addc_co_u32_e32 v1, vcc, 0, v37, vcc
	v_add_co_u32_e32 v38, vcc, s8, v36
	s_mov_b32 s8, 0x1fa0000
	s_nop 0
	v_addc_co_u32_e32 v39, vcc, 0, v37, vcc
	v_add_co_u32_e32 v40, vcc, s8, v36
	global_load_dwordx4 v[12:15], v[0:1], off
	global_load_dwordx4 v[16:19], v[38:39], off
	v_addc_co_u32_e32 v41, vcc, 0, v37, vcc
	s_mov_b32 s8, 0x1fb0000
	v_add_co_u32_e32 v42, vcc, s8, v36
	global_load_dwordx4 v[20:23], v[40:41], off
	s_nop 0
	v_addc_co_u32_e32 v43, vcc, 0, v37, vcc
	global_load_dwordx4 v[24:27], v[42:43], off
	v_add_u32_e32 v0, s6, v150
	v_max_i32_e32 v2, 0xffffffe0, v0
	v_add_u32_e32 v2, 32, v2
	v_med3_i32 v1, v0, 0, v194
	v_min_u32_e32 v2, 0x7ff, v2
	s_waitcnt vmcnt(11)
	v_lshlrev_b32_e32 v32, 4, v151
	v_lshl_or_b32 v34, v1, 11, v32
	v_lshl_or_b32 v44, v2, 11, v32
	global_load_dwordx4 v[28:31], v34, s[18:19]
	global_load_dwordx4 v[8:11], v44, s[18:19]
	v_max_i32_e32 v1, 0xffffffc0, v0
	v_max_i32_e32 v0, 0xffffffa0, v0
	v_add_u32_e32 v0, 0x60, v0
	v_add_u32_e32 v1, 64, v1
	v_min_u32_e32 v0, 0x7ff, v0
	v_min_u32_e32 v1, 0x7ff, v1
	v_lshl_or_b32 v48, v0, 11, v32
	v_lshl_or_b32 v46, v1, 11, v32
	global_load_dwordx4 v[0:3], v48, s[18:19]
	global_load_dwordx4 v[4:7], v46, s[18:19]
	s_add_u32 s10, s14, 0x35180080
	v_mul_lo_u32 v33, v150, s81
	s_mov_b64 s[12:13], 0x1f80000
	s_addc_u32 s11, s15, 0
	v_add3_u32 v152, 0, v33, v32
	v_lshl_add_u64 v[32:33], v[36:37], 0, s[12:13]
	global_load_dwordx4 v[68:71], v34, s[10:11]
	global_load_dwordx4 v[76:79], v[32:33], off offset:128
	global_load_dwordx4 v[72:75], v44, s[10:11]
	global_load_dwordx4 v[80:83], v46, s[10:11]
	global_load_dwordx4 v[84:87], v48, s[10:11]
	s_add_u32 s10, s14, 0x35180100
	global_load_dwordx4 v[92:95], v[38:39], off offset:128
	global_load_dwordx4 v[88:91], v[40:41], off offset:128
	global_load_dwordx4 v[128:131], v[42:43], off offset:128
	s_addc_u32 s11, s15, 0
	v_readfirstlane_b32 s9, v50
	s_mov_b64 s[12:13], 0x1f90000
	s_waitcnt vmcnt(21)
	v_lshl_add_u64 v[134:135], v[36:37], 0, s[12:13]
	s_mov_b64 s[12:13], 0x1fa0000
	v_mov_b32_e32 v45, v35
	v_mov_b32_e32 v47, v35
	v_mov_b32_e32 v49, v35
	s_waitcnt vmcnt(19)
	v_lshl_add_u64 v[138:139], v[36:37], 0, s[12:13]
	s_mov_b64 s[12:13], 0x1fb0000
	v_mov_b32_e32 v52, 0
	s_mov_b32 s8, 0
	v_lshl_add_u64 v[132:133], s[18:19], 0, v[44:45]
	v_lshl_add_u64 v[136:137], s[18:19], 0, v[46:47]
	s_waitcnt vmcnt(18)
	v_lshl_add_u64 v[140:141], s[18:19], 0, v[48:49]
	s_waitcnt vmcnt(17)
	v_lshl_add_u64 v[142:143], v[36:37], 0, s[12:13]
	v_mov_b32_e32 v53, v52
	v_mov_b32_e32 v54, v52
	v_mov_b32_e32 v55, v52
	v_mov_b32_e32 v56, v52
	s_barrier
; #define LOADS(S, k0) { LD1(S, 0, k0) LD1(S, 1, k0) LD1(S, 2, k0) LD1(S, 3, k0) }
; #define STORES(S, buf) { ST1(S, 0, buf) ST1(S, 1, buf) ST1(S, 2, buf) ST1(S, 3, buf) }
; template <int AMODE, bool F16 = false, bool MASK = false>
; DI void gemm_tile(const bf16_t* __restrict__ Ab, int lda, int row0, int rlo, int rhi,
;                   const bf16_t* __restrict__ Bt, int ldb, int K, char* smem, f32x16 (&acc)[2][2]) {
;     ...
;     const int klast = (nk - 1) * 64;
;     LOADS(p0, 0);
;     LOADS(p1, 64);
;     STORES(p0, 0);
;     LOADS(p0, min(128, klast));
;     __syncthreads();
	s_waitcnt vmcnt(15)
	ds_write_b128 v152, v[12:15] offset:36864
	s_waitcnt vmcnt(14)
	ds_write_b128 v152, v[16:19] offset:41472
	s_waitcnt vmcnt(13)
	ds_write_b128 v152, v[20:23] offset:46080
	s_waitcnt vmcnt(12)
	ds_write_b128 v152, v[24:27] offset:50688
	global_load_dwordx4 v[112:115], v34, s[10:11]
	global_load_dwordx4 v[120:123], v[32:33], off offset:256
	global_load_dwordx4 v[96:99], v44, s[10:11]
	global_load_dwordx4 v[124:127], v[38:39], off offset:256
	global_load_dwordx4 v[108:111], v46, s[10:11]
	global_load_dwordx4 v[116:119], v[40:41], off offset:256
	global_load_dwordx4 v[100:103], v48, s[10:11]
	global_load_dwordx4 v[104:107], v[42:43], off offset:256
	s_waitcnt vmcnt(19)
	ds_write_b128 v152, v[28:31]
	s_waitcnt vmcnt(18)
	ds_write_b128 v152, v[8:11] offset:4608
	v_and_b32_e32 v15, 0xffff0000, v8
	v_and_b32_e32 v14, 0xffff0000, v28
	v_lshlrev_b32_e32 v12, 16, v28
	v_lshlrev_b32_e32 v13, 16, v8
	v_pk_mul_f32 v[14:15], v[14:15], v[14:15]
	v_lshlrev_b32_e32 v8, 16, v29
	v_and_b32_e32 v17, 0xffff0000, v11
	v_lshlrev_b32_e32 v19, 16, v11
	v_and_b32_e32 v11, 0xffff0000, v9
	v_pk_fma_f32 v[12:13], v[12:13], v[12:13], v[14:15]
	v_lshlrev_b32_e32 v9, 16, v9
	v_and_b32_e32 v21, 0xffff0000, v10
	v_lshlrev_b32_e32 v23, 16, v10
	v_and_b32_e32 v10, 0xffff0000, v29
	v_pk_fma_f32 v[8:9], v[8:9], v[8:9], v[12:13]
	v_lshlrev_b32_e32 v22, 16, v30
	v_pk_fma_f32 v[8:9], v[10:11], v[10:11], v[8:9]
	v_and_b32_e32 v20, 0xffff0000, v30
	v_pk_fma_f32 v[8:9], v[22:23], v[22:23], v[8:9]
	v_lshlrev_b32_e32 v18, 16, v31
	v_pk_fma_f32 v[8:9], v[20:21], v[20:21], v[8:9]
	v_and_b32_e32 v16, 0xffff0000, v31
	v_pk_fma_f32 v[8:9], v[18:19], v[18:19], v[8:9]
	s_waitcnt vmcnt(17)
	v_and_b32_e32 v11, 0xffff0000, v0
	s_waitcnt vmcnt(16)
	v_and_b32_e32 v10, 0xffff0000, v4
	v_pk_fma_f32 v[144:145], v[16:17], v[16:17], v[8:9]
	v_lshlrev_b32_e32 v9, 16, v0
	v_lshlrev_b32_e32 v8, 16, v4
	ds_write_b128 v152, v[4:7] offset:9216
	ds_write_b128 v152, v[0:3] offset:13824
	v_lshlrev_b32_e32 v0, 16, v5
	v_and_b32_e32 v12, 0xffff0000, v7
	v_lshlrev_b32_e32 v14, 16, v7
	v_and_b32_e32 v17, 0xffff0000, v2
	v_lshlrev_b32_e32 v7, 16, v2
	v_and_b32_e32 v2, 0xffff0000, v5
	v_pk_mul_f32 v[4:5], v[10:11], v[10:11]
	v_and_b32_e32 v13, 0xffff0000, v3
	v_lshlrev_b32_e32 v15, 16, v3
	v_and_b32_e32 v3, 0xffff0000, v1
	v_pk_fma_f32 v[4:5], v[8:9], v[8:9], v[4:5]
	v_lshlrev_b32_e32 v1, 16, v1
	v_pk_fma_f32 v[0:1], v[0:1], v[0:1], v[4:5]
	v_and_b32_e32 v16, 0xffff0000, v6
	v_lshlrev_b32_e32 v6, 16, v6
	v_pk_fma_f32 v[0:1], v[2:3], v[2:3], v[0:1]
	s_lshr_b32 s10, s9, 1
	v_pk_fma_f32 v[0:1], v[6:7], v[6:7], v[0:1]
	v_and_b32_e32 v24, 31, v50
	v_pk_fma_f32 v[0:1], v[16:17], v[16:17], v[0:1]
	s_and_b32 s10, s10, 0xfffffc0
	v_pk_fma_f32 v[0:1], v[14:15], v[14:15], v[0:1]
	v_mov_b32_e32 v57, v52
	v_pk_fma_f32 v[146:147], v[12:13], v[12:13], v[0:1]
	v_or_b32_e32 v0, s10, v24
	v_lshrrev_b32_e32 v1, 1, v50
	v_mul_lo_u32 v0, v0, s81
	v_and_b32_e32 v1, 16, v1
	v_add3_u32 v153, 0, v0, v1
	v_and_or_b32 v0, s9, 64, v24
	v_mul_u32_u24_e32 v0, 0x48, v0
	v_lshlrev_b32_e32 v0, 1, v0
	v_add3_u32 v154, 0, v0, v1
	s_mov_b32 s9, 0
	v_mov_b32_e32 v58, v52
	v_mov_b32_e32 v59, v52
	v_mov_b32_e32 v60, v52
	v_mov_b32_e32 v61, v52
	v_mov_b32_e32 v62, v52
	v_mov_b32_e32 v63, v52
	v_mov_b32_e32 v64, v52
	v_mov_b32_e32 v65, v52
	v_mov_b32_e32 v66, v52
	v_mov_b32_e32 v67, v52
	v_mov_b32_e32 v36, v52
	v_mov_b32_e32 v37, v52
	v_mov_b32_e32 v38, v52
	v_mov_b32_e32 v39, v52
	v_mov_b32_e32 v40, v52
	v_mov_b32_e32 v41, v52
	v_mov_b32_e32 v42, v52
	v_mov_b32_e32 v43, v52
	v_mov_b32_e32 v44, v52
	v_mov_b32_e32 v45, v52
	v_mov_b32_e32 v46, v52
	v_mov_b32_e32 v47, v52
	v_mov_b32_e32 v48, v52
	v_mov_b32_e32 v49, v52
	v_mov_b32_e32 v50, v52
	v_mov_b32_e32 v51, v52
	v_mov_b32_e32 v16, v52
	v_mov_b32_e32 v17, v52
	v_mov_b32_e32 v18, v52
	v_mov_b32_e32 v19, v52
	v_mov_b32_e32 v20, v52
	v_mov_b32_e32 v21, v52
	v_mov_b32_e32 v22, v52
	v_mov_b32_e32 v23, v52
	v_mov_b32_e32 v24, v52
	v_mov_b32_e32 v25, v52
	v_mov_b32_e32 v26, v52
	v_mov_b32_e32 v27, v52
	v_mov_b32_e32 v28, v52
	v_mov_b32_e32 v29, v52
	v_mov_b32_e32 v30, v52
	v_mov_b32_e32 v31, v52
	v_mov_b32_e32 v0, v52
	v_mov_b32_e32 v1, v52
	v_mov_b32_e32 v2, v52
	v_mov_b32_e32 v3, v52
	v_mov_b32_e32 v4, v52
	v_mov_b32_e32 v5, v52
	v_mov_b32_e32 v6, v52
	v_mov_b32_e32 v7, v52
	v_mov_b32_e32 v8, v52
	v_mov_b32_e32 v9, v52
	v_mov_b32_e32 v10, v52
	v_mov_b32_e32 v11, v52
	v_mov_b32_e32 v12, v52
	v_mov_b32_e32 v13, v52
	v_mov_b32_e32 v14, v52
	v_mov_b32_e32 v15, v52
	v_add_u32_e32 v155, 0x1200, v152
	v_add_u32_e32 v156, 0x2400, v152
	v_add_u32_e32 v157, 0x3600, v152
	v_lshl_add_u64 v[148:149], s[18:19], 0, v[34:35]
	s_waitcnt lgkmcnt(0)
	s_barrier
	s_branch .LBB0_1377
